# GEMM phases 2,3,6,7: LDS-read wait moved ahead of the barrier that opens the compute segment
# speedup vs baseline: 1.0001x; 1.0001x over previous
; #define PG8_STAGE(bufoff, gbase, voff) do { _Pragma("unroll") for (int _i = 0; _i < 2; ++_i) \
;     __builtin_amdgcn_global_load_lds((const unsigned*)((const char*)(gbase) + (voff)[_i]), (PG8_LAS unsigned*)(lds + (bufoff) + ldsw + _i * 8192), 16, 0, 0); } while (0)
; #define PG8_LDA(dst, b, h) do { _Pragma("unroll") for (int m = 0; m < 4; ++m) _Pragma("unroll") for (int k = 0; k < 2; ++k) dst[m][k] = *(const PG8_LAS bf16x8*)(lds + PG8_SA(b, h) + aoff + m * 2048 + k * 1024); } while (0)
; #define PG8_LDB(dst, b, h) do { _Pragma("unroll") for (int n = 0; n < 2; ++n) _Pragma("unroll") for (int k = 0; k < 2; ++k) dst[n][k] = *(const PG8_LAS bf16x8*)(lds + PG8_SB(b, h) + boff + n * 2048 + k * 1024); } while (0)
; #define PG8_MMA(ai, bj, At, Bt) do { __builtin_amdgcn_s_setprio(1); _Pragma("unroll") for (int m = 0; m < 4; ++m) _Pragma("unroll") for (int n = 0; n < 2; ++n) _Pragma("unroll") for (int k = 0; k < 2; ++k) \
;     acc[ai][bj][m][n] = __builtin_amdgcn_mfma_f32_16x16x32_bf16(Bt[n][k], At[m][k], acc[ai][bj][m][n], 0, 0, 0); __builtin_amdgcn_s_setprio(0); } while (0)
; #define PG8_WAIT_L(n) asm volatile("s_waitcnt lgkmcnt(" #n ")" ::: "memory")
; #define PG8_BAR __builtin_amdgcn_s_barrier()
; #define PG8_SCHED __builtin_amdgcn_sched_barrier(0)
; template <class Epi, class Sched>
; __device__ __forceinline__ void gemm_phase(PG8_LAS unsigned char* lds, const int lda, const int ldb, const Sched& S, const Epi& E) {
;     ...
;     for (int t = 0; t < nt; t += 2) {
;       const bool last = (t == nt - 2);
;       const char* a1 = cA + (size_t)(t + 1) * kstep;
;       const char* a2 = last ? nA : cA + (size_t)(t + 2) * kstep; const char* b2 = last ? nB : cB + (size_t)(t + 2) * kstep;
;       const char* a3 = a2 + kstep; const char* b3 = b2 + kstep;
;       PG8_LDB(B0, 0, 0); PG8_SCHED; PG8_LDA(At, 0, 0); PG8_STAGE(PG8_SA(1, 1), a1 + hstepA, voffA);
;       PG8_WAIT_L(8); PG8_BAR; PG8_WAIT_L(0); PG8_MMA(0, 0, At, B0); PG8_BAR; PG8_SCHED;
;       PG8_LDB(B1, 0, 1); PG8_STAGE(PG8_SB(0, 0), b2, voffB);
;       PG8_BAR; PG8_WAIT_L(0); PG8_MMA(0, 1, At, B1); PG8_BAR;
;       PG8_LDA(At, 0, 1); PG8_STAGE(PG8_SA(0, 0), a2, voffA);
;       PG8_BAR; PG8_WAIT_L(0); PG8_MMA(1, 0, At, B0); PG8_BAR; PG8_SCHED;
.LBB0_335:
	s_add_u32 s10, s8, 0xfffc0080
	s_addc_u32 s11, s9, -1
	s_add_i32 s31, 0, 0x10000
	v_add_u32_e32 v156, s31, v131
	ds_read_b128 v[144:147], v156
	ds_read_b128 v[148:151], v156 offset:1024
	ds_read_b128 v[152:155], v156 offset:2048
	ds_read_b128 v[200:203], v156 offset:3072
	s_cmp_eq_u32 s30, 12
	s_cselect_b32 s25, s17, s11
	s_cselect_b32 s24, s26, s10
	s_cselect_b32 s11, s15, s29
	s_cselect_b32 s10, s27, s28
	v_lshl_add_u64 v[156:157], s[8:9], 0, v[140:141]
	s_add_i32 m0, s40, 0xc000
	ds_read_b128 v[204:207], v172
	ds_read_b128 v[208:211], v172 offset:1024
	ds_read_b128 v[212:215], v172 offset:2048
	ds_read_b128 v[216:219], v172 offset:3072
	ds_read_b128 v[220:223], v172 offset:4096
	ds_read_b128 v[224:227], v172 offset:5120
	ds_read_b128 v[228:231], v172 offset:6144
	ds_read_b128 v[232:235], v172 offset:7168
	global_load_lds_dwordx4 v[156:157], off
	v_lshl_add_u64 v[156:157], s[8:9], 0, v[142:143]
	s_add_i32 m0, s40, 0xe000
	s_nop 0
	global_load_lds_dwordx4 v[156:157], off
	s_waitcnt lgkmcnt(8)
	s_barrier
	s_waitcnt lgkmcnt(0)
	s_setprio 1
	v_mfma_f32_16x16x32_bf16 v[126:129], v[144:147], v[204:207], v[126:129]
	v_mfma_f32_16x16x32_bf16 v[122:125], v[152:155], v[204:207], v[122:125]
	v_mfma_f32_16x16x32_bf16 v[110:113], v[144:147], v[212:215], v[110:113]
	v_mfma_f32_16x16x32_bf16 v[106:109], v[152:155], v[212:215], v[106:109]
	v_mfma_f32_16x16x32_bf16 v[94:97], v[144:147], v[220:223], v[94:97]
	v_mfma_f32_16x16x32_bf16 v[90:93], v[152:155], v[220:223], v[90:93]
	v_mfma_f32_16x16x32_bf16 v[78:81], v[144:147], v[228:231], v[78:81]
	v_mfma_f32_16x16x32_bf16 v[74:77], v[152:155], v[228:231], v[74:77]
	v_mfma_f32_16x16x32_bf16 v[126:129], v[148:151], v[208:211], v[126:129]
	v_mfma_f32_16x16x32_bf16 v[122:125], v[200:203], v[208:211], v[122:125]
	v_mfma_f32_16x16x32_bf16 v[110:113], v[148:151], v[216:219], v[110:113]
	v_mfma_f32_16x16x32_bf16 v[106:109], v[200:203], v[216:219], v[106:109]
	v_mfma_f32_16x16x32_bf16 v[94:97], v[148:151], v[224:227], v[94:97]
	v_mfma_f32_16x16x32_bf16 v[90:93], v[200:203], v[224:227], v[90:93]
	v_mfma_f32_16x16x32_bf16 v[78:81], v[148:151], v[232:235], v[78:81]
	v_mfma_f32_16x16x32_bf16 v[74:77], v[200:203], v[232:235], v[74:77]
	s_setprio 0
	s_barrier
	s_add_i32 s33, 0, 0x14000
	v_add_u32_e32 v156, s33, v131
	s_add_i32 s31, s31, s39
	ds_read_b128 v[236:239], v156
	ds_read_b128 v[240:243], v156 offset:1024
	ds_read_b128 v[244:247], v156 offset:2048
	ds_read_b128 v[248:251], v156 offset:3072
	v_lshl_add_u64 v[156:157], s[10:11], 0, v[134:135]
	s_mov_b32 m0, s31
	v_lshl_add_u64 v[174:175], s[10:11], 0, v[132:133]
	global_load_lds_dwordx4 v[156:157], off
	s_add_i32 m0, s31, 0x2000
	s_nop 0
	global_load_lds_dwordx4 v[174:175], off
	s_waitcnt lgkmcnt(0)
	s_barrier
	s_setprio 1
	v_mfma_f32_16x16x32_bf16 v[118:121], v[236:239], v[204:207], v[118:121]
	v_mfma_f32_16x16x32_bf16 v[114:117], v[244:247], v[204:207], v[114:117]
	v_mfma_f32_16x16x32_bf16 v[102:105], v[236:239], v[212:215], v[102:105]
	v_mfma_f32_16x16x32_bf16 v[98:101], v[244:247], v[212:215], v[98:101]
	v_mfma_f32_16x16x32_bf16 v[86:89], v[236:239], v[220:223], v[86:89]
	v_mfma_f32_16x16x32_bf16 v[82:85], v[244:247], v[220:223], v[82:85]
	v_mfma_f32_16x16x32_bf16 v[70:73], v[236:239], v[228:231], v[70:73]
	v_mfma_f32_16x16x32_bf16 v[66:69], v[244:247], v[228:231], v[66:69]
	v_mfma_f32_16x16x32_bf16 v[118:121], v[240:243], v[208:211], v[118:121]
	v_mfma_f32_16x16x32_bf16 v[114:117], v[248:251], v[208:211], v[114:117]
	v_mfma_f32_16x16x32_bf16 v[102:105], v[240:243], v[216:219], v[102:105]
	v_mfma_f32_16x16x32_bf16 v[98:101], v[248:251], v[216:219], v[98:101]
	v_mfma_f32_16x16x32_bf16 v[86:89], v[240:243], v[224:227], v[86:89]
	v_mfma_f32_16x16x32_bf16 v[82:85], v[248:251], v[224:227], v[82:85]
	v_mfma_f32_16x16x32_bf16 v[70:73], v[240:243], v[232:235], v[70:73]
	v_mfma_f32_16x16x32_bf16 v[66:69], v[248:251], v[232:235], v[66:69]
	s_setprio 0
	s_mov_b32 m0, s40
	v_lshl_add_u64 v[182:183], s[24:25], 0, v[134:135]
	s_barrier
	ds_read_b128 v[204:207], v172 offset:16384
	ds_read_b128 v[208:211], v172 offset:17408
	ds_read_b128 v[212:215], v172 offset:18432
	ds_read_b128 v[216:219], v172 offset:19456
	ds_read_b128 v[220:223], v172 offset:20480
	ds_read_b128 v[224:227], v172 offset:21504
	ds_read_b128 v[228:231], v172 offset:22528
	ds_read_b128 v[232:235], v172 offset:23552
	global_load_lds_dwordx4 v[182:183], off
	v_lshl_add_u64 v[184:185], s[24:25], 0, v[132:133]
	s_mov_b32 m0, s41
	s_nop 0
	global_load_lds_dwordx4 v[184:185], off
	s_waitcnt lgkmcnt(0)
	s_barrier
	s_setprio 1
	v_mfma_f32_16x16x32_bf16 v[62:65], v[144:147], v[204:207], v[62:65]
	v_mfma_f32_16x16x32_bf16 v[58:61], v[152:155], v[204:207], v[58:61]
	v_mfma_f32_16x16x32_bf16 v[46:49], v[144:147], v[212:215], v[46:49]
	v_mfma_f32_16x16x32_bf16 v[42:45], v[152:155], v[212:215], v[42:45]
	v_mfma_f32_16x16x32_bf16 v[30:33], v[144:147], v[220:223], v[30:33]
	v_mfma_f32_16x16x32_bf16 v[26:29], v[152:155], v[220:223], v[26:29]
	v_mfma_f32_16x16x32_bf16 v[14:17], v[144:147], v[228:231], v[14:17]
	v_mfma_f32_16x16x32_bf16 v[10:13], v[152:155], v[228:231], v[10:13]
	v_mfma_f32_16x16x32_bf16 v[62:65], v[148:151], v[208:211], v[62:65]
	v_mfma_f32_16x16x32_bf16 v[58:61], v[200:203], v[208:211], v[58:61]
	v_mfma_f32_16x16x32_bf16 v[46:49], v[148:151], v[216:219], v[46:49]
	v_mfma_f32_16x16x32_bf16 v[42:45], v[200:203], v[216:219], v[42:45]
	v_mfma_f32_16x16x32_bf16 v[30:33], v[148:151], v[224:227], v[30:33]
	v_mfma_f32_16x16x32_bf16 v[26:29], v[200:203], v[224:227], v[26:29]
	v_mfma_f32_16x16x32_bf16 v[14:17], v[148:151], v[232:235], v[14:17]
	v_mfma_f32_16x16x32_bf16 v[10:13], v[200:203], v[232:235], v[10:13]
	s_setprio 0
	s_barrier
; #define PG8_STAGE(bufoff, gbase, voff) do { _Pragma("unroll") for (int _i = 0; _i < 2; ++_i) \
;     __builtin_amdgcn_global_load_lds((const unsigned*)((const char*)(gbase) + (voff)[_i]), (PG8_LAS unsigned*)(lds + (bufoff) + ldsw + _i * 8192), 16, 0, 0); } while (0)
; #define PG8_LDA(dst, b, h) do { _Pragma("unroll") for (int m = 0; m < 4; ++m) _Pragma("unroll") for (int k = 0; k < 2; ++k) dst[m][k] = *(const PG8_LAS bf16x8*)(lds + PG8_SA(b, h) + aoff + m * 2048 + k * 1024); } while (0)
; #define PG8_LDB(dst, b, h) do { _Pragma("unroll") for (int n = 0; n < 2; ++n) _Pragma("unroll") for (int k = 0; k < 2; ++k) dst[n][k] = *(const PG8_LAS bf16x8*)(lds + PG8_SB(b, h) + boff + n * 2048 + k * 1024); } while (0)
; #define PG8_MMA(ai, bj, At, Bt) do { __builtin_amdgcn_s_setprio(1); _Pragma("unroll") for (int m = 0; m < 4; ++m) _Pragma("unroll") for (int n = 0; n < 2; ++n) _Pragma("unroll") for (int k = 0; k < 2; ++k) \
;     acc[ai][bj][m][n] = __builtin_amdgcn_mfma_f32_16x16x32_bf16(Bt[n][k], At[m][k], acc[ai][bj][m][n], 0, 0, 0); __builtin_amdgcn_s_setprio(0); } while (0)
; #define PG8_WAIT_V(n) asm volatile("s_waitcnt vmcnt(" #n ")" ::: "memory")
; #define PG8_WAIT_L(n) asm volatile("s_waitcnt lgkmcnt(" #n ")" ::: "memory")
; #define PG8_BAR __builtin_amdgcn_s_barrier()
; #define PG8_SCHED __builtin_amdgcn_sched_barrier(0)
; template <class Epi, class Sched>
; __device__ __forceinline__ void gemm_phase(PG8_LAS unsigned char* lds, const int lda, const int ldb, const Sched& S, const Epi& E) {
;     ...
;       PG8_STAGE(PG8_SB(0, 1), b2 + hstepB, voffB);
;       PG8_WAIT_V(6); PG8_BAR; PG8_MMA(1, 1, At, B1); PG8_BAR;
;       PG8_LDB(B0, 1, 0); PG8_SCHED; PG8_LDA(At, 1, 0); PG8_STAGE(PG8_SA(0, 1), a2 + hstepA, voffA);
;       PG8_WAIT_L(8); PG8_BAR; PG8_WAIT_L(0); PG8_MMA(0, 0, At, B0); PG8_BAR; PG8_SCHED;
;       PG8_LDB(B1, 1, 1); PG8_STAGE(PG8_SB(1, 0), b3, voffB);
;       PG8_BAR; PG8_WAIT_L(0); PG8_MMA(0, 1, At, B1); PG8_BAR;
;       PG8_LDA(At, 1, 1); PG8_STAGE(PG8_SA(1, 0), a3, voffA);
;       PG8_BAR; PG8_WAIT_L(0); PG8_MMA(1, 0, At, B0); PG8_BAR; PG8_SCHED;
	s_add_u32 s34, s10, 0x40000
	s_addc_u32 s35, s11, 0
	s_add_i32 s31, s33, s39
	v_lshl_add_u64 v[144:145], s[34:35], 0, v[134:135]
	s_mov_b32 m0, s31
	s_nop 0
	global_load_lds_dwordx4 v[144:145], off
	v_lshl_add_u64 v[144:145], s[34:35], 0, v[132:133]
	s_add_i32 m0, s31, 0x2000
	s_nop 0
	global_load_lds_dwordx4 v[144:145], off
	s_waitcnt vmcnt(6)
	s_barrier
	s_setprio 1
	v_mfma_f32_16x16x32_bf16 v[54:57], v[236:239], v[204:207], v[54:57]
	v_mfma_f32_16x16x32_bf16 v[50:53], v[244:247], v[204:207], v[50:53]
	v_mfma_f32_16x16x32_bf16 v[38:41], v[236:239], v[212:215], v[38:41]
	v_mfma_f32_16x16x32_bf16 v[34:37], v[244:247], v[212:215], v[34:37]
	v_mfma_f32_16x16x32_bf16 v[22:25], v[236:239], v[220:223], v[22:25]
	v_mfma_f32_16x16x32_bf16 v[18:21], v[244:247], v[220:223], v[18:21]
	v_mfma_f32_16x16x32_bf16 v[6:9], v[236:239], v[228:231], v[6:9]
	v_mfma_f32_16x16x32_bf16 v[2:5], v[244:247], v[228:231], v[2:5]
	v_mfma_f32_16x16x32_bf16 v[54:57], v[240:243], v[208:211], v[54:57]
	v_mfma_f32_16x16x32_bf16 v[50:53], v[248:251], v[208:211], v[50:53]
	v_mfma_f32_16x16x32_bf16 v[38:41], v[240:243], v[216:219], v[38:41]
	v_mfma_f32_16x16x32_bf16 v[34:37], v[248:251], v[216:219], v[34:37]
	v_mfma_f32_16x16x32_bf16 v[22:25], v[240:243], v[224:227], v[22:25]
	v_mfma_f32_16x16x32_bf16 v[18:21], v[248:251], v[224:227], v[18:21]
	v_mfma_f32_16x16x32_bf16 v[6:9], v[240:243], v[232:235], v[6:9]
	v_mfma_f32_16x16x32_bf16 v[2:5], v[248:251], v[232:235], v[2:5]
	s_setprio 0
	s_add_i32 s31, 0, 0x18000
	v_add_u32_e32 v173, s31, v131
	s_barrier
	ds_read_b128 v[144:147], v173
	ds_read_b128 v[148:151], v173 offset:1024
	ds_read_b128 v[152:155], v173 offset:2048
	ds_read_b128 v[200:203], v173 offset:3072
	s_add_u32 s24, s24, 0x40000
	s_addc_u32 s25, s25, 0
	s_mov_b32 m0, s42
	v_lshl_add_u64 v[236:237], s[24:25], 0, v[134:135]
	ds_read_b128 v[204:207], v172 offset:32768
	ds_read_b128 v[208:211], v172 offset:33792
	ds_read_b128 v[212:215], v172 offset:34816
	ds_read_b128 v[216:219], v172 offset:35840
	ds_read_b128 v[220:223], v172 offset:36864
	ds_read_b128 v[224:227], v172 offset:37888
	ds_read_b128 v[228:231], v172 offset:38912
	ds_read_b128 v[232:235], v172 offset:39936
	global_load_lds_dwordx4 v[236:237], off
	v_lshl_add_u64 v[236:237], s[24:25], 0, v[132:133]
	s_mov_b32 m0, s43
	s_nop 0
	global_load_lds_dwordx4 v[236:237], off
	s_waitcnt lgkmcnt(8)
	s_barrier
	s_waitcnt lgkmcnt(0)
	s_setprio 1
	v_mfma_f32_16x16x32_bf16 v[126:129], v[144:147], v[204:207], v[126:129]
	v_mfma_f32_16x16x32_bf16 v[122:125], v[152:155], v[204:207], v[122:125]
	v_mfma_f32_16x16x32_bf16 v[110:113], v[144:147], v[212:215], v[110:113]
	v_mfma_f32_16x16x32_bf16 v[106:109], v[152:155], v[212:215], v[106:109]
	v_mfma_f32_16x16x32_bf16 v[94:97], v[144:147], v[220:223], v[94:97]
	v_mfma_f32_16x16x32_bf16 v[90:93], v[152:155], v[220:223], v[90:93]
	v_mfma_f32_16x16x32_bf16 v[78:81], v[144:147], v[228:231], v[78:81]
	v_mfma_f32_16x16x32_bf16 v[74:77], v[152:155], v[228:231], v[74:77]
	v_mfma_f32_16x16x32_bf16 v[126:129], v[148:151], v[208:211], v[126:129]
	v_mfma_f32_16x16x32_bf16 v[122:125], v[200:203], v[208:211], v[122:125]
	v_mfma_f32_16x16x32_bf16 v[110:113], v[148:151], v[216:219], v[110:113]
	v_mfma_f32_16x16x32_bf16 v[106:109], v[200:203], v[216:219], v[106:109]
	v_mfma_f32_16x16x32_bf16 v[94:97], v[148:151], v[224:227], v[94:97]
	v_mfma_f32_16x16x32_bf16 v[90:93], v[200:203], v[224:227], v[90:93]
	v_mfma_f32_16x16x32_bf16 v[78:81], v[148:151], v[232:235], v[78:81]
	v_mfma_f32_16x16x32_bf16 v[74:77], v[200:203], v[232:235], v[74:77]
	s_setprio 0
	s_barrier
	s_add_i32 s24, 0, 0x1c000
	s_add_i32 s25, s31, s39
	v_add_u32_e32 v173, s24, v131
	v_lshl_add_u64 v[156:157], v[156:157], 0, s[86:87]
	s_mov_b32 m0, s25
	ds_read_b128 v[236:239], v173
	ds_read_b128 v[240:243], v173 offset:1024
	ds_read_b128 v[244:247], v173 offset:2048
	ds_read_b128 v[248:251], v173 offset:3072
	global_load_lds_dwordx4 v[156:157], off
	v_lshl_add_u64 v[156:157], v[174:175], 0, s[86:87]
	s_add_i32 m0, s25, 0x2000
	s_nop 0
	global_load_lds_dwordx4 v[156:157], off
	s_waitcnt lgkmcnt(0)
	s_barrier
	s_setprio 1
	v_mfma_f32_16x16x32_bf16 v[118:121], v[236:239], v[204:207], v[118:121]
	v_mfma_f32_16x16x32_bf16 v[114:117], v[244:247], v[204:207], v[114:117]
	v_mfma_f32_16x16x32_bf16 v[102:105], v[236:239], v[212:215], v[102:105]
	v_mfma_f32_16x16x32_bf16 v[98:101], v[244:247], v[212:215], v[98:101]
	v_mfma_f32_16x16x32_bf16 v[86:89], v[236:239], v[220:223], v[86:89]
	v_mfma_f32_16x16x32_bf16 v[82:85], v[244:247], v[220:223], v[82:85]
	v_mfma_f32_16x16x32_bf16 v[70:73], v[236:239], v[228:231], v[70:73]
	v_mfma_f32_16x16x32_bf16 v[66:69], v[244:247], v[228:231], v[66:69]
	v_mfma_f32_16x16x32_bf16 v[118:121], v[240:243], v[208:211], v[118:121]
	v_mfma_f32_16x16x32_bf16 v[114:117], v[248:251], v[208:211], v[114:117]
	v_mfma_f32_16x16x32_bf16 v[102:105], v[240:243], v[216:219], v[102:105]
	v_mfma_f32_16x16x32_bf16 v[98:101], v[248:251], v[216:219], v[98:101]
	v_mfma_f32_16x16x32_bf16 v[86:89], v[240:243], v[224:227], v[86:89]
	v_mfma_f32_16x16x32_bf16 v[82:85], v[248:251], v[224:227], v[82:85]
	v_mfma_f32_16x16x32_bf16 v[70:73], v[240:243], v[232:235], v[70:73]
	v_mfma_f32_16x16x32_bf16 v[66:69], v[248:251], v[232:235], v[66:69]
	s_setprio 0
	s_mov_b32 m0, s45
	v_lshl_add_u64 v[156:157], v[182:183], 0, s[86:87]
	s_barrier
	ds_read_b128 v[204:207], v172 offset:49152
	ds_read_b128 v[208:211], v172 offset:50176
	ds_read_b128 v[212:215], v172 offset:51200
	ds_read_b128 v[216:219], v172 offset:52224
	ds_read_b128 v[220:223], v172 offset:53248
	ds_read_b128 v[224:227], v172 offset:54272
	ds_read_b128 v[228:231], v172 offset:55296
	ds_read_b128 v[232:235], v172 offset:56320
	global_load_lds_dwordx4 v[156:157], off
	v_lshl_add_u64 v[156:157], v[184:185], 0, s[86:87]
	s_mov_b32 m0, s46
	s_nop 0
	global_load_lds_dwordx4 v[156:157], off
	s_waitcnt lgkmcnt(0)
	s_barrier
; #define PG8_STAGE(bufoff, gbase, voff) do { _Pragma("unroll") for (int _i = 0; _i < 2; ++_i) \
;     __builtin_amdgcn_global_load_lds((const unsigned*)((const char*)(gbase) + (voff)[_i]), (PG8_LAS unsigned*)(lds + (bufoff) + ldsw + _i * 8192), 16, 0, 0); } while (0)
; #define PG8_WAIT_V(n) asm volatile("s_waitcnt vmcnt(" #n ")" ::: "memory")
; template <class Epi, class Sched>
; __device__ __forceinline__ void gemm_phase(PG8_LAS unsigned char* lds, const int lda, const int ldb, const Sched& S, const Epi& E) {
;     ...
;       PG8_BAR; PG8_WAIT_L(0); PG8_MMA(1, 0, At, B0); PG8_BAR; PG8_SCHED;
;       PG8_STAGE(PG8_SB(1, 1), b3 + hstepB, voffB);
;       PG8_WAIT_V(6); PG8_BAR; PG8_MMA(1, 1, At, B1); PG8_BAR;
;     }
;   __device__ __forceinline__ void operator()(const f32x4 (&acc)[2][2][4][2], const Unit& u, int wr, int wc, int fr, int fq) const {
;     ...
;         const int r = u.pm * 256 + ai * 128 + wr * 64 + m * 16 + fr;
; #pragma unroll
;         for (int bj = 0; bj < 2; ++bj)
; #pragma unroll
;           for (int n = 0; n < 2; ++n) {
;             const f32x4 v = acc[ai][bj][m][n];
;             const int c = u.pn * 256 + bj * 128 + wc * 32 + n * 16 + 4 * fq;
;             if (u.pn < 7) {
;               uint2 w; w.x = pack2(v[0], v[1]); w.y = pack2(v[2], v[3]);
;               *reinterpret_cast<uint2*>(PB + (size_t)r * PBW + c) = w;
;             } else {
;               const int nn = c - 1792, part = nn >> 8, ch = nn & 255;
;               if (u.pn == 7 && bj == 0 && wc == 1 && n == 1) {
;                 *reinterpret_cast<float4*>(AB + (size_t)r * 16 + 4 * fq) = make_float4(v[0], v[1], v[2], v[3]);
;               } else {
;                 u16* d; int cstride;
;                 if (r < ML) { const int b = r >> 11, tt = r & 2047; d = FT + ((size_t)(b * 256)) * 4096 + part * 2048 + tt; cstride = 4096; }
;                 else { const int rc = r - ML, b = rc >> 8, tt = rc & 255; d = FTC + ((size_t)(b * 256)) * 512 + part * 256 + tt; cstride = 512; }
; #pragma unroll
;                 for (int e = 0; e < 4; ++e) d[(size_t)(ch + e) * cstride] = f2bf(v[e]);
;                 if (u.pn == 7 && bj == 0 && wc == 0) {
; #pragma unroll
;                   for (int e = 0; e < 4; ++e) {
;                     const int kc = n * 16 + 4 * fq + e;
;                     if (kc >= 1 && kc <= 16) d[(size_t)(64 - kc) * cstride] = f2bf(v[e]);
	s_setprio 1
	v_mfma_f32_16x16x32_bf16 v[62:65], v[144:147], v[204:207], v[62:65]
	v_mfma_f32_16x16x32_bf16 v[58:61], v[152:155], v[204:207], v[58:61]
	v_mfma_f32_16x16x32_bf16 v[46:49], v[144:147], v[212:215], v[46:49]
	v_mfma_f32_16x16x32_bf16 v[42:45], v[152:155], v[212:215], v[42:45]
	v_mfma_f32_16x16x32_bf16 v[30:33], v[144:147], v[220:223], v[30:33]
	v_mfma_f32_16x16x32_bf16 v[26:29], v[152:155], v[220:223], v[26:29]
	v_mfma_f32_16x16x32_bf16 v[14:17], v[144:147], v[228:231], v[14:17]
	v_mfma_f32_16x16x32_bf16 v[10:13], v[152:155], v[228:231], v[10:13]
	v_mfma_f32_16x16x32_bf16 v[62:65], v[148:151], v[208:211], v[62:65]
	v_mfma_f32_16x16x32_bf16 v[58:61], v[200:203], v[208:211], v[58:61]
	v_mfma_f32_16x16x32_bf16 v[46:49], v[148:151], v[216:219], v[46:49]
	v_mfma_f32_16x16x32_bf16 v[42:45], v[200:203], v[216:219], v[42:45]
	v_mfma_f32_16x16x32_bf16 v[30:33], v[148:151], v[224:227], v[30:33]
	v_mfma_f32_16x16x32_bf16 v[26:29], v[200:203], v[224:227], v[26:29]
	v_mfma_f32_16x16x32_bf16 v[14:17], v[148:151], v[232:235], v[14:17]
	v_mfma_f32_16x16x32_bf16 v[10:13], v[200:203], v[232:235], v[10:13]
	s_setprio 0
	s_barrier
	s_add_u32 s10, s10, 0x40080
	s_addc_u32 s11, s11, 0
	s_add_i32 s24, s24, s39
	v_lshl_add_u64 v[144:145], s[10:11], 0, v[134:135]
	s_mov_b32 m0, s24
	s_nop 0
	global_load_lds_dwordx4 v[144:145], off
	v_lshl_add_u64 v[144:145], s[10:11], 0, v[132:133]
	s_add_i32 m0, s24, 0x2000
	s_nop 0
	global_load_lds_dwordx4 v[144:145], off
	s_waitcnt vmcnt(6)
	s_barrier
	s_setprio 1
	v_mfma_f32_16x16x32_bf16 v[54:57], v[236:239], v[204:207], v[54:57]
	v_mfma_f32_16x16x32_bf16 v[50:53], v[244:247], v[204:207], v[50:53]
	v_mfma_f32_16x16x32_bf16 v[38:41], v[236:239], v[212:215], v[38:41]
	v_mfma_f32_16x16x32_bf16 v[34:37], v[244:247], v[212:215], v[34:37]
	v_mfma_f32_16x16x32_bf16 v[22:25], v[236:239], v[220:223], v[22:25]
	v_mfma_f32_16x16x32_bf16 v[18:21], v[244:247], v[220:223], v[18:21]
	v_mfma_f32_16x16x32_bf16 v[6:9], v[236:239], v[228:231], v[6:9]
	v_mfma_f32_16x16x32_bf16 v[2:5], v[244:247], v[228:231], v[2:5]
	v_mfma_f32_16x16x32_bf16 v[54:57], v[240:243], v[208:211], v[54:57]
	v_mfma_f32_16x16x32_bf16 v[50:53], v[248:251], v[208:211], v[50:53]
	v_mfma_f32_16x16x32_bf16 v[38:41], v[240:243], v[216:219], v[38:41]
	v_mfma_f32_16x16x32_bf16 v[34:37], v[248:251], v[216:219], v[34:37]
	v_mfma_f32_16x16x32_bf16 v[22:25], v[240:243], v[224:227], v[22:25]
	v_mfma_f32_16x16x32_bf16 v[18:21], v[248:251], v[224:227], v[18:21]
	v_mfma_f32_16x16x32_bf16 v[6:9], v[240:243], v[232:235], v[6:9]
	v_mfma_f32_16x16x32_bf16 v[2:5], v[248:251], v[232:235], v[2:5]
	s_setprio 0
	s_add_i32 s30, s30, 2
	s_add_u32 s8, s8, 0x100
	s_addc_u32 s9, s9, 0
	s_add_u32 s28, s28, 0x100
	s_addc_u32 s29, s29, 0
	s_cmp_gt_u32 s30, 13
	s_barrier
	s_cbranch_scc0 .LBB0_335
	s_lshl_b32 s15, s2, 8
	s_add_i32 s15, s15, s44
	v_or_b32_e32 v152, s15, v1
	s_mov_b32 s2, 0xffff
	v_cmp_lt_i32_e64 s[10:11], s2, v152
	s_and_b32 s2, s15, 0xffffff00
	s_add_i32 s2, s2, 0xffff0000
	s_lshl_b64 s[28:29], s[2:3], 10
	s_ashr_i32 s2, s15, 3
	s_and_b32 s8, s2, 0xffffff00
	s_ashr_i32 s9, s8, 31
	s_lshl_b64 s[26:27], s[8:9], 13
	s_lshl_b32 s24, s48, 8
	s_cmp_gt_i32 s48, 6
	s_cselect_b64 s[30:31], -1, 0
	v_bitop3_b32 v146, s15, v186, v1 bitop3:0xc8
	v_bitop3_b32 v148, s15, v187, v1 bitop3:0xc8
	s_mov_b64 s[8:9], -1
	s_and_b64 vcc, exec, s[30:31]
	s_cbranch_vccz .LBB0_346
	s_and_saveexec_b64 s[8:9], s[10:11]
	s_xor_b64 s[8:9], exec, s[8:9]
	s_add_u32 s34, s54, s28
	s_addc_u32 s35, s55, s29
	s_or_saveexec_b64 s[8:9], s[8:9]
	s_add_i32 s2, s24, 0xfffff900
	v_mov_b64_e32 v[144:145], 0x200
	v_mov_b32_e32 v150, s2
	v_mov_b64_e32 v[154:155], s[34:35]
	v_mov_b64_e32 v[156:157], v[146:147]
	s_xor_b64 exec, exec, s[8:9]
	s_add_u32 s34, s69, s26
	s_addc_u32 s35, s52, s27
	s_lshl_b32 s2, s2, 3
	v_mov_b64_e32 v[144:145], 0x1000
	v_mov_b32_e32 v150, s2
	v_mov_b64_e32 v[154:155], s[34:35]
	v_mov_b64_e32 v[156:157], v[148:149]
	s_or_b64 exec, exec, s[8:9]
	v_ashrrev_i32_e32 v151, 31, v150
	v_lshl_add_u64 v[150:151], v[150:151], 1, v[154:155]
	v_lshlrev_b32_e32 v154, 1, v156
	v_mov_b32_e32 v155, v0
	v_mul_u32_u24_e32 v145, v144, v136
	v_lshl_add_u64 v[150:151], v[150:151], 0, v[154:155]
	v_lshlrev_b32_e32 v154, 1, v145
	v_cvt_pk_bf16_f32 v149, v126, s0
	v_lshl_add_u64 v[154:155], v[150:151], 0, v[154:155]
	v_mul_u32_u24_e32 v147, v144, v166
	global_store_short v[154:155], v149, off
	v_lshlrev_b32_e32 v154, 1, v147
	v_mov_b32_e32 v155, v0
	v_cvt_pk_bf16_f32 v145, v127, s0
	v_lshl_add_u64 v[154:155], v[150:151], 0, v[154:155]
	v_mul_u32_u24_e32 v153, v144, v167
	global_store_short v[154:155], v145, off
	v_lshlrev_b32_e32 v154, 1, v153
	v_mov_b32_e32 v155, v0
	s_cmp_lg_u32 s48, 7
	v_cvt_pk_bf16_f32 v147, v128, s0
	v_lshl_add_u64 v[154:155], v[150:151], 0, v[154:155]
	s_cselect_b64 s[8:9], -1, 0
	global_store_short v[154:155], v147, off
	v_mul_u32_u24_e32 v154, v144, v168
	s_xor_b64 s[34:35], s[12:13], -1
	v_lshlrev_b32_e32 v154, 1, v154
	v_mov_b32_e32 v155, v0
	s_or_b64 s[8:9], s[34:35], s[8:9]
	v_cvt_pk_bf16_f32 v153, v129, s0
	v_lshl_add_u64 v[154:155], v[150:151], 0, v[154:155]
	s_and_b64 vcc, exec, s[8:9]
	global_store_short v[154:155], v153, off
	s_cbranch_vccnz .LBB0_345
	s_and_saveexec_b64 s[8:9], s[4:5]
	s_cbranch_execz .LBB0_344
	v_mul_u32_u24_e32 v154, v144, v158
	v_lshlrev_b32_e32 v154, 1, v154
	v_mov_b32_e32 v155, v0
	v_lshl_add_u64 v[154:155], v[150:151], 0, v[154:155]
	global_store_short v[154:155], v149, off

; #define PG8_STAGE(bufoff, gbase, voff) do { _Pragma("unroll") for (int _i = 0; _i < 2; ++_i) \
;     __builtin_amdgcn_global_load_lds((const unsigned*)((const char*)(gbase) + (voff)[_i]), (PG8_LAS unsigned*)(lds + (bufoff) + ldsw + _i * 8192), 16, 0, 0); } while (0)
; #define PG8_LDA(dst, b, h) do { _Pragma("unroll") for (int m = 0; m < 4; ++m) _Pragma("unroll") for (int k = 0; k < 2; ++k) dst[m][k] = *(const PG8_LAS bf16x8*)(lds + PG8_SA(b, h) + aoff + m * 2048 + k * 1024); } while (0)
; #define PG8_LDB(dst, b, h) do { _Pragma("unroll") for (int n = 0; n < 2; ++n) _Pragma("unroll") for (int k = 0; k < 2; ++k) dst[n][k] = *(const PG8_LAS bf16x8*)(lds + PG8_SB(b, h) + boff + n * 2048 + k * 1024); } while (0)
; #define PG8_MMA(ai, bj, At, Bt) do { __builtin_amdgcn_s_setprio(1); _Pragma("unroll") for (int m = 0; m < 4; ++m) _Pragma("unroll") for (int n = 0; n < 2; ++n) _Pragma("unroll") for (int k = 0; k < 2; ++k) \
;     acc[ai][bj][m][n] = __builtin_amdgcn_mfma_f32_16x16x32_bf16(Bt[n][k], At[m][k], acc[ai][bj][m][n], 0, 0, 0); __builtin_amdgcn_s_setprio(0); } while (0)
; #define PG8_WAIT_L(n) asm volatile("s_waitcnt lgkmcnt(" #n ")" ::: "memory")
; #define PG8_BAR __builtin_amdgcn_s_barrier()
; #define PG8_SCHED __builtin_amdgcn_sched_barrier(0)
; template <class Epi, class Sched>
; __device__ __forceinline__ void gemm_phase(PG8_LAS unsigned char* lds, const int lda, const int ldb, const Sched& S, const Epi& E) {
;     ...
;     for (int t = 0; t < nt; t += 2) {
;       const bool last = (t == nt - 2);
;       const char* a1 = cA + (size_t)(t + 1) * kstep;
;       const char* a2 = last ? nA : cA + (size_t)(t + 2) * kstep; const char* b2 = last ? nB : cB + (size_t)(t + 2) * kstep;
;       const char* a3 = a2 + kstep; const char* b3 = b2 + kstep;
;       PG8_LDB(B0, 0, 0); PG8_SCHED; PG8_LDA(At, 0, 0); PG8_STAGE(PG8_SA(1, 1), a1 + hstepA, voffA);
;       PG8_WAIT_L(8); PG8_BAR; PG8_WAIT_L(0); PG8_MMA(0, 0, At, B0); PG8_BAR; PG8_SCHED;
;       PG8_LDB(B1, 0, 1); PG8_STAGE(PG8_SB(0, 0), b2, voffB);
;       PG8_BAR; PG8_WAIT_L(0); PG8_MMA(0, 1, At, B1); PG8_BAR;
;       PG8_LDA(At, 0, 1); PG8_STAGE(PG8_SA(0, 0), a2, voffA);
;       PG8_BAR; PG8_WAIT_L(0); PG8_MMA(1, 0, At, B0); PG8_BAR; PG8_SCHED;
.LBB0_685:
	s_add_u32 s12, s10, 0xfffc0080
	s_addc_u32 s13, s11, -1
	s_add_i32 s31, 0, 0x10000
	v_add_u32_e32 v156, s31, v131
	ds_read_b128 v[144:147], v156
	ds_read_b128 v[148:151], v156 offset:1024
	ds_read_b128 v[152:155], v156 offset:2048
	ds_read_b128 v[200:203], v156 offset:3072
	s_cmp_eq_u32 s30, 12
	s_cselect_b32 s25, s19, s13
	s_cselect_b32 s24, s26, s12
	s_cselect_b32 s13, s17, s29
	s_cselect_b32 s12, s27, s28
	v_lshl_add_u64 v[156:157], s[10:11], 0, v[140:141]
	s_add_i32 m0, s40, 0xc000
	ds_read_b128 v[204:207], v172
	ds_read_b128 v[208:211], v172 offset:1024
	ds_read_b128 v[212:215], v172 offset:2048
	ds_read_b128 v[216:219], v172 offset:3072
	ds_read_b128 v[220:223], v172 offset:4096
	ds_read_b128 v[224:227], v172 offset:5120
	ds_read_b128 v[228:231], v172 offset:6144
	ds_read_b128 v[232:235], v172 offset:7168
	global_load_lds_dwordx4 v[156:157], off
	v_lshl_add_u64 v[156:157], s[10:11], 0, v[142:143]
	s_add_i32 m0, s40, 0xe000
	s_nop 0
	global_load_lds_dwordx4 v[156:157], off
	s_waitcnt lgkmcnt(8)
	s_barrier
	s_waitcnt lgkmcnt(0)
	s_setprio 1
	v_mfma_f32_16x16x32_bf16 v[126:129], v[144:147], v[204:207], v[126:129]
	v_mfma_f32_16x16x32_bf16 v[122:125], v[152:155], v[204:207], v[122:125]
	v_mfma_f32_16x16x32_bf16 v[110:113], v[144:147], v[212:215], v[110:113]
	v_mfma_f32_16x16x32_bf16 v[106:109], v[152:155], v[212:215], v[106:109]
	v_mfma_f32_16x16x32_bf16 v[94:97], v[144:147], v[220:223], v[94:97]
	v_mfma_f32_16x16x32_bf16 v[90:93], v[152:155], v[220:223], v[90:93]
	v_mfma_f32_16x16x32_bf16 v[78:81], v[144:147], v[228:231], v[78:81]
	v_mfma_f32_16x16x32_bf16 v[74:77], v[152:155], v[228:231], v[74:77]
	v_mfma_f32_16x16x32_bf16 v[126:129], v[148:151], v[208:211], v[126:129]
	v_mfma_f32_16x16x32_bf16 v[122:125], v[200:203], v[208:211], v[122:125]
	v_mfma_f32_16x16x32_bf16 v[110:113], v[148:151], v[216:219], v[110:113]
	v_mfma_f32_16x16x32_bf16 v[106:109], v[200:203], v[216:219], v[106:109]
	v_mfma_f32_16x16x32_bf16 v[94:97], v[148:151], v[224:227], v[94:97]
	v_mfma_f32_16x16x32_bf16 v[90:93], v[200:203], v[224:227], v[90:93]
	v_mfma_f32_16x16x32_bf16 v[78:81], v[148:151], v[232:235], v[78:81]
	v_mfma_f32_16x16x32_bf16 v[74:77], v[200:203], v[232:235], v[74:77]
	s_setprio 0
	s_barrier
	s_add_i32 s33, 0, 0x14000
	v_add_u32_e32 v156, s33, v131
	s_add_i32 s31, s31, s39
	ds_read_b128 v[236:239], v156
	ds_read_b128 v[240:243], v156 offset:1024
	ds_read_b128 v[244:247], v156 offset:2048
	ds_read_b128 v[248:251], v156 offset:3072
	v_lshl_add_u64 v[156:157], s[12:13], 0, v[134:135]
	s_mov_b32 m0, s31
	v_lshl_add_u64 v[174:175], s[12:13], 0, v[132:133]
	global_load_lds_dwordx4 v[156:157], off
	s_add_i32 m0, s31, 0x2000
	s_nop 0
	global_load_lds_dwordx4 v[174:175], off
	s_waitcnt lgkmcnt(0)
	s_barrier
	s_setprio 1
	v_mfma_f32_16x16x32_bf16 v[118:121], v[236:239], v[204:207], v[118:121]
	v_mfma_f32_16x16x32_bf16 v[114:117], v[244:247], v[204:207], v[114:117]
	v_mfma_f32_16x16x32_bf16 v[102:105], v[236:239], v[212:215], v[102:105]
	v_mfma_f32_16x16x32_bf16 v[98:101], v[244:247], v[212:215], v[98:101]
	v_mfma_f32_16x16x32_bf16 v[86:89], v[236:239], v[220:223], v[86:89]
	v_mfma_f32_16x16x32_bf16 v[82:85], v[244:247], v[220:223], v[82:85]
	v_mfma_f32_16x16x32_bf16 v[70:73], v[236:239], v[228:231], v[70:73]
	v_mfma_f32_16x16x32_bf16 v[66:69], v[244:247], v[228:231], v[66:69]
	v_mfma_f32_16x16x32_bf16 v[118:121], v[240:243], v[208:211], v[118:121]
	v_mfma_f32_16x16x32_bf16 v[114:117], v[248:251], v[208:211], v[114:117]
	v_mfma_f32_16x16x32_bf16 v[102:105], v[240:243], v[216:219], v[102:105]
	v_mfma_f32_16x16x32_bf16 v[98:101], v[248:251], v[216:219], v[98:101]
	v_mfma_f32_16x16x32_bf16 v[86:89], v[240:243], v[224:227], v[86:89]
	v_mfma_f32_16x16x32_bf16 v[82:85], v[248:251], v[224:227], v[82:85]
	v_mfma_f32_16x16x32_bf16 v[70:73], v[240:243], v[232:235], v[70:73]
	v_mfma_f32_16x16x32_bf16 v[66:69], v[248:251], v[232:235], v[66:69]
	s_setprio 0
	s_mov_b32 m0, s40
	v_lshl_add_u64 v[182:183], s[24:25], 0, v[134:135]
	s_barrier
	ds_read_b128 v[204:207], v172 offset:16384
	ds_read_b128 v[208:211], v172 offset:17408
	ds_read_b128 v[212:215], v172 offset:18432
	ds_read_b128 v[216:219], v172 offset:19456
	ds_read_b128 v[220:223], v172 offset:20480
	ds_read_b128 v[224:227], v172 offset:21504
	ds_read_b128 v[228:231], v172 offset:22528
	ds_read_b128 v[232:235], v172 offset:23552
	global_load_lds_dwordx4 v[182:183], off
	v_lshl_add_u64 v[184:185], s[24:25], 0, v[132:133]
	s_mov_b32 m0, s41
	s_nop 0
	global_load_lds_dwordx4 v[184:185], off
	s_waitcnt lgkmcnt(0)
	s_barrier
	s_setprio 1
	v_mfma_f32_16x16x32_bf16 v[62:65], v[144:147], v[204:207], v[62:65]
	v_mfma_f32_16x16x32_bf16 v[58:61], v[152:155], v[204:207], v[58:61]
	v_mfma_f32_16x16x32_bf16 v[46:49], v[144:147], v[212:215], v[46:49]
	v_mfma_f32_16x16x32_bf16 v[42:45], v[152:155], v[212:215], v[42:45]
	v_mfma_f32_16x16x32_bf16 v[30:33], v[144:147], v[220:223], v[30:33]
	v_mfma_f32_16x16x32_bf16 v[26:29], v[152:155], v[220:223], v[26:29]
	v_mfma_f32_16x16x32_bf16 v[14:17], v[144:147], v[228:231], v[14:17]
	v_mfma_f32_16x16x32_bf16 v[10:13], v[152:155], v[228:231], v[10:13]
	v_mfma_f32_16x16x32_bf16 v[62:65], v[148:151], v[208:211], v[62:65]
	v_mfma_f32_16x16x32_bf16 v[58:61], v[200:203], v[208:211], v[58:61]
	v_mfma_f32_16x16x32_bf16 v[46:49], v[148:151], v[216:219], v[46:49]
	v_mfma_f32_16x16x32_bf16 v[42:45], v[200:203], v[216:219], v[42:45]
	v_mfma_f32_16x16x32_bf16 v[30:33], v[148:151], v[224:227], v[30:33]
	v_mfma_f32_16x16x32_bf16 v[26:29], v[200:203], v[224:227], v[26:29]
	v_mfma_f32_16x16x32_bf16 v[14:17], v[148:151], v[232:235], v[14:17]
	v_mfma_f32_16x16x32_bf16 v[10:13], v[200:203], v[232:235], v[10:13]
	s_setprio 0
	s_barrier
; #define PG8_STAGE(bufoff, gbase, voff) do { _Pragma("unroll") for (int _i = 0; _i < 2; ++_i) \
;     __builtin_amdgcn_global_load_lds((const unsigned*)((const char*)(gbase) + (voff)[_i]), (PG8_LAS unsigned*)(lds + (bufoff) + ldsw + _i * 8192), 16, 0, 0); } while (0)
; #define PG8_LDA(dst, b, h) do { _Pragma("unroll") for (int m = 0; m < 4; ++m) _Pragma("unroll") for (int k = 0; k < 2; ++k) dst[m][k] = *(const PG8_LAS bf16x8*)(lds + PG8_SA(b, h) + aoff + m * 2048 + k * 1024); } while (0)
; #define PG8_LDB(dst, b, h) do { _Pragma("unroll") for (int n = 0; n < 2; ++n) _Pragma("unroll") for (int k = 0; k < 2; ++k) dst[n][k] = *(const PG8_LAS bf16x8*)(lds + PG8_SB(b, h) + boff + n * 2048 + k * 1024); } while (0)
; #define PG8_MMA(ai, bj, At, Bt) do { __builtin_amdgcn_s_setprio(1); _Pragma("unroll") for (int m = 0; m < 4; ++m) _Pragma("unroll") for (int n = 0; n < 2; ++n) _Pragma("unroll") for (int k = 0; k < 2; ++k) \
;     acc[ai][bj][m][n] = __builtin_amdgcn_mfma_f32_16x16x32_bf16(Bt[n][k], At[m][k], acc[ai][bj][m][n], 0, 0, 0); __builtin_amdgcn_s_setprio(0); } while (0)
; #define PG8_WAIT_V(n) asm volatile("s_waitcnt vmcnt(" #n ")" ::: "memory")
; #define PG8_WAIT_L(n) asm volatile("s_waitcnt lgkmcnt(" #n ")" ::: "memory")
; #define PG8_BAR __builtin_amdgcn_s_barrier()
; #define PG8_SCHED __builtin_amdgcn_sched_barrier(0)
; template <class Epi, class Sched>
; __device__ __forceinline__ void gemm_phase(PG8_LAS unsigned char* lds, const int lda, const int ldb, const Sched& S, const Epi& E) {
;     ...
;       PG8_STAGE(PG8_SB(0, 1), b2 + hstepB, voffB);
;       PG8_WAIT_V(6); PG8_BAR; PG8_MMA(1, 1, At, B1); PG8_BAR;
;       PG8_LDB(B0, 1, 0); PG8_SCHED; PG8_LDA(At, 1, 0); PG8_STAGE(PG8_SA(0, 1), a2 + hstepA, voffA);
;       PG8_WAIT_L(8); PG8_BAR; PG8_WAIT_L(0); PG8_MMA(0, 0, At, B0); PG8_BAR; PG8_SCHED;
;       PG8_LDB(B1, 1, 1); PG8_STAGE(PG8_SB(1, 0), b3, voffB);
;       PG8_BAR; PG8_WAIT_L(0); PG8_MMA(0, 1, At, B1); PG8_BAR;
;       PG8_LDA(At, 1, 1); PG8_STAGE(PG8_SA(1, 0), a3, voffA);
;       PG8_BAR; PG8_WAIT_L(0); PG8_MMA(1, 0, At, B0); PG8_BAR; PG8_SCHED;
	s_add_u32 s34, s12, 0x40000
	s_addc_u32 s35, s13, 0
	s_add_i32 s31, s33, s39
	v_lshl_add_u64 v[144:145], s[34:35], 0, v[134:135]
	s_mov_b32 m0, s31
	s_nop 0
	global_load_lds_dwordx4 v[144:145], off
	v_lshl_add_u64 v[144:145], s[34:35], 0, v[132:133]
	s_add_i32 m0, s31, 0x2000
	s_nop 0
	global_load_lds_dwordx4 v[144:145], off
	s_waitcnt vmcnt(6)
	s_barrier
	s_setprio 1
	v_mfma_f32_16x16x32_bf16 v[54:57], v[236:239], v[204:207], v[54:57]
	v_mfma_f32_16x16x32_bf16 v[50:53], v[244:247], v[204:207], v[50:53]
	v_mfma_f32_16x16x32_bf16 v[38:41], v[236:239], v[212:215], v[38:41]
	v_mfma_f32_16x16x32_bf16 v[34:37], v[244:247], v[212:215], v[34:37]
	v_mfma_f32_16x16x32_bf16 v[22:25], v[236:239], v[220:223], v[22:25]
	v_mfma_f32_16x16x32_bf16 v[18:21], v[244:247], v[220:223], v[18:21]
	v_mfma_f32_16x16x32_bf16 v[6:9], v[236:239], v[228:231], v[6:9]
	v_mfma_f32_16x16x32_bf16 v[2:5], v[244:247], v[228:231], v[2:5]
	v_mfma_f32_16x16x32_bf16 v[54:57], v[240:243], v[208:211], v[54:57]
	v_mfma_f32_16x16x32_bf16 v[50:53], v[248:251], v[208:211], v[50:53]
	v_mfma_f32_16x16x32_bf16 v[38:41], v[240:243], v[216:219], v[38:41]
	v_mfma_f32_16x16x32_bf16 v[34:37], v[248:251], v[216:219], v[34:37]
	v_mfma_f32_16x16x32_bf16 v[22:25], v[240:243], v[224:227], v[22:25]
	v_mfma_f32_16x16x32_bf16 v[18:21], v[248:251], v[224:227], v[18:21]
	v_mfma_f32_16x16x32_bf16 v[6:9], v[240:243], v[232:235], v[6:9]
	v_mfma_f32_16x16x32_bf16 v[2:5], v[248:251], v[232:235], v[2:5]
	s_setprio 0
	s_add_i32 s31, 0, 0x18000
	v_add_u32_e32 v173, s31, v131
	s_barrier
	ds_read_b128 v[144:147], v173
	ds_read_b128 v[148:151], v173 offset:1024
	ds_read_b128 v[152:155], v173 offset:2048
	ds_read_b128 v[200:203], v173 offset:3072
	s_add_u32 s24, s24, 0x40000
	s_addc_u32 s25, s25, 0
	s_mov_b32 m0, s42
	v_lshl_add_u64 v[236:237], s[24:25], 0, v[134:135]
	ds_read_b128 v[204:207], v172 offset:32768
	ds_read_b128 v[208:211], v172 offset:33792
	ds_read_b128 v[212:215], v172 offset:34816
	ds_read_b128 v[216:219], v172 offset:35840
	ds_read_b128 v[220:223], v172 offset:36864
	ds_read_b128 v[224:227], v172 offset:37888
	ds_read_b128 v[228:231], v172 offset:38912
	ds_read_b128 v[232:235], v172 offset:39936
	global_load_lds_dwordx4 v[236:237], off
	v_lshl_add_u64 v[236:237], s[24:25], 0, v[132:133]
	s_mov_b32 m0, s43
	s_nop 0
	global_load_lds_dwordx4 v[236:237], off
	s_waitcnt lgkmcnt(8)
	s_barrier
	s_waitcnt lgkmcnt(0)
	s_setprio 1
	v_mfma_f32_16x16x32_bf16 v[126:129], v[144:147], v[204:207], v[126:129]
	v_mfma_f32_16x16x32_bf16 v[122:125], v[152:155], v[204:207], v[122:125]
	v_mfma_f32_16x16x32_bf16 v[110:113], v[144:147], v[212:215], v[110:113]
	v_mfma_f32_16x16x32_bf16 v[106:109], v[152:155], v[212:215], v[106:109]
	v_mfma_f32_16x16x32_bf16 v[94:97], v[144:147], v[220:223], v[94:97]
	v_mfma_f32_16x16x32_bf16 v[90:93], v[152:155], v[220:223], v[90:93]
	v_mfma_f32_16x16x32_bf16 v[78:81], v[144:147], v[228:231], v[78:81]
	v_mfma_f32_16x16x32_bf16 v[74:77], v[152:155], v[228:231], v[74:77]
	v_mfma_f32_16x16x32_bf16 v[126:129], v[148:151], v[208:211], v[126:129]
	v_mfma_f32_16x16x32_bf16 v[122:125], v[200:203], v[208:211], v[122:125]
	v_mfma_f32_16x16x32_bf16 v[110:113], v[148:151], v[216:219], v[110:113]
	v_mfma_f32_16x16x32_bf16 v[106:109], v[200:203], v[216:219], v[106:109]
	v_mfma_f32_16x16x32_bf16 v[94:97], v[148:151], v[224:227], v[94:97]
	v_mfma_f32_16x16x32_bf16 v[90:93], v[200:203], v[224:227], v[90:93]
	v_mfma_f32_16x16x32_bf16 v[78:81], v[148:151], v[232:235], v[78:81]
	v_mfma_f32_16x16x32_bf16 v[74:77], v[200:203], v[232:235], v[74:77]
	s_setprio 0
	s_barrier
	s_add_i32 s24, 0, 0x1c000
	s_add_i32 s25, s31, s39
	v_add_u32_e32 v173, s24, v131
	v_lshl_add_u64 v[156:157], v[156:157], 0, s[86:87]
	s_mov_b32 m0, s25
	ds_read_b128 v[236:239], v173
	ds_read_b128 v[240:243], v173 offset:1024
	ds_read_b128 v[244:247], v173 offset:2048
	ds_read_b128 v[248:251], v173 offset:3072
	global_load_lds_dwordx4 v[156:157], off
	v_lshl_add_u64 v[156:157], v[174:175], 0, s[86:87]
	s_add_i32 m0, s25, 0x2000
	s_nop 0
	global_load_lds_dwordx4 v[156:157], off
	s_waitcnt lgkmcnt(0)
	s_barrier
	s_setprio 1
	v_mfma_f32_16x16x32_bf16 v[118:121], v[236:239], v[204:207], v[118:121]
	v_mfma_f32_16x16x32_bf16 v[114:117], v[244:247], v[204:207], v[114:117]
	v_mfma_f32_16x16x32_bf16 v[102:105], v[236:239], v[212:215], v[102:105]
	v_mfma_f32_16x16x32_bf16 v[98:101], v[244:247], v[212:215], v[98:101]
	v_mfma_f32_16x16x32_bf16 v[86:89], v[236:239], v[220:223], v[86:89]
	v_mfma_f32_16x16x32_bf16 v[82:85], v[244:247], v[220:223], v[82:85]
	v_mfma_f32_16x16x32_bf16 v[70:73], v[236:239], v[228:231], v[70:73]
	v_mfma_f32_16x16x32_bf16 v[66:69], v[244:247], v[228:231], v[66:69]
	v_mfma_f32_16x16x32_bf16 v[118:121], v[240:243], v[208:211], v[118:121]
	v_mfma_f32_16x16x32_bf16 v[114:117], v[248:251], v[208:211], v[114:117]
	v_mfma_f32_16x16x32_bf16 v[102:105], v[240:243], v[216:219], v[102:105]
	v_mfma_f32_16x16x32_bf16 v[98:101], v[248:251], v[216:219], v[98:101]
	v_mfma_f32_16x16x32_bf16 v[86:89], v[240:243], v[224:227], v[86:89]
	v_mfma_f32_16x16x32_bf16 v[82:85], v[248:251], v[224:227], v[82:85]
	v_mfma_f32_16x16x32_bf16 v[70:73], v[240:243], v[232:235], v[70:73]
	v_mfma_f32_16x16x32_bf16 v[66:69], v[248:251], v[232:235], v[66:69]
	s_setprio 0
	s_mov_b32 m0, s45
	v_lshl_add_u64 v[156:157], v[182:183], 0, s[86:87]
	s_barrier
	ds_read_b128 v[204:207], v172 offset:49152
	ds_read_b128 v[208:211], v172 offset:50176
	ds_read_b128 v[212:215], v172 offset:51200
	ds_read_b128 v[216:219], v172 offset:52224
	ds_read_b128 v[220:223], v172 offset:53248
	ds_read_b128 v[224:227], v172 offset:54272
	ds_read_b128 v[228:231], v172 offset:55296
	ds_read_b128 v[232:235], v172 offset:56320
	global_load_lds_dwordx4 v[156:157], off
	v_lshl_add_u64 v[156:157], v[184:185], 0, s[86:87]
	s_mov_b32 m0, s46
	s_nop 0
	global_load_lds_dwordx4 v[156:157], off
	s_waitcnt lgkmcnt(0)
	s_barrier
; #define PG8_STAGE(bufoff, gbase, voff) do { _Pragma("unroll") for (int _i = 0; _i < 2; ++_i) \
;     __builtin_amdgcn_global_load_lds((const unsigned*)((const char*)(gbase) + (voff)[_i]), (PG8_LAS unsigned*)(lds + (bufoff) + ldsw + _i * 8192), 16, 0, 0); } while (0)
; #define PG8_WAIT_V(n) asm volatile("s_waitcnt vmcnt(" #n ")" ::: "memory")
; template <class Epi, class Sched>
; __device__ __forceinline__ void gemm_phase(PG8_LAS unsigned char* lds, const int lda, const int ldb, const Sched& S, const Epi& E) {
;     ...
;       PG8_BAR; PG8_WAIT_L(0); PG8_MMA(1, 0, At, B0); PG8_BAR; PG8_SCHED;
;       PG8_STAGE(PG8_SB(1, 1), b3 + hstepB, voffB);
;       PG8_WAIT_V(6); PG8_BAR; PG8_MMA(1, 1, At, B1); PG8_BAR;
;     }
;   __device__ __forceinline__ void operator()(const f32x4 (&acc)[2][2][4][2], const Unit& u, int wr, int wc, int fr, int fq) const {
;     ...
;         const int r = u.pm * 256 + ai * 128 + wr * 64 + m * 16 + fr;
; #pragma unroll
;         for (int bj = 0; bj < 2; ++bj)
; #pragma unroll
;           for (int n = 0; n < 2; ++n) {
;             const f32x4 v = acc[ai][bj][m][n];
;             const int c = u.pn * 256 + bj * 128 + wc * 32 + n * 16 + 4 * fq;
;             if (u.pn < 7) {
;               uint2 w; w.x = pack2(v[0], v[1]); w.y = pack2(v[2], v[3]);
;               *reinterpret_cast<uint2*>(PB + (size_t)r * PBW + c) = w;
;             } else {
;               const int nn = c - 1792, part = nn >> 8, ch = nn & 255;
;               if (u.pn == 7 && bj == 0 && wc == 1 && n == 1) {
;                 *reinterpret_cast<float4*>(AB + (size_t)r * 16 + 4 * fq) = make_float4(v[0], v[1], v[2], v[3]);
;               } else {
;                 u16* d; int cstride;
;                 if (r < ML) { const int b = r >> 11, tt = r & 2047; d = FT + ((size_t)(b * 256)) * 4096 + part * 2048 + tt; cstride = 4096; }
;                 else { const int rc = r - ML, b = rc >> 8, tt = rc & 255; d = FTC + ((size_t)(b * 256)) * 512 + part * 256 + tt; cstride = 512; }
; #pragma unroll
;                 for (int e = 0; e < 4; ++e) d[(size_t)(ch + e) * cstride] = f2bf(v[e]);
;                 if (u.pn == 7 && bj == 0 && wc == 0) {
; #pragma unroll
;                   for (int e = 0; e < 4; ++e) {
;                     const int kc = n * 16 + 4 * fq + e;
;                     if (kc >= 1 && kc <= 16) d[(size_t)(64 - kc) * cstride] = f2bf(v[e]);
	s_setprio 1
	v_mfma_f32_16x16x32_bf16 v[62:65], v[144:147], v[204:207], v[62:65]
	v_mfma_f32_16x16x32_bf16 v[58:61], v[152:155], v[204:207], v[58:61]
	v_mfma_f32_16x16x32_bf16 v[46:49], v[144:147], v[212:215], v[46:49]
	v_mfma_f32_16x16x32_bf16 v[42:45], v[152:155], v[212:215], v[42:45]
	v_mfma_f32_16x16x32_bf16 v[30:33], v[144:147], v[220:223], v[30:33]
	v_mfma_f32_16x16x32_bf16 v[26:29], v[152:155], v[220:223], v[26:29]
	v_mfma_f32_16x16x32_bf16 v[14:17], v[144:147], v[228:231], v[14:17]
	v_mfma_f32_16x16x32_bf16 v[10:13], v[152:155], v[228:231], v[10:13]
	v_mfma_f32_16x16x32_bf16 v[62:65], v[148:151], v[208:211], v[62:65]
	v_mfma_f32_16x16x32_bf16 v[58:61], v[200:203], v[208:211], v[58:61]
	v_mfma_f32_16x16x32_bf16 v[46:49], v[148:151], v[216:219], v[46:49]
	v_mfma_f32_16x16x32_bf16 v[42:45], v[200:203], v[216:219], v[42:45]
	v_mfma_f32_16x16x32_bf16 v[30:33], v[148:151], v[224:227], v[30:33]
	v_mfma_f32_16x16x32_bf16 v[26:29], v[200:203], v[224:227], v[26:29]
	v_mfma_f32_16x16x32_bf16 v[14:17], v[148:151], v[232:235], v[14:17]
	v_mfma_f32_16x16x32_bf16 v[10:13], v[200:203], v[232:235], v[10:13]
	s_setprio 0
	s_barrier
	s_add_u32 s12, s12, 0x40080
	s_addc_u32 s13, s13, 0
	s_add_i32 s24, s24, s39
	v_lshl_add_u64 v[144:145], s[12:13], 0, v[134:135]
	s_mov_b32 m0, s24
	s_nop 0
	global_load_lds_dwordx4 v[144:145], off
	v_lshl_add_u64 v[144:145], s[12:13], 0, v[132:133]
	s_add_i32 m0, s24, 0x2000
	s_nop 0
	global_load_lds_dwordx4 v[144:145], off
	s_waitcnt vmcnt(6)
	s_barrier
	s_setprio 1
	v_mfma_f32_16x16x32_bf16 v[54:57], v[236:239], v[204:207], v[54:57]
	v_mfma_f32_16x16x32_bf16 v[50:53], v[244:247], v[204:207], v[50:53]
	v_mfma_f32_16x16x32_bf16 v[38:41], v[236:239], v[212:215], v[38:41]
	v_mfma_f32_16x16x32_bf16 v[34:37], v[244:247], v[212:215], v[34:37]
	v_mfma_f32_16x16x32_bf16 v[22:25], v[236:239], v[220:223], v[22:25]
	v_mfma_f32_16x16x32_bf16 v[18:21], v[244:247], v[220:223], v[18:21]
	v_mfma_f32_16x16x32_bf16 v[6:9], v[236:239], v[228:231], v[6:9]
	v_mfma_f32_16x16x32_bf16 v[2:5], v[244:247], v[228:231], v[2:5]
	v_mfma_f32_16x16x32_bf16 v[54:57], v[240:243], v[208:211], v[54:57]
	v_mfma_f32_16x16x32_bf16 v[50:53], v[248:251], v[208:211], v[50:53]
	v_mfma_f32_16x16x32_bf16 v[38:41], v[240:243], v[216:219], v[38:41]
	v_mfma_f32_16x16x32_bf16 v[34:37], v[248:251], v[216:219], v[34:37]
	v_mfma_f32_16x16x32_bf16 v[22:25], v[240:243], v[224:227], v[22:25]
	v_mfma_f32_16x16x32_bf16 v[18:21], v[248:251], v[224:227], v[18:21]
	v_mfma_f32_16x16x32_bf16 v[6:9], v[240:243], v[232:235], v[6:9]
	v_mfma_f32_16x16x32_bf16 v[2:5], v[248:251], v[232:235], v[2:5]
	s_setprio 0
	s_add_i32 s30, s30, 2
	s_add_u32 s10, s10, 0x100
	s_addc_u32 s11, s11, 0
	s_add_u32 s28, s28, 0x100
	s_addc_u32 s29, s29, 0
	s_cmp_gt_u32 s30, 13
	s_barrier
	s_cbranch_scc0 .LBB0_685
	s_lshl_b32 s17, s2, 8
	s_add_i32 s17, s17, s44
	v_or_b32_e32 v152, s17, v1
	s_mov_b32 s2, 0xffff
	v_cmp_lt_i32_e64 s[12:13], s2, v152
	s_and_b32 s2, s17, 0xffffff00
	s_add_i32 s2, s2, 0xffff0000
	s_lshl_b64 s[28:29], s[2:3], 10
	s_ashr_i32 s2, s17, 3
	s_and_b32 s10, s2, 0xffffff00
	s_ashr_i32 s11, s10, 31
	s_lshl_b64 s[26:27], s[10:11], 13
	s_lshl_b32 s24, s48, 8
	s_cmp_gt_i32 s48, 6
	s_cselect_b64 s[30:31], -1, 0
	v_bitop3_b32 v146, s17, v186, v1 bitop3:0xc8
	v_bitop3_b32 v148, s17, v187, v1 bitop3:0xc8
	s_mov_b64 s[10:11], -1
	s_and_b64 vcc, exec, s[30:31]
	s_cbranch_vccz .LBB0_696
	s_and_saveexec_b64 s[10:11], s[12:13]
	s_xor_b64 s[10:11], exec, s[10:11]
	s_add_u32 s34, s54, s28
	s_addc_u32 s35, s55, s29
	s_or_saveexec_b64 s[10:11], s[10:11]
	s_add_i32 s2, s24, 0xfffff900
	v_mov_b64_e32 v[144:145], 0x200
	v_mov_b32_e32 v150, s2
	v_mov_b64_e32 v[154:155], s[34:35]
	v_mov_b64_e32 v[156:157], v[146:147]
	s_xor_b64 exec, exec, s[10:11]
	s_add_u32 s34, s69, s26
	s_addc_u32 s35, s52, s27
	s_lshl_b32 s2, s2, 3
	v_mov_b64_e32 v[144:145], 0x1000
	v_mov_b32_e32 v150, s2
	v_mov_b64_e32 v[154:155], s[34:35]
	v_mov_b64_e32 v[156:157], v[148:149]
	s_or_b64 exec, exec, s[10:11]
	v_ashrrev_i32_e32 v151, 31, v150
	v_lshl_add_u64 v[150:151], v[150:151], 1, v[154:155]
	v_lshlrev_b32_e32 v154, 1, v156
	v_mov_b32_e32 v155, v0
	v_mul_u32_u24_e32 v145, v144, v136
	v_lshl_add_u64 v[150:151], v[150:151], 0, v[154:155]
	v_lshlrev_b32_e32 v154, 1, v145
	v_cvt_pk_bf16_f32 v149, v126, s0
	v_lshl_add_u64 v[154:155], v[150:151], 0, v[154:155]
	v_mul_u32_u24_e32 v147, v144, v166
	global_store_short v[154:155], v149, off
	v_lshlrev_b32_e32 v154, 1, v147
	v_mov_b32_e32 v155, v0
	v_cvt_pk_bf16_f32 v145, v127, s0
	v_lshl_add_u64 v[154:155], v[150:151], 0, v[154:155]
	v_mul_u32_u24_e32 v153, v144, v167
	global_store_short v[154:155], v145, off
	v_lshlrev_b32_e32 v154, 1, v153
	v_mov_b32_e32 v155, v0
	s_cmp_lg_u32 s48, 7
	v_cvt_pk_bf16_f32 v147, v128, s0
	v_lshl_add_u64 v[154:155], v[150:151], 0, v[154:155]
	s_cselect_b64 s[10:11], -1, 0
	global_store_short v[154:155], v147, off
	v_mul_u32_u24_e32 v154, v144, v168
	s_xor_b64 s[34:35], s[14:15], -1
	v_lshlrev_b32_e32 v154, 1, v154
	v_mov_b32_e32 v155, v0
	s_or_b64 s[10:11], s[34:35], s[10:11]
	v_cvt_pk_bf16_f32 v153, v129, s0
	v_lshl_add_u64 v[154:155], v[150:151], 0, v[154:155]
	s_and_b64 vcc, exec, s[10:11]
	global_store_short v[154:155], v153, off
	s_cbranch_vccnz .LBB0_695
	s_and_saveexec_b64 s[10:11], s[4:5]
	s_cbranch_execz .LBB0_694
	v_mul_u32_u24_e32 v154, v144, v158
	v_lshlrev_b32_e32 v154, 1, v154
	v_mov_b32_e32 v155, v0
	v_lshl_add_u64 v[154:155], v[150:151], 0, v[154:155]
	global_store_short v[154:155], v149, off

; #define PG8_STAGE(bufoff, gbase, voff) do { _Pragma("unroll") for (int _i = 0; _i < 2; ++_i) \
;     __builtin_amdgcn_global_load_lds((const unsigned*)((const char*)(gbase) + (voff)[_i]), (PG8_LAS unsigned*)(lds + (bufoff) + ldsw + _i * 8192), 16, 0, 0); } while (0)
; #define PG8_LDA(dst, b, h) do { _Pragma("unroll") for (int m = 0; m < 4; ++m) _Pragma("unroll") for (int k = 0; k < 2; ++k) dst[m][k] = *(const PG8_LAS bf16x8*)(lds + PG8_SA(b, h) + aoff + m * 2048 + k * 1024); } while (0)
; #define PG8_LDB(dst, b, h) do { _Pragma("unroll") for (int n = 0; n < 2; ++n) _Pragma("unroll") for (int k = 0; k < 2; ++k) dst[n][k] = *(const PG8_LAS bf16x8*)(lds + PG8_SB(b, h) + boff + n * 2048 + k * 1024); } while (0)
; #define PG8_MMA(ai, bj, At, Bt) do { __builtin_amdgcn_s_setprio(1); _Pragma("unroll") for (int m = 0; m < 4; ++m) _Pragma("unroll") for (int n = 0; n < 2; ++n) _Pragma("unroll") for (int k = 0; k < 2; ++k) \
;     acc[ai][bj][m][n] = __builtin_amdgcn_mfma_f32_16x16x32_bf16(Bt[n][k], At[m][k], acc[ai][bj][m][n], 0, 0, 0); __builtin_amdgcn_s_setprio(0); } while (0)
; #define PG8_WAIT_L(n) asm volatile("s_waitcnt lgkmcnt(" #n ")" ::: "memory")
; #define PG8_BAR __builtin_amdgcn_s_barrier()
; #define PG8_SCHED __builtin_amdgcn_sched_barrier(0)
; template <class Epi, class Sched>
; __device__ __forceinline__ void gemm_phase(PG8_LAS unsigned char* lds, const int lda, const int ldb, const Sched& S, const Epi& E) {
;     ...
;     for (int t = 0; t < nt; t += 2) {
;       const bool last = (t == nt - 2);
;       const char* a1 = cA + (size_t)(t + 1) * kstep;
;       const char* a2 = last ? nA : cA + (size_t)(t + 2) * kstep; const char* b2 = last ? nB : cB + (size_t)(t + 2) * kstep;
;       const char* a3 = a2 + kstep; const char* b3 = b2 + kstep;
;       PG8_LDB(B0, 0, 0); PG8_SCHED; PG8_LDA(At, 0, 0); PG8_STAGE(PG8_SA(1, 1), a1 + hstepA, voffA);
;       PG8_WAIT_L(8); PG8_BAR; PG8_WAIT_L(0); PG8_MMA(0, 0, At, B0); PG8_BAR; PG8_SCHED;
;       PG8_LDB(B1, 0, 1); PG8_STAGE(PG8_SB(0, 0), b2, voffB);
;       PG8_BAR; PG8_WAIT_L(0); PG8_MMA(0, 1, At, B1); PG8_BAR;
;       PG8_LDA(At, 0, 1); PG8_STAGE(PG8_SA(0, 0), a2, voffA);
;       PG8_BAR; PG8_WAIT_L(0); PG8_MMA(1, 0, At, B0); PG8_BAR; PG8_SCHED;
.LBB0_1088:
	s_add_u32 s16, s14, 0xfff00080
	s_addc_u32 s17, s15, -1
	s_add_i32 s33, 0, 0x10000
	v_add_u32_e32 v145, s33, v1
	ds_read_b128 v[152:155], v145
	ds_read_b128 v[156:159], v145 offset:1024
	ds_read_b128 v[160:163], v145 offset:2048
	ds_read_b128 v[164:167], v145 offset:3072
	s_cmp_eq_u32 s34, 60
	s_cselect_b32 s19, s7, s17
	s_cselect_b32 s18, s13, s16
	s_cselect_b32 s17, s1, s31
	s_cselect_b32 s16, s29, s30
	v_lshl_add_u64 v[182:183], s[14:15], 0, v[140:141]
	s_add_i32 m0, s21, 0xc000
	ds_read_b128 v[168:171], v131
	ds_read_b128 v[172:175], v131 offset:1024
	ds_read_b128 v[200:203], v131 offset:2048
	ds_read_b128 v[204:207], v131 offset:3072
	ds_read_b128 v[208:211], v131 offset:4096
	ds_read_b128 v[212:215], v131 offset:5120
	ds_read_b128 v[216:219], v131 offset:6144
	ds_read_b128 v[220:223], v131 offset:7168
	global_load_lds_dwordx4 v[182:183], off
	v_lshl_add_u64 v[182:183], s[14:15], 0, v[142:143]
	s_add_i32 m0, s21, 0xe000
	s_nop 0
	global_load_lds_dwordx4 v[182:183], off
	s_waitcnt lgkmcnt(8)
	s_barrier
	s_waitcnt lgkmcnt(0)
	s_setprio 1
	v_mfma_f32_16x16x32_bf16 v[126:129], v[152:155], v[168:171], v[126:129]
	v_mfma_f32_16x16x32_bf16 v[122:125], v[160:163], v[168:171], v[122:125]
	v_mfma_f32_16x16x32_bf16 v[118:121], v[152:155], v[200:203], v[118:121]
	v_mfma_f32_16x16x32_bf16 v[114:117], v[160:163], v[200:203], v[114:117]
	v_mfma_f32_16x16x32_bf16 v[102:105], v[152:155], v[208:211], v[102:105]
	v_mfma_f32_16x16x32_bf16 v[98:101], v[160:163], v[208:211], v[98:101]
	v_mfma_f32_16x16x32_bf16 v[86:89], v[152:155], v[216:219], v[86:89]
	v_mfma_f32_16x16x32_bf16 v[82:85], v[160:163], v[216:219], v[82:85]
	v_mfma_f32_16x16x32_bf16 v[126:129], v[156:159], v[172:175], v[126:129]
	v_mfma_f32_16x16x32_bf16 v[122:125], v[164:167], v[172:175], v[122:125]
	v_mfma_f32_16x16x32_bf16 v[118:121], v[156:159], v[204:207], v[118:121]
	v_mfma_f32_16x16x32_bf16 v[114:117], v[164:167], v[204:207], v[114:117]
	v_mfma_f32_16x16x32_bf16 v[102:105], v[156:159], v[212:215], v[102:105]
	v_mfma_f32_16x16x32_bf16 v[98:101], v[164:167], v[212:215], v[98:101]
	v_mfma_f32_16x16x32_bf16 v[86:89], v[156:159], v[220:223], v[86:89]
	v_mfma_f32_16x16x32_bf16 v[82:85], v[164:167], v[220:223], v[82:85]
	s_setprio 0
	s_barrier
	s_add_i32 s35, 0, 0x14000
	s_add_i32 s33, s33, s20
	v_add_u32_e32 v145, s35, v1
	v_lshl_add_u64 v[182:183], s[16:17], 0, v[134:135]
	s_mov_b32 m0, s33
	ds_read_b128 v[224:227], v145
	ds_read_b128 v[228:231], v145 offset:1024
	ds_read_b128 v[232:235], v145 offset:2048
	ds_read_b128 v[236:239], v145 offset:3072
	global_load_lds_dwordx4 v[182:183], off
	v_lshl_add_u64 v[184:185], s[16:17], 0, v[132:133]
	s_add_i32 m0, s33, 0x2000
	s_nop 0
	global_load_lds_dwordx4 v[184:185], off
	s_waitcnt lgkmcnt(0)
	s_barrier
	s_setprio 1
	v_mfma_f32_16x16x32_bf16 v[110:113], v[224:227], v[168:171], v[110:113]
	v_mfma_f32_16x16x32_bf16 v[106:109], v[232:235], v[168:171], v[106:109]
	v_mfma_f32_16x16x32_bf16 v[94:97], v[224:227], v[200:203], v[94:97]
	v_mfma_f32_16x16x32_bf16 v[90:93], v[232:235], v[200:203], v[90:93]
	v_mfma_f32_16x16x32_bf16 v[78:81], v[224:227], v[208:211], v[78:81]
	v_mfma_f32_16x16x32_bf16 v[74:77], v[232:235], v[208:211], v[74:77]
	v_mfma_f32_16x16x32_bf16 v[70:73], v[224:227], v[216:219], v[70:73]
	v_mfma_f32_16x16x32_bf16 v[66:69], v[232:235], v[216:219], v[66:69]
	v_mfma_f32_16x16x32_bf16 v[110:113], v[228:231], v[172:175], v[110:113]
	v_mfma_f32_16x16x32_bf16 v[106:109], v[236:239], v[172:175], v[106:109]
	v_mfma_f32_16x16x32_bf16 v[94:97], v[228:231], v[204:207], v[94:97]
	v_mfma_f32_16x16x32_bf16 v[90:93], v[236:239], v[204:207], v[90:93]
	v_mfma_f32_16x16x32_bf16 v[78:81], v[228:231], v[212:215], v[78:81]
	v_mfma_f32_16x16x32_bf16 v[74:77], v[236:239], v[212:215], v[74:77]
	v_mfma_f32_16x16x32_bf16 v[70:73], v[228:231], v[220:223], v[70:73]
	v_mfma_f32_16x16x32_bf16 v[66:69], v[236:239], v[220:223], v[66:69]
	s_setprio 0
	s_mov_b32 m0, s21
	v_lshl_add_u64 v[240:241], s[18:19], 0, v[134:135]
	s_barrier
	ds_read_b128 v[168:171], v131 offset:16384
	ds_read_b128 v[172:175], v131 offset:17408
	ds_read_b128 v[200:203], v131 offset:18432
	ds_read_b128 v[204:207], v131 offset:19456
	ds_read_b128 v[208:211], v131 offset:20480
	ds_read_b128 v[212:215], v131 offset:21504
	ds_read_b128 v[216:219], v131 offset:22528
	ds_read_b128 v[220:223], v131 offset:23552
	global_load_lds_dwordx4 v[240:241], off
	v_lshl_add_u64 v[242:243], s[18:19], 0, v[132:133]
	s_mov_b32 m0, s22
	s_nop 0
	global_load_lds_dwordx4 v[242:243], off
	s_waitcnt lgkmcnt(0)
	s_barrier
	s_setprio 1
	v_mfma_f32_16x16x32_bf16 v[62:65], v[152:155], v[168:171], v[62:65]
	v_mfma_f32_16x16x32_bf16 v[58:61], v[160:163], v[168:171], v[58:61]
	v_mfma_f32_16x16x32_bf16 v[54:57], v[152:155], v[200:203], v[54:57]
	v_mfma_f32_16x16x32_bf16 v[46:49], v[160:163], v[200:203], v[46:49]
	v_mfma_f32_16x16x32_bf16 v[38:41], v[152:155], v[208:211], v[38:41]
	v_mfma_f32_16x16x32_bf16 v[34:37], v[160:163], v[208:211], v[34:37]
	v_mfma_f32_16x16x32_bf16 v[22:25], v[152:155], v[216:219], v[22:25]
	v_mfma_f32_16x16x32_bf16 v[18:21], v[160:163], v[216:219], v[18:21]
	v_mfma_f32_16x16x32_bf16 v[62:65], v[156:159], v[172:175], v[62:65]
	v_mfma_f32_16x16x32_bf16 v[58:61], v[164:167], v[172:175], v[58:61]
	v_mfma_f32_16x16x32_bf16 v[54:57], v[156:159], v[204:207], v[54:57]
	v_mfma_f32_16x16x32_bf16 v[46:49], v[164:167], v[204:207], v[46:49]
	v_mfma_f32_16x16x32_bf16 v[38:41], v[156:159], v[212:215], v[38:41]
	v_mfma_f32_16x16x32_bf16 v[34:37], v[164:167], v[212:215], v[34:37]
	v_mfma_f32_16x16x32_bf16 v[22:25], v[156:159], v[220:223], v[22:25]
	v_mfma_f32_16x16x32_bf16 v[18:21], v[164:167], v[220:223], v[18:21]
	s_setprio 0
	s_barrier
; #define PG8_STAGE(bufoff, gbase, voff) do { _Pragma("unroll") for (int _i = 0; _i < 2; ++_i) \
;     __builtin_amdgcn_global_load_lds((const unsigned*)((const char*)(gbase) + (voff)[_i]), (PG8_LAS unsigned*)(lds + (bufoff) + ldsw + _i * 8192), 16, 0, 0); } while (0)
; #define PG8_LDA(dst, b, h) do { _Pragma("unroll") for (int m = 0; m < 4; ++m) _Pragma("unroll") for (int k = 0; k < 2; ++k) dst[m][k] = *(const PG8_LAS bf16x8*)(lds + PG8_SA(b, h) + aoff + m * 2048 + k * 1024); } while (0)
; #define PG8_LDB(dst, b, h) do { _Pragma("unroll") for (int n = 0; n < 2; ++n) _Pragma("unroll") for (int k = 0; k < 2; ++k) dst[n][k] = *(const PG8_LAS bf16x8*)(lds + PG8_SB(b, h) + boff + n * 2048 + k * 1024); } while (0)
; #define PG8_MMA(ai, bj, At, Bt) do { __builtin_amdgcn_s_setprio(1); _Pragma("unroll") for (int m = 0; m < 4; ++m) _Pragma("unroll") for (int n = 0; n < 2; ++n) _Pragma("unroll") for (int k = 0; k < 2; ++k) \
;     acc[ai][bj][m][n] = __builtin_amdgcn_mfma_f32_16x16x32_bf16(Bt[n][k], At[m][k], acc[ai][bj][m][n], 0, 0, 0); __builtin_amdgcn_s_setprio(0); } while (0)
; #define PG8_WAIT_V(n) asm volatile("s_waitcnt vmcnt(" #n ")" ::: "memory")
; #define PG8_WAIT_L(n) asm volatile("s_waitcnt lgkmcnt(" #n ")" ::: "memory")
; #define PG8_BAR __builtin_amdgcn_s_barrier()
; #define PG8_SCHED __builtin_amdgcn_sched_barrier(0)
; template <class Epi, class Sched>
; __device__ __forceinline__ void gemm_phase(PG8_LAS unsigned char* lds, const int lda, const int ldb, const Sched& S, const Epi& E) {
;     ...
;       PG8_STAGE(PG8_SB(0, 1), b2 + hstepB, voffB);
;       PG8_WAIT_V(6); PG8_BAR; PG8_MMA(1, 1, At, B1); PG8_BAR;
;       PG8_LDB(B0, 1, 0); PG8_SCHED; PG8_LDA(At, 1, 0); PG8_STAGE(PG8_SA(0, 1), a2 + hstepA, voffA);
;       PG8_WAIT_L(8); PG8_BAR; PG8_WAIT_L(0); PG8_MMA(0, 0, At, B0); PG8_BAR; PG8_SCHED;
;       PG8_LDB(B1, 1, 1); PG8_STAGE(PG8_SB(1, 0), b3, voffB);
;       PG8_BAR; PG8_WAIT_L(0); PG8_MMA(0, 1, At, B1); PG8_BAR;
;       PG8_LDA(At, 1, 1); PG8_STAGE(PG8_SA(1, 0), a3, voffA);
;       PG8_BAR; PG8_WAIT_L(0); PG8_MMA(1, 0, At, B0); PG8_BAR; PG8_SCHED;
	s_add_u32 s36, s16, 0x100000
	s_addc_u32 s37, s17, 0
	s_add_i32 s33, s35, s20
	v_lshl_add_u64 v[152:153], s[36:37], 0, v[134:135]
	s_mov_b32 m0, s33
	s_nop 0
	global_load_lds_dwordx4 v[152:153], off
	v_lshl_add_u64 v[152:153], s[36:37], 0, v[132:133]
	s_add_i32 m0, s33, 0x2000
	s_nop 0
	global_load_lds_dwordx4 v[152:153], off
	s_waitcnt vmcnt(6)
	s_barrier
	s_setprio 1
	v_mfma_f32_16x16x32_bf16 v[50:53], v[224:227], v[168:171], v[50:53]
	v_mfma_f32_16x16x32_bf16 v[42:45], v[232:235], v[168:171], v[42:45]
	v_mfma_f32_16x16x32_bf16 v[30:33], v[224:227], v[200:203], v[30:33]
	v_mfma_f32_16x16x32_bf16 v[26:29], v[232:235], v[200:203], v[26:29]
	v_mfma_f32_16x16x32_bf16 v[14:17], v[224:227], v[208:211], v[14:17]
	v_mfma_f32_16x16x32_bf16 v[10:13], v[232:235], v[208:211], v[10:13]
	v_mfma_f32_16x16x32_bf16 v[6:9], v[224:227], v[216:219], v[6:9]
	v_mfma_f32_16x16x32_bf16 v[2:5], v[232:235], v[216:219], v[2:5]
	v_mfma_f32_16x16x32_bf16 v[50:53], v[228:231], v[172:175], v[50:53]
	v_mfma_f32_16x16x32_bf16 v[42:45], v[236:239], v[172:175], v[42:45]
	v_mfma_f32_16x16x32_bf16 v[30:33], v[228:231], v[204:207], v[30:33]
	v_mfma_f32_16x16x32_bf16 v[26:29], v[236:239], v[204:207], v[26:29]
	v_mfma_f32_16x16x32_bf16 v[14:17], v[228:231], v[212:215], v[14:17]
	v_mfma_f32_16x16x32_bf16 v[10:13], v[236:239], v[212:215], v[10:13]
	v_mfma_f32_16x16x32_bf16 v[6:9], v[228:231], v[220:223], v[6:9]
	v_mfma_f32_16x16x32_bf16 v[2:5], v[236:239], v[220:223], v[2:5]
	s_setprio 0
	s_add_i32 s33, 0, 0x18000
	v_add_u32_e32 v145, s33, v1
	s_barrier
	ds_read_b128 v[152:155], v145
	ds_read_b128 v[156:159], v145 offset:1024
	ds_read_b128 v[160:163], v145 offset:2048
	ds_read_b128 v[164:167], v145 offset:3072
	s_add_u32 s18, s18, 0x100000
	s_addc_u32 s19, s19, 0
	s_mov_b32 m0, s23
	v_lshl_add_u64 v[224:225], s[18:19], 0, v[134:135]
	ds_read_b128 v[168:171], v131 offset:32768
	ds_read_b128 v[172:175], v131 offset:33792
	ds_read_b128 v[200:203], v131 offset:34816
	ds_read_b128 v[204:207], v131 offset:35840
	ds_read_b128 v[208:211], v131 offset:36864
	ds_read_b128 v[212:215], v131 offset:37888
	ds_read_b128 v[216:219], v131 offset:38912
	ds_read_b128 v[220:223], v131 offset:39936
	global_load_lds_dwordx4 v[224:225], off
	v_lshl_add_u64 v[224:225], s[18:19], 0, v[132:133]
	s_mov_b32 m0, s24
	s_nop 0
	global_load_lds_dwordx4 v[224:225], off
	s_waitcnt lgkmcnt(8)
	s_barrier
	s_waitcnt lgkmcnt(0)
	s_setprio 1
	v_mfma_f32_16x16x32_bf16 v[126:129], v[152:155], v[168:171], v[126:129]
	v_mfma_f32_16x16x32_bf16 v[122:125], v[160:163], v[168:171], v[122:125]
	v_mfma_f32_16x16x32_bf16 v[118:121], v[152:155], v[200:203], v[118:121]
	v_mfma_f32_16x16x32_bf16 v[114:117], v[160:163], v[200:203], v[114:117]
	v_mfma_f32_16x16x32_bf16 v[102:105], v[152:155], v[208:211], v[102:105]
	v_mfma_f32_16x16x32_bf16 v[98:101], v[160:163], v[208:211], v[98:101]
	v_mfma_f32_16x16x32_bf16 v[86:89], v[152:155], v[216:219], v[86:89]
	v_mfma_f32_16x16x32_bf16 v[82:85], v[160:163], v[216:219], v[82:85]
	v_mfma_f32_16x16x32_bf16 v[126:129], v[156:159], v[172:175], v[126:129]
	v_mfma_f32_16x16x32_bf16 v[122:125], v[164:167], v[172:175], v[122:125]
	v_mfma_f32_16x16x32_bf16 v[118:121], v[156:159], v[204:207], v[118:121]
	v_mfma_f32_16x16x32_bf16 v[114:117], v[164:167], v[204:207], v[114:117]
	v_mfma_f32_16x16x32_bf16 v[102:105], v[156:159], v[212:215], v[102:105]
	v_mfma_f32_16x16x32_bf16 v[98:101], v[164:167], v[212:215], v[98:101]
	v_mfma_f32_16x16x32_bf16 v[86:89], v[156:159], v[220:223], v[86:89]
	v_mfma_f32_16x16x32_bf16 v[82:85], v[164:167], v[220:223], v[82:85]
	s_setprio 0
	s_barrier
	s_add_i32 s18, 0, 0x1c000
	s_add_i32 s19, s33, s20
	v_add_u32_e32 v145, s18, v1
	v_lshl_add_u64 v[182:183], v[182:183], 0, s[86:87]
	s_mov_b32 m0, s19
	ds_read_b128 v[224:227], v145
	ds_read_b128 v[228:231], v145 offset:1024
	ds_read_b128 v[232:235], v145 offset:2048
	ds_read_b128 v[236:239], v145 offset:3072
	global_load_lds_dwordx4 v[182:183], off
	v_lshl_add_u64 v[182:183], v[184:185], 0, s[86:87]
	s_add_i32 m0, s19, 0x2000
	s_nop 0
	global_load_lds_dwordx4 v[182:183], off
	s_waitcnt lgkmcnt(0)
	s_barrier
	s_setprio 1
	v_mfma_f32_16x16x32_bf16 v[110:113], v[224:227], v[168:171], v[110:113]
	v_mfma_f32_16x16x32_bf16 v[106:109], v[232:235], v[168:171], v[106:109]
	v_mfma_f32_16x16x32_bf16 v[94:97], v[224:227], v[200:203], v[94:97]
	v_mfma_f32_16x16x32_bf16 v[90:93], v[232:235], v[200:203], v[90:93]
	v_mfma_f32_16x16x32_bf16 v[78:81], v[224:227], v[208:211], v[78:81]
	v_mfma_f32_16x16x32_bf16 v[74:77], v[232:235], v[208:211], v[74:77]
	v_mfma_f32_16x16x32_bf16 v[70:73], v[224:227], v[216:219], v[70:73]
	v_mfma_f32_16x16x32_bf16 v[66:69], v[232:235], v[216:219], v[66:69]
	v_mfma_f32_16x16x32_bf16 v[110:113], v[228:231], v[172:175], v[110:113]
	v_mfma_f32_16x16x32_bf16 v[106:109], v[236:239], v[172:175], v[106:109]
	v_mfma_f32_16x16x32_bf16 v[94:97], v[228:231], v[204:207], v[94:97]
	v_mfma_f32_16x16x32_bf16 v[90:93], v[236:239], v[204:207], v[90:93]
	v_mfma_f32_16x16x32_bf16 v[78:81], v[228:231], v[212:215], v[78:81]
	v_mfma_f32_16x16x32_bf16 v[74:77], v[236:239], v[212:215], v[74:77]
	v_mfma_f32_16x16x32_bf16 v[70:73], v[228:231], v[220:223], v[70:73]
	v_mfma_f32_16x16x32_bf16 v[66:69], v[236:239], v[220:223], v[66:69]
	s_setprio 0
	s_mov_b32 m0, s25
	v_lshl_add_u64 v[182:183], v[240:241], 0, s[86:87]
	s_barrier
	ds_read_b128 v[168:171], v131 offset:49152
	ds_read_b128 v[172:175], v131 offset:50176
	ds_read_b128 v[200:203], v131 offset:51200
	ds_read_b128 v[204:207], v131 offset:52224
	ds_read_b128 v[208:211], v131 offset:53248
	ds_read_b128 v[212:215], v131 offset:54272
	ds_read_b128 v[216:219], v131 offset:55296
	ds_read_b128 v[220:223], v131 offset:56320
	global_load_lds_dwordx4 v[182:183], off
	v_lshl_add_u64 v[182:183], v[242:243], 0, s[86:87]
	s_mov_b32 m0, s26
	s_nop 0
	global_load_lds_dwordx4 v[182:183], off
	s_waitcnt lgkmcnt(0)
	s_barrier
; #define PG8_STAGE(bufoff, gbase, voff) do { _Pragma("unroll") for (int _i = 0; _i < 2; ++_i) \
;     __builtin_amdgcn_global_load_lds((const unsigned*)((const char*)(gbase) + (voff)[_i]), (PG8_LAS unsigned*)(lds + (bufoff) + ldsw + _i * 8192), 16, 0, 0); } while (0)
; #define PG8_MMA(ai, bj, At, Bt) do { __builtin_amdgcn_s_setprio(1); _Pragma("unroll") for (int m = 0; m < 4; ++m) _Pragma("unroll") for (int n = 0; n < 2; ++n) _Pragma("unroll") for (int k = 0; k < 2; ++k) \
;     acc[ai][bj][m][n] = __builtin_amdgcn_mfma_f32_16x16x32_bf16(Bt[n][k], At[m][k], acc[ai][bj][m][n], 0, 0, 0); __builtin_amdgcn_s_setprio(0); } while (0)
; #define PG8_WAIT_V(n) asm volatile("s_waitcnt vmcnt(" #n ")" ::: "memory")
; #define PG8_WAIT_L(n) asm volatile("s_waitcnt lgkmcnt(" #n ")" ::: "memory")
; #define PG8_BAR __builtin_amdgcn_s_barrier()
; #define PG8_SCHED __builtin_amdgcn_sched_barrier(0)
; template <class Epi, class Sched>
; __device__ __forceinline__ void gemm_phase(PG8_LAS unsigned char* lds, const int lda, const int ldb, const Sched& S, const Epi& E) {
;     ...
;       PG8_BAR; PG8_WAIT_L(0); PG8_MMA(1, 0, At, B0); PG8_BAR; PG8_SCHED;
;       PG8_STAGE(PG8_SB(1, 1), b3 + hstepB, voffB);
;       PG8_WAIT_V(6); PG8_BAR; PG8_MMA(1, 1, At, B1); PG8_BAR;
;     }
	s_setprio 1
	v_mfma_f32_16x16x32_bf16 v[62:65], v[152:155], v[168:171], v[62:65]
	v_mfma_f32_16x16x32_bf16 v[58:61], v[160:163], v[168:171], v[58:61]
	v_mfma_f32_16x16x32_bf16 v[54:57], v[152:155], v[200:203], v[54:57]
	v_mfma_f32_16x16x32_bf16 v[46:49], v[160:163], v[200:203], v[46:49]
	v_mfma_f32_16x16x32_bf16 v[38:41], v[152:155], v[208:211], v[38:41]
	v_mfma_f32_16x16x32_bf16 v[34:37], v[160:163], v[208:211], v[34:37]
	v_mfma_f32_16x16x32_bf16 v[22:25], v[152:155], v[216:219], v[22:25]
	v_mfma_f32_16x16x32_bf16 v[18:21], v[160:163], v[216:219], v[18:21]
	v_mfma_f32_16x16x32_bf16 v[62:65], v[156:159], v[172:175], v[62:65]
	v_mfma_f32_16x16x32_bf16 v[58:61], v[164:167], v[172:175], v[58:61]
	v_mfma_f32_16x16x32_bf16 v[54:57], v[156:159], v[204:207], v[54:57]
	v_mfma_f32_16x16x32_bf16 v[46:49], v[164:167], v[204:207], v[46:49]
	v_mfma_f32_16x16x32_bf16 v[38:41], v[156:159], v[212:215], v[38:41]
	v_mfma_f32_16x16x32_bf16 v[34:37], v[164:167], v[212:215], v[34:37]
	v_mfma_f32_16x16x32_bf16 v[22:25], v[156:159], v[220:223], v[22:25]
	v_mfma_f32_16x16x32_bf16 v[18:21], v[164:167], v[220:223], v[18:21]
	s_setprio 0
	s_barrier
	s_add_u32 s16, s16, 0x100080
	s_addc_u32 s17, s17, 0
	s_add_i32 s18, s18, s20
	v_lshl_add_u64 v[152:153], s[16:17], 0, v[134:135]
	s_mov_b32 m0, s18
	s_nop 0
	global_load_lds_dwordx4 v[152:153], off
	v_lshl_add_u64 v[152:153], s[16:17], 0, v[132:133]
	s_add_i32 m0, s18, 0x2000
	s_nop 0
	global_load_lds_dwordx4 v[152:153], off
	s_waitcnt vmcnt(6)
	s_barrier
	s_setprio 1
	v_mfma_f32_16x16x32_bf16 v[50:53], v[224:227], v[168:171], v[50:53]
	v_mfma_f32_16x16x32_bf16 v[42:45], v[232:235], v[168:171], v[42:45]
	v_mfma_f32_16x16x32_bf16 v[30:33], v[224:227], v[200:203], v[30:33]
	v_mfma_f32_16x16x32_bf16 v[26:29], v[232:235], v[200:203], v[26:29]
	v_mfma_f32_16x16x32_bf16 v[14:17], v[224:227], v[208:211], v[14:17]
	v_mfma_f32_16x16x32_bf16 v[10:13], v[232:235], v[208:211], v[10:13]
	v_mfma_f32_16x16x32_bf16 v[6:9], v[224:227], v[216:219], v[6:9]
	v_mfma_f32_16x16x32_bf16 v[2:5], v[232:235], v[216:219], v[2:5]
	v_mfma_f32_16x16x32_bf16 v[50:53], v[228:231], v[172:175], v[50:53]
	v_mfma_f32_16x16x32_bf16 v[42:45], v[236:239], v[172:175], v[42:45]
	v_mfma_f32_16x16x32_bf16 v[30:33], v[228:231], v[204:207], v[30:33]
	v_mfma_f32_16x16x32_bf16 v[26:29], v[236:239], v[204:207], v[26:29]
	v_mfma_f32_16x16x32_bf16 v[14:17], v[228:231], v[212:215], v[14:17]
	v_mfma_f32_16x16x32_bf16 v[10:13], v[236:239], v[212:215], v[10:13]
	v_mfma_f32_16x16x32_bf16 v[6:9], v[228:231], v[220:223], v[6:9]
	v_mfma_f32_16x16x32_bf16 v[2:5], v[236:239], v[220:223], v[2:5]
	s_setprio 0
	s_add_i32 s34, s34, 2
	s_add_u32 s14, s14, 0x100
	s_addc_u32 s15, s15, 0
	s_add_u32 s30, s30, 0x100
	s_addc_u32 s31, s31, 0
	s_cmp_gt_u32 s34, 61
	s_barrier
	s_cbranch_scc0 .LBB0_1088
;   __device__ __forceinline__ int kt(const Unit& u) const { return ((u.pn & 7) < 4) ? 4 : 16; }
; template <class Epi, class Sched>
; __device__ __forceinline__ void gemm_phase(PG8_LAS unsigned char* lds, const int lda, const int ldb, const Sched& S, const Epi& E) {
;     ...
;     E(acc, cur, wr, wc, fr, fq);
;     if (!has_next) break;
; #pragma unroll
;     for (int a = 0; a < 2; ++a)
; #pragma unroll
;       for (int b = 0; b < 2; ++b)
; #pragma unroll
;         for (int m = 0; m < 4; ++m)
; #pragma unroll
;           for (int n = 0; n < 2; ++n) acc[a][b][m][n] = (f32x4){0.f, 0.f, 0.f, 0.f};
;     cur = nxt; cA = nA; cB = nB; ++ui;
;     nt = S.kt(cur);
;   __device__ __forceinline__ void operator()(const f32x4 (&acc)[2][2][4][2], const Unit& u, int wr, int wc, int fr, int fq) const {
;     ...
;     for (int ai = 0; ai < 2; ++ai)
; #pragma unroll
;       for (int m = 0; m < 4; ++m) {
;         const size_t r = (size_t)rowbase + (size_t)u.pn * rows_per_b + u.pm * 256 + ai * 128 + wr * 64 + m * 16 + fr;
; #pragma unroll
;         for (int bj = 0; bj < 2; ++bj)
; #pragma unroll
;           for (int n = 0; n < 2; ++n) {
;             const f32x4 v = acc[ai][bj][m][n];
;             const int c = 256 + bj * 128 + wc * 32 + n * 16 + 4 * fq;
;             uint2 w; w.x = pack2(v[0], v[1]); w.y = pack2(v[2], v[3]);
;             *reinterpret_cast<uint2*>(Y + r * 1024 + c) = w;
;           }
	s_lshl_b32 s14, s28, 8
	s_ashr_i32 s15, s14, 31
	s_ashr_i32 s13, s12, 31
	v_lshl_add_u64 v[152:153], v[136:137], 0, s[14:15]
	s_lshl_b64 s[12:13], s[12:13], 22
	v_lshlrev_b64 v[152:153], 11, v[152:153]
	v_lshl_add_u64 v[152:153], v[152:153], 0, s[12:13]
	v_readlane_b32 s12, v253, 54
	v_readlane_b32 s13, v253, 55
	v_mov_b32_e32 v145, v0
	v_cvt_pk_bf16_f32 v109, v108, v109
	v_lshl_add_u64 v[154:155], s[12:13], 0, v[152:153]
	v_lshl_add_u64 v[156:157], v[154:155], 0, v[144:145]
	v_cvt_pk_bf16_f32 v108, v106, v107
	v_or_b32_e32 v106, 0x8000, v152
	v_mov_b32_e32 v107, v153
	s_mov_b64 s[12:13], 0x40000
	v_cvt_pk_bf16_f32 v129, v128, v129
	v_cvt_pk_bf16_f32 v128, v126, v127
	v_cvt_pk_bf16_f32 v125, v124, v125
	v_cvt_pk_bf16_f32 v124, v122, v123
	v_cvt_pk_bf16_f32 v113, v112, v113
	v_cvt_pk_bf16_f32 v112, v110, v111
	global_store_dwordx2 v[156:157], v[108:109], off offset:800
	v_lshl_add_u64 v[106:107], v[138:139], 0, v[106:107]
	v_cvt_pk_bf16_f32 v109, v120, v121
	v_cvt_pk_bf16_f32 v108, v118, v119
	v_cvt_pk_bf16_f32 v93, v92, v93
	v_cvt_pk_bf16_f32 v92, v90, v91
	v_or_b32_e32 v90, 0x10000, v152
	v_mov_b32_e32 v91, v153
	v_cvt_pk_bf16_f32 v69, v68, v69
	v_cvt_pk_bf16_f32 v68, v66, v67
	v_lshl_add_u64 v[66:67], v[154:155], 0, s[12:13]
	s_mov_b64 s[12:13], 0x48000
	global_store_dwordx2 v[156:157], v[128:129], off offset:512
	global_store_dwordx2 v[156:157], v[124:125], off offset:544
	global_store_dwordx2 v[156:157], v[112:113], off offset:768
	global_store_dwordx2 v[106:107], v[108:109], off offset:512
	v_cvt_pk_bf16_f32 v109, v116, v117
	v_cvt_pk_bf16_f32 v108, v114, v115
	v_cvt_pk_bf16_f32 v97, v96, v97
	v_cvt_pk_bf16_f32 v96, v94, v95
	global_store_dwordx2 v[106:107], v[92:93], off offset:800
	v_lshl_add_u64 v[90:91], v[138:139], 0, v[90:91]
	v_cvt_pk_bf16_f32 v93, v104, v105
	v_cvt_pk_bf16_f32 v92, v102, v103
	v_cvt_pk_bf16_f32 v77, v76, v77
	v_cvt_pk_bf16_f32 v76, v74, v75
	v_or_b32_e32 v152, 0x18000, v152
	v_cvt_pk_bf16_f32 v45, v44, v45
	v_cvt_pk_bf16_f32 v44, v42, v43
	v_lshl_add_u64 v[42:43], v[154:155], 0, s[12:13]
	s_mov_b64 s[12:13], 0x50000
	global_store_dwordx2 v[106:107], v[108:109], off offset:544
	global_store_dwordx2 v[106:107], v[96:97], off offset:768
	global_store_dwordx2 v[90:91], v[92:93], off offset:512
	v_cvt_pk_bf16_f32 v93, v100, v101
	v_cvt_pk_bf16_f32 v92, v98, v99
	v_cvt_pk_bf16_f32 v81, v80, v81
	v_cvt_pk_bf16_f32 v80, v78, v79
	global_store_dwordx2 v[90:91], v[76:77], off offset:800
	v_lshl_add_u64 v[74:75], v[138:139], 0, v[152:153]
	v_cvt_pk_bf16_f32 v77, v88, v89
	v_cvt_pk_bf16_f32 v76, v86, v87
	v_mov_b32_e32 v151, v0
	v_cvt_pk_bf16_f32 v29, v28, v29
	v_cvt_pk_bf16_f32 v28, v26, v27
	v_lshl_add_u64 v[26:27], v[154:155], 0, s[12:13]
	s_mov_b64 s[12:13], 0x58000
	global_store_dwordx2 v[90:91], v[92:93], off offset:544
	global_store_dwordx2 v[90:91], v[80:81], off offset:768
	global_store_dwordx2 v[74:75], v[76:77], off offset:512
	v_cvt_pk_bf16_f32 v77, v84, v85
	v_cvt_pk_bf16_f32 v76, v82, v83
	v_cvt_pk_bf16_f32 v73, v72, v73
	v_cvt_pk_bf16_f32 v72, v70, v71
	v_cvt_pk_bf16_f32 v53, v52, v53
	v_cvt_pk_bf16_f32 v52, v50, v51
	v_lshl_add_u64 v[50:51], v[66:67], 0, v[150:151]
	v_cvt_pk_bf16_f32 v33, v32, v33
	v_cvt_pk_bf16_f32 v32, v30, v31
	v_lshl_add_u64 v[30:31], v[42:43], 0, v[150:151]
	v_cvt_pk_bf16_f32 v17, v16, v17
	v_cvt_pk_bf16_f32 v16, v14, v15
	v_lshl_add_u64 v[14:15], v[26:27], 0, v[150:151]
	v_cvt_pk_bf16_f32 v13, v12, v13
	v_cvt_pk_bf16_f32 v12, v10, v11
	v_lshl_add_u64 v[10:11], v[154:155], 0, s[12:13]
	global_store_dwordx2 v[74:75], v[76:77], off offset:544
	global_store_dwordx2 v[74:75], v[72:73], off offset:768
	global_store_dwordx2 v[74:75], v[68:69], off offset:800
	v_mov_b32_e32 v147, v0
	global_store_dwordx2 v[50:51], v[44:45], off offset:512
	v_lshl_add_u64 v[44:45], v[42:43], 0, v[144:145]
	v_cvt_pk_bf16_f32 v51, v56, v57
	v_cvt_pk_bf16_f32 v50, v54, v55
	global_store_dwordx2 v[30:31], v[28:29], off offset:512
	v_lshl_add_u64 v[28:29], v[26:27], 0, v[144:145]
	v_cvt_pk_bf16_f32 v31, v40, v41
	v_cvt_pk_bf16_f32 v30, v38, v39
	global_store_dwordx2 v[14:15], v[12:13], off offset:512
	v_lshl_add_u64 v[12:13], v[10:11], 0, v[144:145]
	v_cvt_pk_bf16_f32 v15, v24, v25
	v_cvt_pk_bf16_f32 v14, v22, v23
	v_mov_b32_e32 v149, v0
	global_store_dwordx2 v[44:45], v[50:51], off offset:512
	v_lshl_add_u64 v[44:45], v[42:43], 0, v[146:147]
	v_cvt_pk_bf16_f32 v49, v48, v49
	v_cvt_pk_bf16_f32 v48, v46, v47
	global_store_dwordx2 v[28:29], v[30:31], off offset:512
	v_lshl_add_u64 v[28:29], v[26:27], 0, v[146:147]
	v_cvt_pk_bf16_f32 v31, v36, v37
	v_cvt_pk_bf16_f32 v30, v34, v35
	global_store_dwordx2 v[12:13], v[14:15], off offset:512
	v_lshl_add_u64 v[12:13], v[10:11], 0, v[146:147]
	v_cvt_pk_bf16_f32 v15, v20, v21
	v_cvt_pk_bf16_f32 v14, v18, v19
	v_lshl_add_u64 v[68:69], v[66:67], 0, v[144:145]
	v_cvt_pk_bf16_f32 v65, v64, v65
	v_cvt_pk_bf16_f32 v64, v62, v63
	v_lshl_add_u64 v[62:63], v[66:67], 0, v[146:147]
	v_cvt_pk_bf16_f32 v61, v60, v61
	v_cvt_pk_bf16_f32 v60, v58, v59
	v_lshl_add_u64 v[58:59], v[66:67], 0, v[148:149]
	global_store_dwordx2 v[44:45], v[48:49], off offset:512
	v_lshl_add_u64 v[44:45], v[42:43], 0, v[148:149]
	global_store_dwordx2 v[28:29], v[30:31], off offset:512
	v_lshl_add_u64 v[28:29], v[26:27], 0, v[148:149]
	global_store_dwordx2 v[12:13], v[14:15], off offset:512
	v_lshl_add_u64 v[12:13], v[10:11], 0, v[148:149]
	v_cvt_pk_bf16_f32 v9, v8, v9
	v_cvt_pk_bf16_f32 v8, v6, v7
	v_lshl_add_u64 v[6:7], v[10:11], 0, v[150:151]
	v_cvt_pk_bf16_f32 v5, v4, v5
	v_cvt_pk_bf16_f32 v4, v2, v3
	s_and_b64 vcc, exec, s[4:5]
	s_mov_b32 s12, s0
	s_mov_b32 s28, s6
	s_mov_b64 s[16:17], s[10:11]
	s_mov_b64 s[14:15], s[8:9]
	global_store_dwordx2 v[68:69], v[64:65], off offset:512
	global_store_dwordx2 v[62:63], v[60:61], off offset:512
	global_store_dwordx2 v[58:59], v[52:53], off offset:512
	global_store_dwordx2 v[44:45], v[32:33], off offset:512
	global_store_dwordx2 v[28:29], v[16:17], off offset:512
	global_store_dwordx2 v[12:13], v[8:9], off offset:512
	global_store_dwordx2 v[6:7], v[4:5], off offset:512
	s_cbranch_vccz .LBB0_1081
	s_waitcnt vmcnt(0)
	s_cmpk_gt_u32 s2, 0xff
	s_movk_i32 s21, 0x210
	s_mov_b32 s26, 0x2aaaaaab
	s_movk_i32 s27, 0xff40
	s_cbranch_scc1 .LBB0_1092
	s_barrier

; #define PG8_STAGE(bufoff, gbase, voff) do { _Pragma("unroll") for (int _i = 0; _i < 2; ++_i) \
;     __builtin_amdgcn_global_load_lds((const unsigned*)((const char*)(gbase) + (voff)[_i]), (PG8_LAS unsigned*)(lds + (bufoff) + ldsw + _i * 8192), 16, 0, 0); } while (0)
; #define PG8_LDA(dst, b, h) do { _Pragma("unroll") for (int m = 0; m < 4; ++m) _Pragma("unroll") for (int k = 0; k < 2; ++k) dst[m][k] = *(const PG8_LAS bf16x8*)(lds + PG8_SA(b, h) + aoff + m * 2048 + k * 1024); } while (0)
; #define PG8_LDB(dst, b, h) do { _Pragma("unroll") for (int n = 0; n < 2; ++n) _Pragma("unroll") for (int k = 0; k < 2; ++k) dst[n][k] = *(const PG8_LAS bf16x8*)(lds + PG8_SB(b, h) + boff + n * 2048 + k * 1024); } while (0)
; #define PG8_MMA(ai, bj, At, Bt) do { __builtin_amdgcn_s_setprio(1); _Pragma("unroll") for (int m = 0; m < 4; ++m) _Pragma("unroll") for (int n = 0; n < 2; ++n) _Pragma("unroll") for (int k = 0; k < 2; ++k) \
;     acc[ai][bj][m][n] = __builtin_amdgcn_mfma_f32_16x16x32_bf16(Bt[n][k], At[m][k], acc[ai][bj][m][n], 0, 0, 0); __builtin_amdgcn_s_setprio(0); } while (0)
; #define PG8_WAIT_L(n) asm volatile("s_waitcnt lgkmcnt(" #n ")" ::: "memory")
; #define PG8_BAR __builtin_amdgcn_s_barrier()
; #define PG8_SCHED __builtin_amdgcn_sched_barrier(0)
; template <class Epi, class Sched>
; __device__ __forceinline__ void gemm_phase(PG8_LAS unsigned char* lds, const int lda, const int ldb, const Sched& S, const Epi& E) {
;     ...
;     for (int t = 0; t < nt; t += 2) {
;       const bool last = (t == nt - 2);
;       const char* a1 = cA + (size_t)(t + 1) * kstep;
;       const char* a2 = last ? nA : cA + (size_t)(t + 2) * kstep; const char* b2 = last ? nB : cB + (size_t)(t + 2) * kstep;
;       const char* a3 = a2 + kstep; const char* b3 = b2 + kstep;
;       PG8_LDB(B0, 0, 0); PG8_SCHED; PG8_LDA(At, 0, 0); PG8_STAGE(PG8_SA(1, 1), a1 + hstepA, voffA);
;       PG8_WAIT_L(8); PG8_BAR; PG8_WAIT_L(0); PG8_MMA(0, 0, At, B0); PG8_BAR; PG8_SCHED;
;       PG8_LDB(B1, 0, 1); PG8_STAGE(PG8_SB(0, 0), b2, voffB);
;       PG8_BAR; PG8_WAIT_L(0); PG8_MMA(0, 1, At, B1); PG8_BAR;
;       PG8_LDA(At, 0, 1); PG8_STAGE(PG8_SA(0, 0), a2, voffA);
;       PG8_BAR; PG8_WAIT_L(0); PG8_MMA(1, 0, At, B0); PG8_BAR; PG8_SCHED;
.LBB0_1412:
	s_add_i32 s33, s18, 2
	s_add_u32 s19, s14, 0xfffc0080
	s_addc_u32 s20, s15, -1
	s_add_i32 s44, 0, 0x10000
	v_add_u32_e32 v152, s44, v131
	ds_read_b128 v[140:143], v152
	ds_read_b128 v[144:147], v152 offset:1024
	ds_read_b128 v[148:151], v152 offset:2048
	ds_read_b128 v[152:155], v152 offset:3072
	s_cmp_eq_u32 s11, s18
	s_cselect_b32 s18, s12, s22
	s_cselect_b32 s21, s7, s20
	s_cselect_b32 s20, s6, s19
	s_cselect_b32 s19, s13, s23
	v_lshl_add_u64 v[182:183], s[14:15], 0, v[136:137]
	s_add_i32 m0, s17, 0xc000
	ds_read_b128 v[156:159], v201
	ds_read_b128 v[160:163], v201 offset:1024
	ds_read_b128 v[164:167], v201 offset:2048
	ds_read_b128 v[168:171], v201 offset:3072
	ds_read_b128 v[172:175], v201 offset:4096
	ds_read_b128 v[202:205], v201 offset:5120
	ds_read_b128 v[206:209], v201 offset:6144
	ds_read_b128 v[210:213], v201 offset:7168
	global_load_lds_dwordx4 v[182:183], off
	v_lshl_add_u64 v[182:183], s[14:15], 0, v[138:139]
	s_add_i32 m0, s17, 0xe000
	s_nop 0
	global_load_lds_dwordx4 v[182:183], off
	s_waitcnt lgkmcnt(8)
	s_barrier
	s_waitcnt lgkmcnt(0)
	s_setprio 1
	v_mfma_f32_16x16x32_bf16 v[126:129], v[140:143], v[156:159], v[126:129]
	v_mfma_f32_16x16x32_bf16 v[122:125], v[148:151], v[156:159], v[122:125]
	v_mfma_f32_16x16x32_bf16 v[118:121], v[140:143], v[164:167], v[118:121]
	v_mfma_f32_16x16x32_bf16 v[114:117], v[148:151], v[164:167], v[114:117]
	v_mfma_f32_16x16x32_bf16 v[110:113], v[140:143], v[172:175], v[110:113]
	v_mfma_f32_16x16x32_bf16 v[106:109], v[148:151], v[172:175], v[106:109]
	v_mfma_f32_16x16x32_bf16 v[102:105], v[140:143], v[206:209], v[102:105]
	v_mfma_f32_16x16x32_bf16 v[98:101], v[148:151], v[206:209], v[98:101]
	v_mfma_f32_16x16x32_bf16 v[126:129], v[144:147], v[160:163], v[126:129]
	v_mfma_f32_16x16x32_bf16 v[122:125], v[152:155], v[160:163], v[122:125]
	v_mfma_f32_16x16x32_bf16 v[118:121], v[144:147], v[168:171], v[118:121]
	v_mfma_f32_16x16x32_bf16 v[114:117], v[152:155], v[168:171], v[114:117]
	v_mfma_f32_16x16x32_bf16 v[110:113], v[144:147], v[202:205], v[110:113]
	v_mfma_f32_16x16x32_bf16 v[106:109], v[152:155], v[202:205], v[106:109]
	v_mfma_f32_16x16x32_bf16 v[102:105], v[144:147], v[210:213], v[102:105]
	v_mfma_f32_16x16x32_bf16 v[98:101], v[152:155], v[210:213], v[98:101]
	s_setprio 0
	s_barrier
	s_add_i32 s46, 0, 0x14000
	v_add_u32_e32 v182, s46, v131
	s_add_i32 s44, s44, s29
	ds_read_b128 v[214:217], v182
	ds_read_b128 v[218:221], v182 offset:1024
	ds_read_b128 v[222:225], v182 offset:2048
	ds_read_b128 v[226:229], v182 offset:3072
	v_lshl_add_u64 v[182:183], s[18:19], 0, v[134:135]
	s_mov_b32 m0, s44
	v_lshl_add_u64 v[184:185], s[18:19], 0, v[132:133]
	global_load_lds_dwordx4 v[182:183], off
	s_add_i32 m0, s44, 0x2000
	s_nop 0
	global_load_lds_dwordx4 v[184:185], off
	s_waitcnt lgkmcnt(0)
	s_barrier
	s_setprio 1
	v_mfma_f32_16x16x32_bf16 v[94:97], v[214:217], v[156:159], v[94:97]
	v_mfma_f32_16x16x32_bf16 v[90:93], v[222:225], v[156:159], v[90:93]
	v_mfma_f32_16x16x32_bf16 v[86:89], v[214:217], v[164:167], v[86:89]
	v_mfma_f32_16x16x32_bf16 v[82:85], v[222:225], v[164:167], v[82:85]
	v_mfma_f32_16x16x32_bf16 v[78:81], v[214:217], v[172:175], v[78:81]
	v_mfma_f32_16x16x32_bf16 v[74:77], v[222:225], v[172:175], v[74:77]
	v_mfma_f32_16x16x32_bf16 v[70:73], v[214:217], v[206:209], v[70:73]
	v_mfma_f32_16x16x32_bf16 v[66:69], v[222:225], v[206:209], v[66:69]
	v_mfma_f32_16x16x32_bf16 v[94:97], v[218:221], v[160:163], v[94:97]
	v_mfma_f32_16x16x32_bf16 v[90:93], v[226:229], v[160:163], v[90:93]
	v_mfma_f32_16x16x32_bf16 v[86:89], v[218:221], v[168:171], v[86:89]
	v_mfma_f32_16x16x32_bf16 v[82:85], v[226:229], v[168:171], v[82:85]
	v_mfma_f32_16x16x32_bf16 v[78:81], v[218:221], v[202:205], v[78:81]
	v_mfma_f32_16x16x32_bf16 v[74:77], v[226:229], v[202:205], v[74:77]
	v_mfma_f32_16x16x32_bf16 v[70:73], v[218:221], v[210:213], v[70:73]
	v_mfma_f32_16x16x32_bf16 v[66:69], v[226:229], v[210:213], v[66:69]
	s_setprio 0
	s_mov_b32 m0, s17
	v_lshl_add_u64 v[230:231], s[20:21], 0, v[134:135]
	s_barrier
	ds_read_b128 v[156:159], v201 offset:16384
	ds_read_b128 v[160:163], v201 offset:17408
	ds_read_b128 v[164:167], v201 offset:18432
	ds_read_b128 v[168:171], v201 offset:19456
	ds_read_b128 v[172:175], v201 offset:20480
	ds_read_b128 v[202:205], v201 offset:21504
	ds_read_b128 v[206:209], v201 offset:22528
	ds_read_b128 v[210:213], v201 offset:23552
	global_load_lds_dwordx4 v[230:231], off
	v_lshl_add_u64 v[232:233], s[20:21], 0, v[132:133]
	s_mov_b32 m0, s34
	s_nop 0
	global_load_lds_dwordx4 v[232:233], off
	s_waitcnt lgkmcnt(0)
	s_barrier
	s_setprio 1
	v_mfma_f32_16x16x32_bf16 v[62:65], v[140:143], v[156:159], v[62:65]
	v_mfma_f32_16x16x32_bf16 v[58:61], v[148:151], v[156:159], v[58:61]
	v_mfma_f32_16x16x32_bf16 v[54:57], v[140:143], v[164:167], v[54:57]
	v_mfma_f32_16x16x32_bf16 v[50:53], v[148:151], v[164:167], v[50:53]
	v_mfma_f32_16x16x32_bf16 v[46:49], v[140:143], v[172:175], v[46:49]
	v_mfma_f32_16x16x32_bf16 v[42:45], v[148:151], v[172:175], v[42:45]
	v_mfma_f32_16x16x32_bf16 v[38:41], v[140:143], v[206:209], v[38:41]
	v_mfma_f32_16x16x32_bf16 v[34:37], v[148:151], v[206:209], v[34:37]
	v_mfma_f32_16x16x32_bf16 v[62:65], v[144:147], v[160:163], v[62:65]
	v_mfma_f32_16x16x32_bf16 v[58:61], v[152:155], v[160:163], v[58:61]
	v_mfma_f32_16x16x32_bf16 v[54:57], v[144:147], v[168:171], v[54:57]
	v_mfma_f32_16x16x32_bf16 v[50:53], v[152:155], v[168:171], v[50:53]
	v_mfma_f32_16x16x32_bf16 v[46:49], v[144:147], v[202:205], v[46:49]
	v_mfma_f32_16x16x32_bf16 v[42:45], v[152:155], v[202:205], v[42:45]
	v_mfma_f32_16x16x32_bf16 v[38:41], v[144:147], v[210:213], v[38:41]
	v_mfma_f32_16x16x32_bf16 v[34:37], v[152:155], v[210:213], v[34:37]
	s_setprio 0
	s_barrier
; #define PG8_STAGE(bufoff, gbase, voff) do { _Pragma("unroll") for (int _i = 0; _i < 2; ++_i) \
;     __builtin_amdgcn_global_load_lds((const unsigned*)((const char*)(gbase) + (voff)[_i]), (PG8_LAS unsigned*)(lds + (bufoff) + ldsw + _i * 8192), 16, 0, 0); } while (0)
; #define PG8_LDA(dst, b, h) do { _Pragma("unroll") for (int m = 0; m < 4; ++m) _Pragma("unroll") for (int k = 0; k < 2; ++k) dst[m][k] = *(const PG8_LAS bf16x8*)(lds + PG8_SA(b, h) + aoff + m * 2048 + k * 1024); } while (0)
; #define PG8_LDB(dst, b, h) do { _Pragma("unroll") for (int n = 0; n < 2; ++n) _Pragma("unroll") for (int k = 0; k < 2; ++k) dst[n][k] = *(const PG8_LAS bf16x8*)(lds + PG8_SB(b, h) + boff + n * 2048 + k * 1024); } while (0)
; #define PG8_MMA(ai, bj, At, Bt) do { __builtin_amdgcn_s_setprio(1); _Pragma("unroll") for (int m = 0; m < 4; ++m) _Pragma("unroll") for (int n = 0; n < 2; ++n) _Pragma("unroll") for (int k = 0; k < 2; ++k) \
;     acc[ai][bj][m][n] = __builtin_amdgcn_mfma_f32_16x16x32_bf16(Bt[n][k], At[m][k], acc[ai][bj][m][n], 0, 0, 0); __builtin_amdgcn_s_setprio(0); } while (0)
; #define PG8_WAIT_V(n) asm volatile("s_waitcnt vmcnt(" #n ")" ::: "memory")
; #define PG8_WAIT_L(n) asm volatile("s_waitcnt lgkmcnt(" #n ")" ::: "memory")
; #define PG8_BAR __builtin_amdgcn_s_barrier()
; #define PG8_SCHED __builtin_amdgcn_sched_barrier(0)
; template <class Epi, class Sched>
; __device__ __forceinline__ void gemm_phase(PG8_LAS unsigned char* lds, const int lda, const int ldb, const Sched& S, const Epi& E) {
;     ...
;       PG8_STAGE(PG8_SB(0, 1), b2 + hstepB, voffB);
;       PG8_WAIT_V(6); PG8_BAR; PG8_MMA(1, 1, At, B1); PG8_BAR;
;       PG8_LDB(B0, 1, 0); PG8_SCHED; PG8_LDA(At, 1, 0); PG8_STAGE(PG8_SA(0, 1), a2 + hstepA, voffA);
;       PG8_WAIT_L(8); PG8_BAR; PG8_WAIT_L(0); PG8_MMA(0, 0, At, B0); PG8_BAR; PG8_SCHED;
;       PG8_LDB(B1, 1, 1); PG8_STAGE(PG8_SB(1, 0), b3, voffB);
;       PG8_BAR; PG8_WAIT_L(0); PG8_MMA(0, 1, At, B1); PG8_BAR;
	s_add_u32 s44, s18, 0x40000
	s_addc_u32 s45, s19, 0
	s_add_i32 s46, s46, s29
	v_lshl_add_u64 v[140:141], s[44:45], 0, v[134:135]
	s_mov_b32 m0, s46
	s_nop 0
	global_load_lds_dwordx4 v[140:141], off
	v_lshl_add_u64 v[140:141], s[44:45], 0, v[132:133]
	s_add_i32 m0, s46, 0x2000
	s_nop 0
	global_load_lds_dwordx4 v[140:141], off
	s_waitcnt vmcnt(6)
	s_barrier
	s_setprio 1
	v_mfma_f32_16x16x32_bf16 v[30:33], v[214:217], v[156:159], v[30:33]
	v_mfma_f32_16x16x32_bf16 v[26:29], v[222:225], v[156:159], v[26:29]
	v_mfma_f32_16x16x32_bf16 v[22:25], v[214:217], v[164:167], v[22:25]
	v_mfma_f32_16x16x32_bf16 v[18:21], v[222:225], v[164:167], v[18:21]
	v_mfma_f32_16x16x32_bf16 v[14:17], v[214:217], v[172:175], v[14:17]
	v_mfma_f32_16x16x32_bf16 v[10:13], v[222:225], v[172:175], v[10:13]
	v_mfma_f32_16x16x32_bf16 v[6:9], v[214:217], v[206:209], v[6:9]
	v_mfma_f32_16x16x32_bf16 v[2:5], v[222:225], v[206:209], v[2:5]
	v_mfma_f32_16x16x32_bf16 v[30:33], v[218:221], v[160:163], v[30:33]
	v_mfma_f32_16x16x32_bf16 v[26:29], v[226:229], v[160:163], v[26:29]
	v_mfma_f32_16x16x32_bf16 v[22:25], v[218:221], v[168:171], v[22:25]
	v_mfma_f32_16x16x32_bf16 v[18:21], v[226:229], v[168:171], v[18:21]
	v_mfma_f32_16x16x32_bf16 v[14:17], v[218:221], v[202:205], v[14:17]
	v_mfma_f32_16x16x32_bf16 v[10:13], v[226:229], v[202:205], v[10:13]
	v_mfma_f32_16x16x32_bf16 v[6:9], v[218:221], v[210:213], v[6:9]
	v_mfma_f32_16x16x32_bf16 v[2:5], v[226:229], v[210:213], v[2:5]
	s_setprio 0
	s_add_i32 s44, 0, 0x18000
	v_add_u32_e32 v152, s44, v131
	s_barrier
	ds_read_b128 v[140:143], v152
	ds_read_b128 v[144:147], v152 offset:1024
	ds_read_b128 v[148:151], v152 offset:2048
	ds_read_b128 v[152:155], v152 offset:3072
	s_add_u32 s20, s20, 0x40000
	s_addc_u32 s21, s21, 0
	s_mov_b32 m0, s35
	v_lshl_add_u64 v[214:215], s[20:21], 0, v[134:135]
	ds_read_b128 v[156:159], v201 offset:32768
	ds_read_b128 v[160:163], v201 offset:33792
	ds_read_b128 v[164:167], v201 offset:34816
	ds_read_b128 v[168:171], v201 offset:35840
	ds_read_b128 v[172:175], v201 offset:36864
	ds_read_b128 v[202:205], v201 offset:37888
	ds_read_b128 v[206:209], v201 offset:38912
	ds_read_b128 v[210:213], v201 offset:39936
	global_load_lds_dwordx4 v[214:215], off
	v_lshl_add_u64 v[214:215], s[20:21], 0, v[132:133]
	s_mov_b32 m0, s36
	s_nop 0
	global_load_lds_dwordx4 v[214:215], off
	s_waitcnt lgkmcnt(8)
	s_barrier
	s_waitcnt lgkmcnt(0)
	s_setprio 1
	v_mfma_f32_16x16x32_bf16 v[126:129], v[140:143], v[156:159], v[126:129]
	v_mfma_f32_16x16x32_bf16 v[122:125], v[148:151], v[156:159], v[122:125]
	v_mfma_f32_16x16x32_bf16 v[118:121], v[140:143], v[164:167], v[118:121]
	v_mfma_f32_16x16x32_bf16 v[114:117], v[148:151], v[164:167], v[114:117]
	v_mfma_f32_16x16x32_bf16 v[110:113], v[140:143], v[172:175], v[110:113]
	v_mfma_f32_16x16x32_bf16 v[106:109], v[148:151], v[172:175], v[106:109]
	v_mfma_f32_16x16x32_bf16 v[102:105], v[140:143], v[206:209], v[102:105]
	v_mfma_f32_16x16x32_bf16 v[98:101], v[148:151], v[206:209], v[98:101]
	v_mfma_f32_16x16x32_bf16 v[126:129], v[144:147], v[160:163], v[126:129]
	v_mfma_f32_16x16x32_bf16 v[122:125], v[152:155], v[160:163], v[122:125]
	v_mfma_f32_16x16x32_bf16 v[118:121], v[144:147], v[168:171], v[118:121]
	v_mfma_f32_16x16x32_bf16 v[114:117], v[152:155], v[168:171], v[114:117]
	v_mfma_f32_16x16x32_bf16 v[110:113], v[144:147], v[202:205], v[110:113]
	v_mfma_f32_16x16x32_bf16 v[106:109], v[152:155], v[202:205], v[106:109]
	v_mfma_f32_16x16x32_bf16 v[102:105], v[144:147], v[210:213], v[102:105]
	v_mfma_f32_16x16x32_bf16 v[98:101], v[152:155], v[210:213], v[98:101]
	s_setprio 0
	s_barrier
	s_add_i32 s20, 0, 0x1c000
	s_add_i32 s21, s44, s29
	v_add_u32_e32 v226, s20, v131
	v_lshl_add_u64 v[182:183], v[182:183], 0, s[86:87]
	s_mov_b32 m0, s21
	ds_read_b128 v[214:217], v226
	ds_read_b128 v[218:221], v226 offset:1024
	ds_read_b128 v[222:225], v226 offset:2048
	ds_read_b128 v[226:229], v226 offset:3072
	global_load_lds_dwordx4 v[182:183], off
	v_lshl_add_u64 v[182:183], v[184:185], 0, s[86:87]
	s_add_i32 m0, s21, 0x2000
	s_nop 0
	global_load_lds_dwordx4 v[182:183], off
	s_waitcnt lgkmcnt(0)
	s_barrier
; __device__ __forceinline__ int tid_l() { int t = threadIdx.x; asm volatile("" : "+v"(t)); return t; }
; #define PG8_STAGE(bufoff, gbase, voff) do { _Pragma("unroll") for (int _i = 0; _i < 2; ++_i) \
;     __builtin_amdgcn_global_load_lds((const unsigned*)((const char*)(gbase) + (voff)[_i]), (PG8_LAS unsigned*)(lds + (bufoff) + ldsw + _i * 8192), 16, 0, 0); } while (0)
; #define PG8_LDA(dst, b, h) do { _Pragma("unroll") for (int m = 0; m < 4; ++m) _Pragma("unroll") for (int k = 0; k < 2; ++k) dst[m][k] = *(const PG8_LAS bf16x8*)(lds + PG8_SA(b, h) + aoff + m * 2048 + k * 1024); } while (0)
; #define PG8_MMA(ai, bj, At, Bt) do { __builtin_amdgcn_s_setprio(1); _Pragma("unroll") for (int m = 0; m < 4; ++m) _Pragma("unroll") for (int n = 0; n < 2; ++n) _Pragma("unroll") for (int k = 0; k < 2; ++k) \
;     acc[ai][bj][m][n] = __builtin_amdgcn_mfma_f32_16x16x32_bf16(Bt[n][k], At[m][k], acc[ai][bj][m][n], 0, 0, 0); __builtin_amdgcn_s_setprio(0); } while (0)
; #define PG8_WAIT_V(n) asm volatile("s_waitcnt vmcnt(" #n ")" ::: "memory")
; #define PG8_WAIT_L(n) asm volatile("s_waitcnt lgkmcnt(" #n ")" ::: "memory")
; #define PG8_BAR __builtin_amdgcn_s_barrier()
; #define PG8_SCHED __builtin_amdgcn_sched_barrier(0)
; template <class Epi, class Sched>
; __device__ __forceinline__ void gemm_phase(PG8_LAS unsigned char* lds, const int lda, const int ldb, const Sched& S, const Epi& E) {
;     ...
;       PG8_BAR; PG8_WAIT_L(0); PG8_MMA(0, 1, At, B1); PG8_BAR;
;       PG8_LDA(At, 1, 1); PG8_STAGE(PG8_SA(1, 0), a3, voffA);
;       PG8_BAR; PG8_WAIT_L(0); PG8_MMA(1, 0, At, B0); PG8_BAR; PG8_SCHED;
;       PG8_STAGE(PG8_SB(1, 1), b3 + hstepB, voffB);
;       PG8_WAIT_V(6); PG8_BAR; PG8_MMA(1, 1, At, B1); PG8_BAR;
;     }
;   __device__ __forceinline__ void operator()(const f32x4 (&acc)[2][2][4][2], const Unit& u, int wr, int wc, int fr, int fq) const {
;     const int s = u.pn & 7, dq = u.pn >> 3;
;     const int tid = tid_l();
;     if (s < 4) {
	s_setprio 1
	v_mfma_f32_16x16x32_bf16 v[94:97], v[214:217], v[156:159], v[94:97]
	v_mfma_f32_16x16x32_bf16 v[90:93], v[222:225], v[156:159], v[90:93]
	v_mfma_f32_16x16x32_bf16 v[86:89], v[214:217], v[164:167], v[86:89]
	v_mfma_f32_16x16x32_bf16 v[82:85], v[222:225], v[164:167], v[82:85]
	v_mfma_f32_16x16x32_bf16 v[78:81], v[214:217], v[172:175], v[78:81]
	v_mfma_f32_16x16x32_bf16 v[74:77], v[222:225], v[172:175], v[74:77]
	v_mfma_f32_16x16x32_bf16 v[70:73], v[214:217], v[206:209], v[70:73]
	v_mfma_f32_16x16x32_bf16 v[66:69], v[222:225], v[206:209], v[66:69]
	v_mfma_f32_16x16x32_bf16 v[94:97], v[218:221], v[160:163], v[94:97]
	v_mfma_f32_16x16x32_bf16 v[90:93], v[226:229], v[160:163], v[90:93]
	v_mfma_f32_16x16x32_bf16 v[86:89], v[218:221], v[168:171], v[86:89]
	v_mfma_f32_16x16x32_bf16 v[82:85], v[226:229], v[168:171], v[82:85]
	v_mfma_f32_16x16x32_bf16 v[78:81], v[218:221], v[202:205], v[78:81]
	v_mfma_f32_16x16x32_bf16 v[74:77], v[226:229], v[202:205], v[74:77]
	v_mfma_f32_16x16x32_bf16 v[70:73], v[218:221], v[210:213], v[70:73]
	v_mfma_f32_16x16x32_bf16 v[66:69], v[226:229], v[210:213], v[66:69]
	s_setprio 0
	s_mov_b32 m0, s39
	v_lshl_add_u64 v[182:183], v[230:231], 0, s[86:87]
	s_barrier
	ds_read_b128 v[156:159], v201 offset:49152
	ds_read_b128 v[160:163], v201 offset:50176
	ds_read_b128 v[164:167], v201 offset:51200
	ds_read_b128 v[168:171], v201 offset:52224
	ds_read_b128 v[172:175], v201 offset:53248
	ds_read_b128 v[202:205], v201 offset:54272
	ds_read_b128 v[206:209], v201 offset:55296
	ds_read_b128 v[210:213], v201 offset:56320
	global_load_lds_dwordx4 v[182:183], off
	v_lshl_add_u64 v[182:183], v[232:233], 0, s[86:87]
	s_mov_b32 m0, s40
	s_nop 0
	global_load_lds_dwordx4 v[182:183], off
	s_waitcnt lgkmcnt(0)
	s_barrier
	s_setprio 1
	v_mfma_f32_16x16x32_bf16 v[62:65], v[140:143], v[156:159], v[62:65]
	v_mfma_f32_16x16x32_bf16 v[58:61], v[148:151], v[156:159], v[58:61]
	v_mfma_f32_16x16x32_bf16 v[54:57], v[140:143], v[164:167], v[54:57]
	v_mfma_f32_16x16x32_bf16 v[50:53], v[148:151], v[164:167], v[50:53]
	v_mfma_f32_16x16x32_bf16 v[46:49], v[140:143], v[172:175], v[46:49]
	v_mfma_f32_16x16x32_bf16 v[42:45], v[148:151], v[172:175], v[42:45]
	v_mfma_f32_16x16x32_bf16 v[38:41], v[140:143], v[206:209], v[38:41]
	v_mfma_f32_16x16x32_bf16 v[34:37], v[148:151], v[206:209], v[34:37]
	v_mfma_f32_16x16x32_bf16 v[62:65], v[144:147], v[160:163], v[62:65]
	v_mfma_f32_16x16x32_bf16 v[58:61], v[152:155], v[160:163], v[58:61]
	v_mfma_f32_16x16x32_bf16 v[54:57], v[144:147], v[168:171], v[54:57]
	v_mfma_f32_16x16x32_bf16 v[50:53], v[152:155], v[168:171], v[50:53]
	v_mfma_f32_16x16x32_bf16 v[46:49], v[144:147], v[202:205], v[46:49]
	v_mfma_f32_16x16x32_bf16 v[42:45], v[152:155], v[202:205], v[42:45]
	v_mfma_f32_16x16x32_bf16 v[38:41], v[144:147], v[210:213], v[38:41]
	v_mfma_f32_16x16x32_bf16 v[34:37], v[152:155], v[210:213], v[34:37]
	s_setprio 0
	s_barrier
	s_add_u32 s18, s18, 0x40080
	s_addc_u32 s19, s19, 0
	s_add_i32 s20, s20, s29
	v_lshl_add_u64 v[140:141], s[18:19], 0, v[134:135]
	s_mov_b32 m0, s20
	s_nop 0
	global_load_lds_dwordx4 v[140:141], off
	v_lshl_add_u64 v[140:141], s[18:19], 0, v[132:133]
	s_add_i32 m0, s20, 0x2000
	s_nop 0
	global_load_lds_dwordx4 v[140:141], off
	s_waitcnt vmcnt(6)
	s_barrier
	s_setprio 1
	v_mfma_f32_16x16x32_bf16 v[30:33], v[214:217], v[156:159], v[30:33]
	v_mfma_f32_16x16x32_bf16 v[26:29], v[222:225], v[156:159], v[26:29]
	v_mfma_f32_16x16x32_bf16 v[22:25], v[214:217], v[164:167], v[22:25]
	v_mfma_f32_16x16x32_bf16 v[18:21], v[222:225], v[164:167], v[18:21]
	v_mfma_f32_16x16x32_bf16 v[14:17], v[214:217], v[172:175], v[14:17]
	v_mfma_f32_16x16x32_bf16 v[10:13], v[222:225], v[172:175], v[10:13]
	v_mfma_f32_16x16x32_bf16 v[6:9], v[214:217], v[206:209], v[6:9]
	v_mfma_f32_16x16x32_bf16 v[2:5], v[222:225], v[206:209], v[2:5]
	v_mfma_f32_16x16x32_bf16 v[30:33], v[218:221], v[160:163], v[30:33]
	v_mfma_f32_16x16x32_bf16 v[26:29], v[226:229], v[160:163], v[26:29]
	v_mfma_f32_16x16x32_bf16 v[22:25], v[218:221], v[168:171], v[22:25]
	v_mfma_f32_16x16x32_bf16 v[18:21], v[226:229], v[168:171], v[18:21]
	v_mfma_f32_16x16x32_bf16 v[14:17], v[218:221], v[202:205], v[14:17]
	v_mfma_f32_16x16x32_bf16 v[10:13], v[226:229], v[202:205], v[10:13]
	v_mfma_f32_16x16x32_bf16 v[6:9], v[218:221], v[210:213], v[6:9]
	v_mfma_f32_16x16x32_bf16 v[2:5], v[226:229], v[210:213], v[2:5]
	s_setprio 0
	s_add_u32 s14, s14, 0x100
	s_addc_u32 s15, s15, 0
	s_add_u32 s22, s22, 0x100
	s_addc_u32 s23, s23, 0
	s_cmp_ge_u32 s33, s43
	s_mov_b32 s18, s33
	s_barrier
	s_cbranch_scc0 .LBB0_1412
	s_and_b32 s11, s2, 7
	v_mov_b32_e32 v140, v176
	s_mov_b64 s[14:15], -1
	s_cmp_gt_u32 s11, 3
	v_ashrrev_i32_e32 v141, 31, v140
	s_cbranch_scc1 .LBB0_1416
	s_andn2_b64 vcc, exec, s[14:15]
	s_cbranch_vccz .LBB0_1417

; #define PG8_STAGE(bufoff, gbase, voff) do { _Pragma("unroll") for (int _i = 0; _i < 2; ++_i) \
;     __builtin_amdgcn_global_load_lds((const unsigned*)((const char*)(gbase) + (voff)[_i]), (PG8_LAS unsigned*)(lds + (bufoff) + ldsw + _i * 8192), 16, 0, 0); } while (0)
; #define PG8_LDA(dst, b, h) do { _Pragma("unroll") for (int m = 0; m < 4; ++m) _Pragma("unroll") for (int k = 0; k < 2; ++k) dst[m][k] = *(const PG8_LAS bf16x8*)(lds + PG8_SA(b, h) + aoff + m * 2048 + k * 1024); } while (0)
; #define PG8_LDB(dst, b, h) do { _Pragma("unroll") for (int n = 0; n < 2; ++n) _Pragma("unroll") for (int k = 0; k < 2; ++k) dst[n][k] = *(const PG8_LAS bf16x8*)(lds + PG8_SB(b, h) + boff + n * 2048 + k * 1024); } while (0)
; #define PG8_MMA(ai, bj, At, Bt) do { __builtin_amdgcn_s_setprio(1); _Pragma("unroll") for (int m = 0; m < 4; ++m) _Pragma("unroll") for (int n = 0; n < 2; ++n) _Pragma("unroll") for (int k = 0; k < 2; ++k) \
;     acc[ai][bj][m][n] = __builtin_amdgcn_mfma_f32_16x16x32_bf16(Bt[n][k], At[m][k], acc[ai][bj][m][n], 0, 0, 0); __builtin_amdgcn_s_setprio(0); } while (0)
; #define PG8_WAIT_L(n) asm volatile("s_waitcnt lgkmcnt(" #n ")" ::: "memory")
; #define PG8_BAR __builtin_amdgcn_s_barrier()
; #define PG8_SCHED __builtin_amdgcn_sched_barrier(0)
; template <class Epi, class Sched>
; __device__ __forceinline__ void gemm_phase(PG8_LAS unsigned char* lds, const int lda, const int ldb, const Sched& S, const Epi& E) {
;     ...
;     for (int t = 0; t < nt; t += 2) {
;       const bool last = (t == nt - 2);
;       const char* a1 = cA + (size_t)(t + 1) * kstep;
;       const char* a2 = last ? nA : cA + (size_t)(t + 2) * kstep; const char* b2 = last ? nB : cB + (size_t)(t + 2) * kstep;
;       const char* a3 = a2 + kstep; const char* b3 = b2 + kstep;
;       PG8_LDB(B0, 0, 0); PG8_SCHED; PG8_LDA(At, 0, 0); PG8_STAGE(PG8_SA(1, 1), a1 + hstepA, voffA);
;       PG8_WAIT_L(8); PG8_BAR; PG8_WAIT_L(0); PG8_MMA(0, 0, At, B0); PG8_BAR; PG8_SCHED;
;       PG8_LDB(B1, 0, 1); PG8_STAGE(PG8_SB(0, 0), b2, voffB);
;       PG8_BAR; PG8_WAIT_L(0); PG8_MMA(0, 1, At, B1); PG8_BAR;
;       PG8_LDA(At, 0, 1); PG8_STAGE(PG8_SA(0, 0), a2, voffA);
;       PG8_BAR; PG8_WAIT_L(0); PG8_MMA(1, 0, At, B0); PG8_BAR; PG8_SCHED;
.LBB0_1482:
	s_add_u32 s20, s18, 0x100
	s_addc_u32 s21, s19, 0
	s_add_i32 s33, 0, 0x10000
	v_add_u32_e32 v154, s33, v131
	ds_read_b128 v[140:143], v154
	ds_read_b128 v[146:149], v154 offset:1024
	ds_read_b128 v[150:153], v154 offset:2048
	ds_read_b128 v[154:157], v154 offset:3072
	s_cmp_eq_u32 s54, 12
	s_cselect_b32 s25, s11, s21
	s_cselect_b32 s24, s50, s20
	s_cselect_b32 s23, s1, s53
	s_cselect_b32 s22, s51, s52
	v_lshl_add_u64 v[174:175], s[18:19], 0, v[136:137]
	s_add_i32 m0, s17, 0xc000
	ds_read_b128 v[158:161], v145
	ds_read_b128 v[162:165], v145 offset:1024
	ds_read_b128 v[166:169], v145 offset:2048
	ds_read_b128 v[170:173], v145 offset:3072
	ds_read_b128 v[200:203], v145 offset:4096
	ds_read_b128 v[204:207], v145 offset:5120
	ds_read_b128 v[208:211], v145 offset:6144
	ds_read_b128 v[212:215], v145 offset:7168
	global_load_lds_dwordx4 v[174:175], off
	v_lshl_add_u64 v[174:175], s[18:19], 0, v[138:139]
	s_add_i32 m0, s17, 0xe000
	s_nop 0
	global_load_lds_dwordx4 v[174:175], off
	s_waitcnt lgkmcnt(8)
	s_barrier
	s_waitcnt lgkmcnt(0)
	s_setprio 1
	v_mfma_f32_16x16x32_bf16 v[126:129], v[140:143], v[158:161], v[126:129]
	v_mfma_f32_16x16x32_bf16 v[122:125], v[150:153], v[158:161], v[122:125]
	v_mfma_f32_16x16x32_bf16 v[110:113], v[140:143], v[166:169], v[110:113]
	v_mfma_f32_16x16x32_bf16 v[106:109], v[150:153], v[166:169], v[106:109]
	v_mfma_f32_16x16x32_bf16 v[94:97], v[140:143], v[200:203], v[94:97]
	v_mfma_f32_16x16x32_bf16 v[90:93], v[150:153], v[200:203], v[90:93]
	v_mfma_f32_16x16x32_bf16 v[78:81], v[140:143], v[208:211], v[78:81]
	v_mfma_f32_16x16x32_bf16 v[74:77], v[150:153], v[208:211], v[74:77]
	v_mfma_f32_16x16x32_bf16 v[126:129], v[146:149], v[162:165], v[126:129]
	v_mfma_f32_16x16x32_bf16 v[122:125], v[154:157], v[162:165], v[122:125]
	v_mfma_f32_16x16x32_bf16 v[110:113], v[146:149], v[170:173], v[110:113]
	v_mfma_f32_16x16x32_bf16 v[106:109], v[154:157], v[170:173], v[106:109]
	v_mfma_f32_16x16x32_bf16 v[94:97], v[146:149], v[204:207], v[94:97]
	v_mfma_f32_16x16x32_bf16 v[90:93], v[154:157], v[204:207], v[90:93]
	v_mfma_f32_16x16x32_bf16 v[78:81], v[146:149], v[212:215], v[78:81]
	v_mfma_f32_16x16x32_bf16 v[74:77], v[154:157], v[212:215], v[74:77]
	s_setprio 0
	s_barrier
	s_add_i32 s55, 0, 0x14000
	v_add_u32_e32 v174, s55, v131
	s_add_i32 s18, s33, s34
	ds_read_b128 v[216:219], v174
	ds_read_b128 v[220:223], v174 offset:1024
	ds_read_b128 v[224:227], v174 offset:2048
	ds_read_b128 v[228:231], v174 offset:3072
	v_lshl_add_u64 v[174:175], s[22:23], 0, v[134:135]
	s_mov_b32 m0, s18
	v_lshl_add_u64 v[182:183], s[22:23], 0, v[132:133]
	global_load_lds_dwordx4 v[174:175], off
	s_add_i32 m0, s18, 0x2000
	s_nop 0
	global_load_lds_dwordx4 v[182:183], off
	s_waitcnt lgkmcnt(0)
	s_barrier
	s_setprio 1
	v_mfma_f32_16x16x32_bf16 v[118:121], v[216:219], v[158:161], v[118:121]
	v_mfma_f32_16x16x32_bf16 v[114:117], v[224:227], v[158:161], v[114:117]
	v_mfma_f32_16x16x32_bf16 v[102:105], v[216:219], v[166:169], v[102:105]
	v_mfma_f32_16x16x32_bf16 v[98:101], v[224:227], v[166:169], v[98:101]
	v_mfma_f32_16x16x32_bf16 v[86:89], v[216:219], v[200:203], v[86:89]
	v_mfma_f32_16x16x32_bf16 v[82:85], v[224:227], v[200:203], v[82:85]
	v_mfma_f32_16x16x32_bf16 v[70:73], v[216:219], v[208:211], v[70:73]
	v_mfma_f32_16x16x32_bf16 v[66:69], v[224:227], v[208:211], v[66:69]
	v_mfma_f32_16x16x32_bf16 v[118:121], v[220:223], v[162:165], v[118:121]
	v_mfma_f32_16x16x32_bf16 v[114:117], v[228:231], v[162:165], v[114:117]
	v_mfma_f32_16x16x32_bf16 v[102:105], v[220:223], v[170:173], v[102:105]
	v_mfma_f32_16x16x32_bf16 v[98:101], v[228:231], v[170:173], v[98:101]
	v_mfma_f32_16x16x32_bf16 v[86:89], v[220:223], v[204:207], v[86:89]
	v_mfma_f32_16x16x32_bf16 v[82:85], v[228:231], v[204:207], v[82:85]
	v_mfma_f32_16x16x32_bf16 v[70:73], v[220:223], v[212:215], v[70:73]
	v_mfma_f32_16x16x32_bf16 v[66:69], v[228:231], v[212:215], v[66:69]
	s_setprio 0
	s_mov_b32 m0, s17
	v_lshl_add_u64 v[184:185], s[24:25], 0, v[134:135]
	s_barrier
	ds_read_b128 v[158:161], v145 offset:16384
	ds_read_b128 v[162:165], v145 offset:17408
	ds_read_b128 v[166:169], v145 offset:18432
	ds_read_b128 v[170:173], v145 offset:19456
	ds_read_b128 v[200:203], v145 offset:20480
	ds_read_b128 v[204:207], v145 offset:21504
	ds_read_b128 v[208:211], v145 offset:22528
	ds_read_b128 v[212:215], v145 offset:23552
	global_load_lds_dwordx4 v[184:185], off
	v_lshl_add_u64 v[232:233], s[24:25], 0, v[132:133]
	s_mov_b32 m0, s37
	s_nop 0
	global_load_lds_dwordx4 v[232:233], off
	s_waitcnt lgkmcnt(0)
	s_barrier
	s_setprio 1
	v_mfma_f32_16x16x32_bf16 v[62:65], v[140:143], v[158:161], v[62:65]
	v_mfma_f32_16x16x32_bf16 v[58:61], v[150:153], v[158:161], v[58:61]
	v_mfma_f32_16x16x32_bf16 v[46:49], v[140:143], v[166:169], v[46:49]
	v_mfma_f32_16x16x32_bf16 v[42:45], v[150:153], v[166:169], v[42:45]
	v_mfma_f32_16x16x32_bf16 v[30:33], v[140:143], v[200:203], v[30:33]
	v_mfma_f32_16x16x32_bf16 v[26:29], v[150:153], v[200:203], v[26:29]
	v_mfma_f32_16x16x32_bf16 v[14:17], v[140:143], v[208:211], v[14:17]
	v_mfma_f32_16x16x32_bf16 v[10:13], v[150:153], v[208:211], v[10:13]
	v_mfma_f32_16x16x32_bf16 v[62:65], v[146:149], v[162:165], v[62:65]
	v_mfma_f32_16x16x32_bf16 v[58:61], v[154:157], v[162:165], v[58:61]
	v_mfma_f32_16x16x32_bf16 v[46:49], v[146:149], v[170:173], v[46:49]
	v_mfma_f32_16x16x32_bf16 v[42:45], v[154:157], v[170:173], v[42:45]
	v_mfma_f32_16x16x32_bf16 v[30:33], v[146:149], v[204:207], v[30:33]
	v_mfma_f32_16x16x32_bf16 v[26:29], v[154:157], v[204:207], v[26:29]
	v_mfma_f32_16x16x32_bf16 v[14:17], v[146:149], v[212:215], v[14:17]
	v_mfma_f32_16x16x32_bf16 v[10:13], v[154:157], v[212:215], v[10:13]
	s_setprio 0
	s_barrier
; #define PG8_STAGE(bufoff, gbase, voff) do { _Pragma("unroll") for (int _i = 0; _i < 2; ++_i) \
;     __builtin_amdgcn_global_load_lds((const unsigned*)((const char*)(gbase) + (voff)[_i]), (PG8_LAS unsigned*)(lds + (bufoff) + ldsw + _i * 8192), 16, 0, 0); } while (0)
; #define PG8_LDA(dst, b, h) do { _Pragma("unroll") for (int m = 0; m < 4; ++m) _Pragma("unroll") for (int k = 0; k < 2; ++k) dst[m][k] = *(const PG8_LAS bf16x8*)(lds + PG8_SA(b, h) + aoff + m * 2048 + k * 1024); } while (0)
; #define PG8_LDB(dst, b, h) do { _Pragma("unroll") for (int n = 0; n < 2; ++n) _Pragma("unroll") for (int k = 0; k < 2; ++k) dst[n][k] = *(const PG8_LAS bf16x8*)(lds + PG8_SB(b, h) + boff + n * 2048 + k * 1024); } while (0)
; #define PG8_MMA(ai, bj, At, Bt) do { __builtin_amdgcn_s_setprio(1); _Pragma("unroll") for (int m = 0; m < 4; ++m) _Pragma("unroll") for (int n = 0; n < 2; ++n) _Pragma("unroll") for (int k = 0; k < 2; ++k) \
;     acc[ai][bj][m][n] = __builtin_amdgcn_mfma_f32_16x16x32_bf16(Bt[n][k], At[m][k], acc[ai][bj][m][n], 0, 0, 0); __builtin_amdgcn_s_setprio(0); } while (0)
; #define PG8_WAIT_V(n) asm volatile("s_waitcnt vmcnt(" #n ")" ::: "memory")
; #define PG8_WAIT_L(n) asm volatile("s_waitcnt lgkmcnt(" #n ")" ::: "memory")
; #define PG8_BAR __builtin_amdgcn_s_barrier()
; #define PG8_SCHED __builtin_amdgcn_sched_barrier(0)
; template <class Epi, class Sched>
; __device__ __forceinline__ void gemm_phase(PG8_LAS unsigned char* lds, const int lda, const int ldb, const Sched& S, const Epi& E) {
;     ...
;       PG8_STAGE(PG8_SB(0, 1), b2 + hstepB, voffB);
;       PG8_WAIT_V(6); PG8_BAR; PG8_MMA(1, 1, At, B1); PG8_BAR;
;       PG8_LDB(B0, 1, 0); PG8_SCHED; PG8_LDA(At, 1, 0); PG8_STAGE(PG8_SA(0, 1), a2 + hstepA, voffA);
;       PG8_WAIT_L(8); PG8_BAR; PG8_WAIT_L(0); PG8_MMA(0, 0, At, B0); PG8_BAR; PG8_SCHED;
;       PG8_LDB(B1, 1, 1); PG8_STAGE(PG8_SB(1, 0), b3, voffB);
;       PG8_BAR; PG8_WAIT_L(0); PG8_MMA(0, 1, At, B1); PG8_BAR;
	s_add_u32 s18, s22, 0x40000
	s_addc_u32 s19, s23, 0
	s_add_i32 s33, s55, s34
	v_lshl_add_u64 v[140:141], s[18:19], 0, v[134:135]
	s_mov_b32 m0, s33
	s_nop 0
	global_load_lds_dwordx4 v[140:141], off
	v_lshl_add_u64 v[140:141], s[18:19], 0, v[132:133]
	s_add_i32 m0, s33, 0x2000
	s_nop 0
	global_load_lds_dwordx4 v[140:141], off
	s_waitcnt vmcnt(6)
	s_barrier
	s_setprio 1
	v_mfma_f32_16x16x32_bf16 v[54:57], v[216:219], v[158:161], v[54:57]
	v_mfma_f32_16x16x32_bf16 v[50:53], v[224:227], v[158:161], v[50:53]
	v_mfma_f32_16x16x32_bf16 v[38:41], v[216:219], v[166:169], v[38:41]
	v_mfma_f32_16x16x32_bf16 v[34:37], v[224:227], v[166:169], v[34:37]
	v_mfma_f32_16x16x32_bf16 v[22:25], v[216:219], v[200:203], v[22:25]
	v_mfma_f32_16x16x32_bf16 v[18:21], v[224:227], v[200:203], v[18:21]
	v_mfma_f32_16x16x32_bf16 v[6:9], v[216:219], v[208:211], v[6:9]
	v_mfma_f32_16x16x32_bf16 v[2:5], v[224:227], v[208:211], v[2:5]
	v_mfma_f32_16x16x32_bf16 v[54:57], v[220:223], v[162:165], v[54:57]
	v_mfma_f32_16x16x32_bf16 v[50:53], v[228:231], v[162:165], v[50:53]
	v_mfma_f32_16x16x32_bf16 v[38:41], v[220:223], v[170:173], v[38:41]
	v_mfma_f32_16x16x32_bf16 v[34:37], v[228:231], v[170:173], v[34:37]
	v_mfma_f32_16x16x32_bf16 v[22:25], v[220:223], v[204:207], v[22:25]
	v_mfma_f32_16x16x32_bf16 v[18:21], v[228:231], v[204:207], v[18:21]
	v_mfma_f32_16x16x32_bf16 v[6:9], v[220:223], v[212:215], v[6:9]
	v_mfma_f32_16x16x32_bf16 v[2:5], v[228:231], v[212:215], v[2:5]
	s_setprio 0
	s_add_i32 s33, 0, 0x18000
	v_add_u32_e32 v154, s33, v131
	s_barrier
	ds_read_b128 v[140:143], v154
	ds_read_b128 v[146:149], v154 offset:1024
	ds_read_b128 v[150:153], v154 offset:2048
	ds_read_b128 v[154:157], v154 offset:3072
	s_add_u32 s18, s24, 0x40000
	s_addc_u32 s19, s25, 0
	s_mov_b32 m0, s38
	v_lshl_add_u64 v[216:217], s[18:19], 0, v[134:135]
	ds_read_b128 v[158:161], v145 offset:32768
	ds_read_b128 v[162:165], v145 offset:33792
	ds_read_b128 v[166:169], v145 offset:34816
	ds_read_b128 v[170:173], v145 offset:35840
	ds_read_b128 v[200:203], v145 offset:36864
	ds_read_b128 v[204:207], v145 offset:37888
	ds_read_b128 v[208:211], v145 offset:38912
	ds_read_b128 v[212:215], v145 offset:39936
	global_load_lds_dwordx4 v[216:217], off
	v_lshl_add_u64 v[216:217], s[18:19], 0, v[132:133]
	s_mov_b32 m0, s39
	s_nop 0
	global_load_lds_dwordx4 v[216:217], off
	s_waitcnt lgkmcnt(8)
	s_barrier
	s_waitcnt lgkmcnt(0)
	s_setprio 1
	v_mfma_f32_16x16x32_bf16 v[126:129], v[140:143], v[158:161], v[126:129]
	v_mfma_f32_16x16x32_bf16 v[122:125], v[150:153], v[158:161], v[122:125]
	v_mfma_f32_16x16x32_bf16 v[110:113], v[140:143], v[166:169], v[110:113]
	v_mfma_f32_16x16x32_bf16 v[106:109], v[150:153], v[166:169], v[106:109]
	v_mfma_f32_16x16x32_bf16 v[94:97], v[140:143], v[200:203], v[94:97]
	v_mfma_f32_16x16x32_bf16 v[90:93], v[150:153], v[200:203], v[90:93]
	v_mfma_f32_16x16x32_bf16 v[78:81], v[140:143], v[208:211], v[78:81]
	v_mfma_f32_16x16x32_bf16 v[74:77], v[150:153], v[208:211], v[74:77]
	v_mfma_f32_16x16x32_bf16 v[126:129], v[146:149], v[162:165], v[126:129]
	v_mfma_f32_16x16x32_bf16 v[122:125], v[154:157], v[162:165], v[122:125]
	v_mfma_f32_16x16x32_bf16 v[110:113], v[146:149], v[170:173], v[110:113]
	v_mfma_f32_16x16x32_bf16 v[106:109], v[154:157], v[170:173], v[106:109]
	v_mfma_f32_16x16x32_bf16 v[94:97], v[146:149], v[204:207], v[94:97]
	v_mfma_f32_16x16x32_bf16 v[90:93], v[154:157], v[204:207], v[90:93]
	v_mfma_f32_16x16x32_bf16 v[78:81], v[146:149], v[212:215], v[78:81]
	v_mfma_f32_16x16x32_bf16 v[74:77], v[154:157], v[212:215], v[74:77]
	s_setprio 0
	s_barrier
	s_add_i32 s24, 0, 0x1c000
	s_add_i32 s18, s33, s34
	v_add_u32_e32 v228, s24, v131
	v_lshl_add_u64 v[174:175], v[174:175], 0, s[86:87]
	s_mov_b32 m0, s18
	ds_read_b128 v[216:219], v228
	ds_read_b128 v[220:223], v228 offset:1024
	ds_read_b128 v[224:227], v228 offset:2048
	ds_read_b128 v[228:231], v228 offset:3072
	global_load_lds_dwordx4 v[174:175], off
	v_lshl_add_u64 v[174:175], v[182:183], 0, s[86:87]
	s_add_i32 m0, s18, 0x2000
	s_nop 0
	global_load_lds_dwordx4 v[174:175], off
	s_waitcnt lgkmcnt(0)
	s_barrier
; #define PG8_STAGE(bufoff, gbase, voff) do { _Pragma("unroll") for (int _i = 0; _i < 2; ++_i) \
;     __builtin_amdgcn_global_load_lds((const unsigned*)((const char*)(gbase) + (voff)[_i]), (PG8_LAS unsigned*)(lds + (bufoff) + ldsw + _i * 8192), 16, 0, 0); } while (0)
; #define PG8_LDA(dst, b, h) do { _Pragma("unroll") for (int m = 0; m < 4; ++m) _Pragma("unroll") for (int k = 0; k < 2; ++k) dst[m][k] = *(const PG8_LAS bf16x8*)(lds + PG8_SA(b, h) + aoff + m * 2048 + k * 1024); } while (0)
; #define PG8_MMA(ai, bj, At, Bt) do { __builtin_amdgcn_s_setprio(1); _Pragma("unroll") for (int m = 0; m < 4; ++m) _Pragma("unroll") for (int n = 0; n < 2; ++n) _Pragma("unroll") for (int k = 0; k < 2; ++k) \
;     acc[ai][bj][m][n] = __builtin_amdgcn_mfma_f32_16x16x32_bf16(Bt[n][k], At[m][k], acc[ai][bj][m][n], 0, 0, 0); __builtin_amdgcn_s_setprio(0); } while (0)
; #define PG8_WAIT_V(n) asm volatile("s_waitcnt vmcnt(" #n ")" ::: "memory")
; #define PG8_WAIT_L(n) asm volatile("s_waitcnt lgkmcnt(" #n ")" ::: "memory")
; #define PG8_BAR __builtin_amdgcn_s_barrier()
; #define PG8_SCHED __builtin_amdgcn_sched_barrier(0)
; template <class Epi, class Sched>
; __device__ __forceinline__ void gemm_phase(PG8_LAS unsigned char* lds, const int lda, const int ldb, const Sched& S, const Epi& E) {
;     ...
;       PG8_BAR; PG8_WAIT_L(0); PG8_MMA(0, 1, At, B1); PG8_BAR;
;       PG8_LDA(At, 1, 1); PG8_STAGE(PG8_SA(1, 0), a3, voffA);
;       PG8_BAR; PG8_WAIT_L(0); PG8_MMA(1, 0, At, B0); PG8_BAR; PG8_SCHED;
;       PG8_STAGE(PG8_SB(1, 1), b3 + hstepB, voffB);
;       PG8_WAIT_V(6); PG8_BAR; PG8_MMA(1, 1, At, B1); PG8_BAR;
;     }
;   __device__ __forceinline__ void operator()(const f32x4 (&acc)[2][2][4][2], const Unit& u, int wr, int wc, int fr, int fq) const {
;     const int mr = (u.pm * 256 < ML) ? ((u.pm * 256) >> 11) : 32;
;     const float* gp = mod + (size_t)mr * 6144 + gate_off;
	s_setprio 1
	v_mfma_f32_16x16x32_bf16 v[118:121], v[216:219], v[158:161], v[118:121]
	v_mfma_f32_16x16x32_bf16 v[114:117], v[224:227], v[158:161], v[114:117]
	v_mfma_f32_16x16x32_bf16 v[102:105], v[216:219], v[166:169], v[102:105]
	v_mfma_f32_16x16x32_bf16 v[98:101], v[224:227], v[166:169], v[98:101]
	v_mfma_f32_16x16x32_bf16 v[86:89], v[216:219], v[200:203], v[86:89]
	v_mfma_f32_16x16x32_bf16 v[82:85], v[224:227], v[200:203], v[82:85]
	v_mfma_f32_16x16x32_bf16 v[70:73], v[216:219], v[208:211], v[70:73]
	v_mfma_f32_16x16x32_bf16 v[66:69], v[224:227], v[208:211], v[66:69]
	v_mfma_f32_16x16x32_bf16 v[118:121], v[220:223], v[162:165], v[118:121]
	v_mfma_f32_16x16x32_bf16 v[114:117], v[228:231], v[162:165], v[114:117]
	v_mfma_f32_16x16x32_bf16 v[102:105], v[220:223], v[170:173], v[102:105]
	v_mfma_f32_16x16x32_bf16 v[98:101], v[228:231], v[170:173], v[98:101]
	v_mfma_f32_16x16x32_bf16 v[86:89], v[220:223], v[204:207], v[86:89]
	v_mfma_f32_16x16x32_bf16 v[82:85], v[228:231], v[204:207], v[82:85]
	v_mfma_f32_16x16x32_bf16 v[70:73], v[220:223], v[212:215], v[70:73]
	v_mfma_f32_16x16x32_bf16 v[66:69], v[228:231], v[212:215], v[66:69]
	s_setprio 0
	s_mov_b32 m0, s44
	v_lshl_add_u64 v[174:175], v[184:185], 0, s[86:87]
	s_barrier
	ds_read_b128 v[158:161], v145 offset:49152
	ds_read_b128 v[162:165], v145 offset:50176
	ds_read_b128 v[166:169], v145 offset:51200
	ds_read_b128 v[170:173], v145 offset:52224
	ds_read_b128 v[200:203], v145 offset:53248
	ds_read_b128 v[204:207], v145 offset:54272
	ds_read_b128 v[208:211], v145 offset:55296
	ds_read_b128 v[212:215], v145 offset:56320
	global_load_lds_dwordx4 v[174:175], off
	v_lshl_add_u64 v[174:175], v[232:233], 0, s[86:87]
	s_mov_b32 m0, s45
	s_nop 0
	global_load_lds_dwordx4 v[174:175], off
	s_waitcnt lgkmcnt(0)
	s_barrier
	s_setprio 1
	v_mfma_f32_16x16x32_bf16 v[62:65], v[140:143], v[158:161], v[62:65]
	v_mfma_f32_16x16x32_bf16 v[58:61], v[150:153], v[158:161], v[58:61]
	v_mfma_f32_16x16x32_bf16 v[46:49], v[140:143], v[166:169], v[46:49]
	v_mfma_f32_16x16x32_bf16 v[42:45], v[150:153], v[166:169], v[42:45]
	v_mfma_f32_16x16x32_bf16 v[30:33], v[140:143], v[200:203], v[30:33]
	v_mfma_f32_16x16x32_bf16 v[26:29], v[150:153], v[200:203], v[26:29]
	v_mfma_f32_16x16x32_bf16 v[14:17], v[140:143], v[208:211], v[14:17]
	v_mfma_f32_16x16x32_bf16 v[10:13], v[150:153], v[208:211], v[10:13]
	v_mfma_f32_16x16x32_bf16 v[62:65], v[146:149], v[162:165], v[62:65]
	v_mfma_f32_16x16x32_bf16 v[58:61], v[154:157], v[162:165], v[58:61]
	v_mfma_f32_16x16x32_bf16 v[46:49], v[146:149], v[170:173], v[46:49]
	v_mfma_f32_16x16x32_bf16 v[42:45], v[154:157], v[170:173], v[42:45]
	v_mfma_f32_16x16x32_bf16 v[30:33], v[146:149], v[204:207], v[30:33]
	v_mfma_f32_16x16x32_bf16 v[26:29], v[154:157], v[204:207], v[26:29]
	v_mfma_f32_16x16x32_bf16 v[14:17], v[146:149], v[212:215], v[14:17]
	v_mfma_f32_16x16x32_bf16 v[10:13], v[154:157], v[212:215], v[10:13]
	s_setprio 0
	s_barrier
	s_add_u32 s18, s22, 0x40080
	s_addc_u32 s19, s23, 0
	s_add_i32 s22, s24, s34
	v_lshl_add_u64 v[140:141], s[18:19], 0, v[134:135]
	s_mov_b32 m0, s22
	s_nop 0
	global_load_lds_dwordx4 v[140:141], off
	v_lshl_add_u64 v[140:141], s[18:19], 0, v[132:133]
	s_add_i32 m0, s22, 0x2000
	s_nop 0
	global_load_lds_dwordx4 v[140:141], off
	s_waitcnt vmcnt(6)
	s_barrier
	s_setprio 1
	v_mfma_f32_16x16x32_bf16 v[54:57], v[216:219], v[158:161], v[54:57]
	v_mfma_f32_16x16x32_bf16 v[50:53], v[224:227], v[158:161], v[50:53]
	v_mfma_f32_16x16x32_bf16 v[38:41], v[216:219], v[166:169], v[38:41]
	v_mfma_f32_16x16x32_bf16 v[34:37], v[224:227], v[166:169], v[34:37]
	v_mfma_f32_16x16x32_bf16 v[22:25], v[216:219], v[200:203], v[22:25]
	v_mfma_f32_16x16x32_bf16 v[18:21], v[224:227], v[200:203], v[18:21]
	v_mfma_f32_16x16x32_bf16 v[6:9], v[216:219], v[208:211], v[6:9]
	v_mfma_f32_16x16x32_bf16 v[2:5], v[224:227], v[208:211], v[2:5]
	v_mfma_f32_16x16x32_bf16 v[54:57], v[220:223], v[162:165], v[54:57]
	v_mfma_f32_16x16x32_bf16 v[50:53], v[228:231], v[162:165], v[50:53]
	v_mfma_f32_16x16x32_bf16 v[38:41], v[220:223], v[170:173], v[38:41]
	v_mfma_f32_16x16x32_bf16 v[34:37], v[228:231], v[170:173], v[34:37]
	v_mfma_f32_16x16x32_bf16 v[22:25], v[220:223], v[204:207], v[22:25]
	v_mfma_f32_16x16x32_bf16 v[18:21], v[228:231], v[204:207], v[18:21]
	v_mfma_f32_16x16x32_bf16 v[6:9], v[220:223], v[212:215], v[6:9]
	v_mfma_f32_16x16x32_bf16 v[2:5], v[228:231], v[212:215], v[2:5]
	s_setprio 0
	s_add_i32 s54, s54, 2
	s_add_u32 s52, s52, 0x100
	s_addc_u32 s53, s53, 0
	s_cmp_gt_u32 s54, 13
	s_mov_b64 s[18:19], s[20:21]
	s_barrier
	s_cbranch_scc0 .LBB0_1482
	s_cmpk_gt_i32 s16, 0xff
	s_mov_b64 s[18:19], 0x30000
	s_cbranch_scc1 .LBB0_1478
	s_ashr_i32 s1, s16, 3
	s_mul_hi_i32 s19, s1, 0x1800
	s_mul_i32 s18, s1, 0x1800
	s_branch .LBB0_1478

; #define PG8_STAGE(bufoff, gbase, voff) do { _Pragma("unroll") for (int _i = 0; _i < 2; ++_i) \
;     __builtin_amdgcn_global_load_lds((const unsigned*)((const char*)(gbase) + (voff)[_i]), (PG8_LAS unsigned*)(lds + (bufoff) + ldsw + _i * 8192), 16, 0, 0); } while (0)
; #define PG8_LDA(dst, b, h) do { _Pragma("unroll") for (int m = 0; m < 4; ++m) _Pragma("unroll") for (int k = 0; k < 2; ++k) dst[m][k] = *(const PG8_LAS bf16x8*)(lds + PG8_SA(b, h) + aoff + m * 2048 + k * 1024); } while (0)
; #define PG8_LDB(dst, b, h) do { _Pragma("unroll") for (int n = 0; n < 2; ++n) _Pragma("unroll") for (int k = 0; k < 2; ++k) dst[n][k] = *(const PG8_LAS bf16x8*)(lds + PG8_SB(b, h) + boff + n * 2048 + k * 1024); } while (0)
; #define PG8_MMA(ai, bj, At, Bt) do { __builtin_amdgcn_s_setprio(1); _Pragma("unroll") for (int m = 0; m < 4; ++m) _Pragma("unroll") for (int n = 0; n < 2; ++n) _Pragma("unroll") for (int k = 0; k < 2; ++k) \
;     acc[ai][bj][m][n] = __builtin_amdgcn_mfma_f32_16x16x32_bf16(Bt[n][k], At[m][k], acc[ai][bj][m][n], 0, 0, 0); __builtin_amdgcn_s_setprio(0); } while (0)
; #define PG8_WAIT_L(n) asm volatile("s_waitcnt lgkmcnt(" #n ")" ::: "memory")
; #define PG8_BAR __builtin_amdgcn_s_barrier()
; #define PG8_SCHED __builtin_amdgcn_sched_barrier(0)
; template <class Epi, class Sched>
; __device__ __forceinline__ void gemm_phase(PG8_LAS unsigned char* lds, const int lda, const int ldb, const Sched& S, const Epi& E) {
;     ...
;     for (int t = 0; t < nt; t += 2) {
;       const bool last = (t == nt - 2);
;       const char* a1 = cA + (size_t)(t + 1) * kstep;
;       const char* a2 = last ? nA : cA + (size_t)(t + 2) * kstep; const char* b2 = last ? nB : cB + (size_t)(t + 2) * kstep;
;       const char* a3 = a2 + kstep; const char* b3 = b2 + kstep;
;       PG8_LDB(B0, 0, 0); PG8_SCHED; PG8_LDA(At, 0, 0); PG8_STAGE(PG8_SA(1, 1), a1 + hstepA, voffA);
;       PG8_WAIT_L(8); PG8_BAR; PG8_WAIT_L(0); PG8_MMA(0, 0, At, B0); PG8_BAR; PG8_SCHED;
;       PG8_LDB(B1, 0, 1); PG8_STAGE(PG8_SB(0, 0), b2, voffB);
;       PG8_BAR; PG8_WAIT_L(0); PG8_MMA(0, 1, At, B1); PG8_BAR;
;       PG8_LDA(At, 0, 1); PG8_STAGE(PG8_SA(0, 0), a2, voffA);
;       PG8_BAR; PG8_WAIT_L(0); PG8_MMA(1, 0, At, B0); PG8_BAR; PG8_SCHED;
.LBB0_1604:
	s_add_u32 s20, s18, 0xfffc0080
	s_addc_u32 s21, s19, -1
	s_add_i32 s33, 0, 0x10000
	v_add_u32_e32 v154, s33, v131
	ds_read_b128 v[142:145], v154
	ds_read_b128 v[146:149], v154 offset:1024
	ds_read_b128 v[150:153], v154 offset:2048
	ds_read_b128 v[154:157], v154 offset:3072
	s_cmp_eq_u32 s46, 12
	s_cselect_b32 s23, s11, s21
	s_cselect_b32 s22, s42, s20
	s_cselect_b32 s21, s1, s45
	s_cselect_b32 s20, s43, s44
	v_lshl_add_u64 v[174:175], s[18:19], 0, v[136:137]
	s_add_i32 m0, s17, 0xc000
	ds_read_b128 v[158:161], v141
	ds_read_b128 v[162:165], v141 offset:1024
	ds_read_b128 v[166:169], v141 offset:2048
	ds_read_b128 v[170:173], v141 offset:3072
	ds_read_b128 v[200:203], v141 offset:4096
	ds_read_b128 v[204:207], v141 offset:5120
	ds_read_b128 v[208:211], v141 offset:6144
	ds_read_b128 v[212:215], v141 offset:7168
	global_load_lds_dwordx4 v[174:175], off
	v_lshl_add_u64 v[174:175], s[18:19], 0, v[138:139]
	s_add_i32 m0, s17, 0xe000
	s_nop 0
	global_load_lds_dwordx4 v[174:175], off
	s_waitcnt lgkmcnt(8)
	s_barrier
	s_waitcnt lgkmcnt(0)
	s_setprio 1
	v_mfma_f32_16x16x32_bf16 v[126:129], v[142:145], v[158:161], v[126:129]
	v_mfma_f32_16x16x32_bf16 v[118:121], v[150:153], v[158:161], v[118:121]
	v_mfma_f32_16x16x32_bf16 v[110:113], v[142:145], v[166:169], v[110:113]
	v_mfma_f32_16x16x32_bf16 v[102:105], v[150:153], v[166:169], v[102:105]
	v_mfma_f32_16x16x32_bf16 v[94:97], v[142:145], v[200:203], v[94:97]
	v_mfma_f32_16x16x32_bf16 v[86:89], v[150:153], v[200:203], v[86:89]
	v_mfma_f32_16x16x32_bf16 v[78:81], v[142:145], v[208:211], v[78:81]
	v_mfma_f32_16x16x32_bf16 v[70:73], v[150:153], v[208:211], v[70:73]
	v_mfma_f32_16x16x32_bf16 v[126:129], v[146:149], v[162:165], v[126:129]
	v_mfma_f32_16x16x32_bf16 v[118:121], v[154:157], v[162:165], v[118:121]
	v_mfma_f32_16x16x32_bf16 v[110:113], v[146:149], v[170:173], v[110:113]
	v_mfma_f32_16x16x32_bf16 v[102:105], v[154:157], v[170:173], v[102:105]
	v_mfma_f32_16x16x32_bf16 v[94:97], v[146:149], v[204:207], v[94:97]
	v_mfma_f32_16x16x32_bf16 v[86:89], v[154:157], v[204:207], v[86:89]
	v_mfma_f32_16x16x32_bf16 v[78:81], v[146:149], v[212:215], v[78:81]
	v_mfma_f32_16x16x32_bf16 v[70:73], v[154:157], v[212:215], v[70:73]
	s_setprio 0
	s_barrier
	s_add_i32 s47, 0, 0x14000
	v_add_u32_e32 v174, s47, v131
	s_add_i32 s33, s33, s30
	ds_read_b128 v[216:219], v174
	ds_read_b128 v[220:223], v174 offset:1024
	ds_read_b128 v[224:227], v174 offset:2048
	ds_read_b128 v[228:231], v174 offset:3072
	v_lshl_add_u64 v[174:175], s[20:21], 0, v[134:135]
	s_mov_b32 m0, s33
	v_lshl_add_u64 v[182:183], s[20:21], 0, v[132:133]
	global_load_lds_dwordx4 v[174:175], off
	s_add_i32 m0, s33, 0x2000
	s_nop 0
	global_load_lds_dwordx4 v[182:183], off
	s_waitcnt lgkmcnt(0)
	s_barrier
	s_setprio 1
	v_mfma_f32_16x16x32_bf16 v[122:125], v[216:219], v[158:161], v[122:125]
	v_mfma_f32_16x16x32_bf16 v[114:117], v[224:227], v[158:161], v[114:117]
	v_mfma_f32_16x16x32_bf16 v[106:109], v[216:219], v[166:169], v[106:109]
	v_mfma_f32_16x16x32_bf16 v[98:101], v[224:227], v[166:169], v[98:101]
	v_mfma_f32_16x16x32_bf16 v[90:93], v[216:219], v[200:203], v[90:93]
	v_mfma_f32_16x16x32_bf16 v[82:85], v[224:227], v[200:203], v[82:85]
	v_mfma_f32_16x16x32_bf16 v[74:77], v[216:219], v[208:211], v[74:77]
	v_mfma_f32_16x16x32_bf16 v[66:69], v[224:227], v[208:211], v[66:69]
	v_mfma_f32_16x16x32_bf16 v[122:125], v[220:223], v[162:165], v[122:125]
	v_mfma_f32_16x16x32_bf16 v[114:117], v[228:231], v[162:165], v[114:117]
	v_mfma_f32_16x16x32_bf16 v[106:109], v[220:223], v[170:173], v[106:109]
	v_mfma_f32_16x16x32_bf16 v[98:101], v[228:231], v[170:173], v[98:101]
	v_mfma_f32_16x16x32_bf16 v[90:93], v[220:223], v[204:207], v[90:93]
	v_mfma_f32_16x16x32_bf16 v[82:85], v[228:231], v[204:207], v[82:85]
	v_mfma_f32_16x16x32_bf16 v[74:77], v[220:223], v[212:215], v[74:77]
	v_mfma_f32_16x16x32_bf16 v[66:69], v[228:231], v[212:215], v[66:69]
	s_setprio 0
	s_mov_b32 m0, s17
	v_lshl_add_u64 v[184:185], s[22:23], 0, v[134:135]
	s_barrier
	ds_read_b128 v[158:161], v141 offset:16384
	ds_read_b128 v[162:165], v141 offset:17408
	ds_read_b128 v[166:169], v141 offset:18432
	ds_read_b128 v[170:173], v141 offset:19456
	ds_read_b128 v[200:203], v141 offset:20480
	ds_read_b128 v[204:207], v141 offset:21504
	ds_read_b128 v[208:211], v141 offset:22528
	ds_read_b128 v[212:215], v141 offset:23552
	global_load_lds_dwordx4 v[184:185], off
	v_lshl_add_u64 v[232:233], s[22:23], 0, v[132:133]
	s_mov_b32 m0, s35
	s_nop 0
	global_load_lds_dwordx4 v[232:233], off
	s_waitcnt lgkmcnt(0)
	s_barrier
	s_setprio 1
	v_mfma_f32_16x16x32_bf16 v[62:65], v[142:145], v[158:161], v[62:65]
	v_mfma_f32_16x16x32_bf16 v[54:57], v[150:153], v[158:161], v[54:57]
	v_mfma_f32_16x16x32_bf16 v[46:49], v[142:145], v[166:169], v[46:49]
	v_mfma_f32_16x16x32_bf16 v[38:41], v[150:153], v[166:169], v[38:41]
	v_mfma_f32_16x16x32_bf16 v[30:33], v[142:145], v[200:203], v[30:33]
	v_mfma_f32_16x16x32_bf16 v[22:25], v[150:153], v[200:203], v[22:25]
	v_mfma_f32_16x16x32_bf16 v[14:17], v[142:145], v[208:211], v[14:17]
	v_mfma_f32_16x16x32_bf16 v[6:9], v[150:153], v[208:211], v[6:9]
	v_mfma_f32_16x16x32_bf16 v[62:65], v[146:149], v[162:165], v[62:65]
	v_mfma_f32_16x16x32_bf16 v[54:57], v[154:157], v[162:165], v[54:57]
	v_mfma_f32_16x16x32_bf16 v[46:49], v[146:149], v[170:173], v[46:49]
	v_mfma_f32_16x16x32_bf16 v[38:41], v[154:157], v[170:173], v[38:41]
	v_mfma_f32_16x16x32_bf16 v[30:33], v[146:149], v[204:207], v[30:33]
	v_mfma_f32_16x16x32_bf16 v[22:25], v[154:157], v[204:207], v[22:25]
	v_mfma_f32_16x16x32_bf16 v[14:17], v[146:149], v[212:215], v[14:17]
	v_mfma_f32_16x16x32_bf16 v[6:9], v[154:157], v[212:215], v[6:9]
	s_setprio 0
	s_barrier
; #define PG8_STAGE(bufoff, gbase, voff) do { _Pragma("unroll") for (int _i = 0; _i < 2; ++_i) \
;     __builtin_amdgcn_global_load_lds((const unsigned*)((const char*)(gbase) + (voff)[_i]), (PG8_LAS unsigned*)(lds + (bufoff) + ldsw + _i * 8192), 16, 0, 0); } while (0)
; #define PG8_LDA(dst, b, h) do { _Pragma("unroll") for (int m = 0; m < 4; ++m) _Pragma("unroll") for (int k = 0; k < 2; ++k) dst[m][k] = *(const PG8_LAS bf16x8*)(lds + PG8_SA(b, h) + aoff + m * 2048 + k * 1024); } while (0)
; #define PG8_LDB(dst, b, h) do { _Pragma("unroll") for (int n = 0; n < 2; ++n) _Pragma("unroll") for (int k = 0; k < 2; ++k) dst[n][k] = *(const PG8_LAS bf16x8*)(lds + PG8_SB(b, h) + boff + n * 2048 + k * 1024); } while (0)
; #define PG8_MMA(ai, bj, At, Bt) do { __builtin_amdgcn_s_setprio(1); _Pragma("unroll") for (int m = 0; m < 4; ++m) _Pragma("unroll") for (int n = 0; n < 2; ++n) _Pragma("unroll") for (int k = 0; k < 2; ++k) \
;     acc[ai][bj][m][n] = __builtin_amdgcn_mfma_f32_16x16x32_bf16(Bt[n][k], At[m][k], acc[ai][bj][m][n], 0, 0, 0); __builtin_amdgcn_s_setprio(0); } while (0)
; #define PG8_WAIT_V(n) asm volatile("s_waitcnt vmcnt(" #n ")" ::: "memory")
; #define PG8_WAIT_L(n) asm volatile("s_waitcnt lgkmcnt(" #n ")" ::: "memory")
; #define PG8_BAR __builtin_amdgcn_s_barrier()
; #define PG8_SCHED __builtin_amdgcn_sched_barrier(0)
; template <class Epi, class Sched>
; __device__ __forceinline__ void gemm_phase(PG8_LAS unsigned char* lds, const int lda, const int ldb, const Sched& S, const Epi& E) {
;     ...
;       PG8_STAGE(PG8_SB(0, 1), b2 + hstepB, voffB);
;       PG8_WAIT_V(6); PG8_BAR; PG8_MMA(1, 1, At, B1); PG8_BAR;
;       PG8_LDB(B0, 1, 0); PG8_SCHED; PG8_LDA(At, 1, 0); PG8_STAGE(PG8_SA(0, 1), a2 + hstepA, voffA);
;       PG8_WAIT_L(8); PG8_BAR; PG8_WAIT_L(0); PG8_MMA(0, 0, At, B0); PG8_BAR; PG8_SCHED;
;       PG8_LDB(B1, 1, 1); PG8_STAGE(PG8_SB(1, 0), b3, voffB);
;       PG8_BAR; PG8_WAIT_L(0); PG8_MMA(0, 1, At, B1); PG8_BAR;
;       PG8_LDA(At, 1, 1); PG8_STAGE(PG8_SA(1, 0), a3, voffA);
	s_add_u32 s48, s20, 0x40000
	s_addc_u32 s49, s21, 0
	s_add_i32 s33, s47, s30
	v_lshl_add_u64 v[142:143], s[48:49], 0, v[134:135]
	s_mov_b32 m0, s33
	s_nop 0
	global_load_lds_dwordx4 v[142:143], off
	v_lshl_add_u64 v[142:143], s[48:49], 0, v[132:133]
	s_add_i32 m0, s33, 0x2000
	s_nop 0
	global_load_lds_dwordx4 v[142:143], off
	s_waitcnt vmcnt(6)
	s_barrier
	s_setprio 1
	v_mfma_f32_16x16x32_bf16 v[58:61], v[216:219], v[158:161], v[58:61]
	v_mfma_f32_16x16x32_bf16 v[50:53], v[224:227], v[158:161], v[50:53]
	v_mfma_f32_16x16x32_bf16 v[42:45], v[216:219], v[166:169], v[42:45]
	v_mfma_f32_16x16x32_bf16 v[34:37], v[224:227], v[166:169], v[34:37]
	v_mfma_f32_16x16x32_bf16 v[26:29], v[216:219], v[200:203], v[26:29]
	v_mfma_f32_16x16x32_bf16 v[18:21], v[224:227], v[200:203], v[18:21]
	v_mfma_f32_16x16x32_bf16 v[10:13], v[216:219], v[208:211], v[10:13]
	v_mfma_f32_16x16x32_bf16 v[2:5], v[224:227], v[208:211], v[2:5]
	v_mfma_f32_16x16x32_bf16 v[58:61], v[220:223], v[162:165], v[58:61]
	v_mfma_f32_16x16x32_bf16 v[50:53], v[228:231], v[162:165], v[50:53]
	v_mfma_f32_16x16x32_bf16 v[42:45], v[220:223], v[170:173], v[42:45]
	v_mfma_f32_16x16x32_bf16 v[34:37], v[228:231], v[170:173], v[34:37]
	v_mfma_f32_16x16x32_bf16 v[26:29], v[220:223], v[204:207], v[26:29]
	v_mfma_f32_16x16x32_bf16 v[18:21], v[228:231], v[204:207], v[18:21]
	v_mfma_f32_16x16x32_bf16 v[10:13], v[220:223], v[212:215], v[10:13]
	v_mfma_f32_16x16x32_bf16 v[2:5], v[228:231], v[212:215], v[2:5]
	s_setprio 0
	s_add_i32 s33, 0, 0x18000
	v_add_u32_e32 v154, s33, v131
	s_barrier
	ds_read_b128 v[142:145], v154
	ds_read_b128 v[146:149], v154 offset:1024
	ds_read_b128 v[150:153], v154 offset:2048
	ds_read_b128 v[154:157], v154 offset:3072
	s_add_u32 s22, s22, 0x40000
	s_addc_u32 s23, s23, 0
	s_mov_b32 m0, s36
	v_lshl_add_u64 v[216:217], s[22:23], 0, v[134:135]
	ds_read_b128 v[158:161], v141 offset:32768
	ds_read_b128 v[162:165], v141 offset:33792
	ds_read_b128 v[166:169], v141 offset:34816
	ds_read_b128 v[170:173], v141 offset:35840
	ds_read_b128 v[200:203], v141 offset:36864
	ds_read_b128 v[204:207], v141 offset:37888
	ds_read_b128 v[208:211], v141 offset:38912
	ds_read_b128 v[212:215], v141 offset:39936
	global_load_lds_dwordx4 v[216:217], off
	v_lshl_add_u64 v[216:217], s[22:23], 0, v[132:133]
	s_mov_b32 m0, s37
	s_nop 0
	global_load_lds_dwordx4 v[216:217], off
	s_waitcnt lgkmcnt(8)
	s_barrier
	s_waitcnt lgkmcnt(0)
	s_setprio 1
	v_mfma_f32_16x16x32_bf16 v[126:129], v[142:145], v[158:161], v[126:129]
	v_mfma_f32_16x16x32_bf16 v[118:121], v[150:153], v[158:161], v[118:121]
	v_mfma_f32_16x16x32_bf16 v[110:113], v[142:145], v[166:169], v[110:113]
	v_mfma_f32_16x16x32_bf16 v[102:105], v[150:153], v[166:169], v[102:105]
	v_mfma_f32_16x16x32_bf16 v[94:97], v[142:145], v[200:203], v[94:97]
	v_mfma_f32_16x16x32_bf16 v[86:89], v[150:153], v[200:203], v[86:89]
	v_mfma_f32_16x16x32_bf16 v[78:81], v[142:145], v[208:211], v[78:81]
	v_mfma_f32_16x16x32_bf16 v[70:73], v[150:153], v[208:211], v[70:73]
	v_mfma_f32_16x16x32_bf16 v[126:129], v[146:149], v[162:165], v[126:129]
	v_mfma_f32_16x16x32_bf16 v[118:121], v[154:157], v[162:165], v[118:121]
	v_mfma_f32_16x16x32_bf16 v[110:113], v[146:149], v[170:173], v[110:113]
	v_mfma_f32_16x16x32_bf16 v[102:105], v[154:157], v[170:173], v[102:105]
	v_mfma_f32_16x16x32_bf16 v[94:97], v[146:149], v[204:207], v[94:97]
	v_mfma_f32_16x16x32_bf16 v[86:89], v[154:157], v[204:207], v[86:89]
	v_mfma_f32_16x16x32_bf16 v[78:81], v[146:149], v[212:215], v[78:81]
	v_mfma_f32_16x16x32_bf16 v[70:73], v[154:157], v[212:215], v[70:73]
	s_setprio 0
	s_barrier
	s_add_i32 s22, 0, 0x1c000
	s_add_i32 s23, s33, s30
	v_add_u32_e32 v228, s22, v131
	v_lshl_add_u64 v[174:175], v[174:175], 0, s[86:87]
	s_mov_b32 m0, s23
	ds_read_b128 v[216:219], v228
	ds_read_b128 v[220:223], v228 offset:1024
	ds_read_b128 v[224:227], v228 offset:2048
	ds_read_b128 v[228:231], v228 offset:3072
	global_load_lds_dwordx4 v[174:175], off
	v_lshl_add_u64 v[174:175], v[182:183], 0, s[86:87]
	s_add_i32 m0, s23, 0x2000
	s_nop 0
	global_load_lds_dwordx4 v[174:175], off
	s_waitcnt lgkmcnt(0)
	s_barrier
	s_setprio 1
	v_mfma_f32_16x16x32_bf16 v[122:125], v[216:219], v[158:161], v[122:125]
	v_mfma_f32_16x16x32_bf16 v[114:117], v[224:227], v[158:161], v[114:117]
	v_mfma_f32_16x16x32_bf16 v[106:109], v[216:219], v[166:169], v[106:109]
	v_mfma_f32_16x16x32_bf16 v[98:101], v[224:227], v[166:169], v[98:101]
	v_mfma_f32_16x16x32_bf16 v[90:93], v[216:219], v[200:203], v[90:93]
	v_mfma_f32_16x16x32_bf16 v[82:85], v[224:227], v[200:203], v[82:85]
	v_mfma_f32_16x16x32_bf16 v[74:77], v[216:219], v[208:211], v[74:77]
	v_mfma_f32_16x16x32_bf16 v[66:69], v[224:227], v[208:211], v[66:69]
	v_mfma_f32_16x16x32_bf16 v[122:125], v[220:223], v[162:165], v[122:125]
	v_mfma_f32_16x16x32_bf16 v[114:117], v[228:231], v[162:165], v[114:117]
	v_mfma_f32_16x16x32_bf16 v[106:109], v[220:223], v[170:173], v[106:109]
	v_mfma_f32_16x16x32_bf16 v[98:101], v[228:231], v[170:173], v[98:101]
	v_mfma_f32_16x16x32_bf16 v[90:93], v[220:223], v[204:207], v[90:93]
	v_mfma_f32_16x16x32_bf16 v[82:85], v[228:231], v[204:207], v[82:85]
	v_mfma_f32_16x16x32_bf16 v[74:77], v[220:223], v[212:215], v[74:77]
	v_mfma_f32_16x16x32_bf16 v[66:69], v[228:231], v[212:215], v[66:69]
	s_setprio 0
	s_mov_b32 m0, s38
	v_lshl_add_u64 v[174:175], v[184:185], 0, s[86:87]
	s_barrier
	ds_read_b128 v[158:161], v141 offset:49152
	ds_read_b128 v[162:165], v141 offset:50176
	ds_read_b128 v[166:169], v141 offset:51200
	ds_read_b128 v[170:173], v141 offset:52224
	ds_read_b128 v[200:203], v141 offset:53248
	ds_read_b128 v[204:207], v141 offset:54272
	ds_read_b128 v[208:211], v141 offset:55296
	ds_read_b128 v[212:215], v141 offset:56320
	global_load_lds_dwordx4 v[174:175], off
	v_lshl_add_u64 v[174:175], v[232:233], 0, s[86:87]
	s_mov_b32 m0, s39
	s_nop 0
	global_load_lds_dwordx4 v[174:175], off
	s_waitcnt lgkmcnt(0)
	s_barrier
; __device__ __forceinline__ float silu_f(float x) { return x * sigm(x); }
; #define PG8_STAGE(bufoff, gbase, voff) do { _Pragma("unroll") for (int _i = 0; _i < 2; ++_i) \
;     __builtin_amdgcn_global_load_lds((const unsigned*)((const char*)(gbase) + (voff)[_i]), (PG8_LAS unsigned*)(lds + (bufoff) + ldsw + _i * 8192), 16, 0, 0); } while (0)
; #define PG8_MMA(ai, bj, At, Bt) do { __builtin_amdgcn_s_setprio(1); _Pragma("unroll") for (int m = 0; m < 4; ++m) _Pragma("unroll") for (int n = 0; n < 2; ++n) _Pragma("unroll") for (int k = 0; k < 2; ++k) \
;     acc[ai][bj][m][n] = __builtin_amdgcn_mfma_f32_16x16x32_bf16(Bt[n][k], At[m][k], acc[ai][bj][m][n], 0, 0, 0); __builtin_amdgcn_s_setprio(0); } while (0)
; #define PG8_WAIT_V(n) asm volatile("s_waitcnt vmcnt(" #n ")" ::: "memory")
; #define PG8_WAIT_L(n) asm volatile("s_waitcnt lgkmcnt(" #n ")" ::: "memory")
; #define PG8_BAR __builtin_amdgcn_s_barrier()
; #define PG8_SCHED __builtin_amdgcn_sched_barrier(0)
; template <class Epi, class Sched>
; __device__ __forceinline__ void gemm_phase(PG8_LAS unsigned char* lds, const int lda, const int ldb, const Sched& S, const Epi& E) {
;     ...
;       PG8_BAR; PG8_WAIT_L(0); PG8_MMA(1, 0, At, B0); PG8_BAR; PG8_SCHED;
;       PG8_STAGE(PG8_SB(1, 1), b3 + hstepB, voffB);
;       PG8_WAIT_V(6); PG8_BAR; PG8_MMA(1, 1, At, B1); PG8_BAR;
;     }
;   __device__ __forceinline__ void operator()(const f32x4 (&acc)[2][2][4][2], const Unit& u, int wr, int wc, int fr, int fq) const {
; #pragma unroll
;     for (int ai = 0; ai < 2; ++ai)
; #pragma unroll
;       for (int m = 0; m < 4; ++m) {
;         const int r = u.pm * 256 + ai * 128 + wr * 64 + m * 16 + fr;
; #pragma unroll
;         for (int n = 0; n < 2; ++n) {
;           const f32x4 g = acc[ai][0][m][n], up = acc[ai][1][m][n];
;           const int c = u.pn * 128 + wc * 32 + n * 16 + 4 * fq;
;           uint2 w;
;           w.x = pack2(silu_f(g[0]) * up[0], silu_f(g[1]) * up[1]);
;           w.y = pack2(silu_f(g[2]) * up[2], silu_f(g[3]) * up[3]);
;           *reinterpret_cast<uint2*>(HID + (size_t)r * DFF + c) = w;
;         }
;       }
	s_setprio 1
	v_mfma_f32_16x16x32_bf16 v[62:65], v[142:145], v[158:161], v[62:65]
	v_mfma_f32_16x16x32_bf16 v[54:57], v[150:153], v[158:161], v[54:57]
	v_mfma_f32_16x16x32_bf16 v[46:49], v[142:145], v[166:169], v[46:49]
	v_mfma_f32_16x16x32_bf16 v[38:41], v[150:153], v[166:169], v[38:41]
	v_mfma_f32_16x16x32_bf16 v[30:33], v[142:145], v[200:203], v[30:33]
	v_mfma_f32_16x16x32_bf16 v[22:25], v[150:153], v[200:203], v[22:25]
	v_mfma_f32_16x16x32_bf16 v[14:17], v[142:145], v[208:211], v[14:17]
	v_mfma_f32_16x16x32_bf16 v[6:9], v[150:153], v[208:211], v[6:9]
	v_mfma_f32_16x16x32_bf16 v[62:65], v[146:149], v[162:165], v[62:65]
	v_mfma_f32_16x16x32_bf16 v[54:57], v[154:157], v[162:165], v[54:57]
	v_mfma_f32_16x16x32_bf16 v[46:49], v[146:149], v[170:173], v[46:49]
	v_mfma_f32_16x16x32_bf16 v[38:41], v[154:157], v[170:173], v[38:41]
	v_mfma_f32_16x16x32_bf16 v[30:33], v[146:149], v[204:207], v[30:33]
	v_mfma_f32_16x16x32_bf16 v[22:25], v[154:157], v[204:207], v[22:25]
	v_mfma_f32_16x16x32_bf16 v[14:17], v[146:149], v[212:215], v[14:17]
	v_mfma_f32_16x16x32_bf16 v[6:9], v[154:157], v[212:215], v[6:9]
	s_setprio 0
	s_barrier
	s_add_u32 s20, s20, 0x40080
	s_addc_u32 s21, s21, 0
	s_add_i32 s22, s22, s30
	v_lshl_add_u64 v[142:143], s[20:21], 0, v[134:135]
	s_mov_b32 m0, s22
	s_nop 0
	global_load_lds_dwordx4 v[142:143], off
	v_lshl_add_u64 v[142:143], s[20:21], 0, v[132:133]
	s_add_i32 m0, s22, 0x2000
	s_nop 0
	global_load_lds_dwordx4 v[142:143], off
	s_waitcnt vmcnt(6)
	s_barrier
	s_setprio 1
	v_mfma_f32_16x16x32_bf16 v[58:61], v[216:219], v[158:161], v[58:61]
	v_mfma_f32_16x16x32_bf16 v[50:53], v[224:227], v[158:161], v[50:53]
	v_mfma_f32_16x16x32_bf16 v[42:45], v[216:219], v[166:169], v[42:45]
	v_mfma_f32_16x16x32_bf16 v[34:37], v[224:227], v[166:169], v[34:37]
	v_mfma_f32_16x16x32_bf16 v[26:29], v[216:219], v[200:203], v[26:29]
	v_mfma_f32_16x16x32_bf16 v[18:21], v[224:227], v[200:203], v[18:21]
	v_mfma_f32_16x16x32_bf16 v[10:13], v[216:219], v[208:211], v[10:13]
	v_mfma_f32_16x16x32_bf16 v[2:5], v[224:227], v[208:211], v[2:5]
	v_mfma_f32_16x16x32_bf16 v[58:61], v[220:223], v[162:165], v[58:61]
	v_mfma_f32_16x16x32_bf16 v[50:53], v[228:231], v[162:165], v[50:53]
	v_mfma_f32_16x16x32_bf16 v[42:45], v[220:223], v[170:173], v[42:45]
	v_mfma_f32_16x16x32_bf16 v[34:37], v[228:231], v[170:173], v[34:37]
	v_mfma_f32_16x16x32_bf16 v[26:29], v[220:223], v[204:207], v[26:29]
	v_mfma_f32_16x16x32_bf16 v[18:21], v[228:231], v[204:207], v[18:21]
	v_mfma_f32_16x16x32_bf16 v[10:13], v[220:223], v[212:215], v[10:13]
	v_mfma_f32_16x16x32_bf16 v[2:5], v[228:231], v[212:215], v[2:5]
	s_setprio 0
	s_add_i32 s46, s46, 2
	s_add_u32 s18, s18, 0x100
	s_addc_u32 s19, s19, 0
	s_add_u32 s44, s44, 0x100
	s_addc_u32 s45, s45, 0
	s_cmp_gt_u32 s46, 13
	s_barrier
	s_cbranch_scc0 .LBB0_1604
	v_mul_f32_e32 v143, 0xbfb8aa3b, v126
	v_exp_f32_e32 v143, v143
	v_lshl_or_b32 v144, s41, 7, v140
	v_lshl_add_u32 v142, s16, 8, v1
	v_ashrrev_i32_e32 v145, 31, v144
	v_add_f32_e32 v143, 1.0, v143
	v_rcp_f32_e32 v146, v143
	v_mul_f32_e32 v143, 0xbfb8aa3b, v127
	v_exp_f32_e32 v143, v143
	s_and_b64 vcc, exec, s[6:7]
	s_mov_b32 s41, s0
	s_mov_b32 s16, s10
	v_add_f32_e32 v143, 1.0, v143
	v_rcp_f32_e32 v147, v143
	s_mov_b64 s[20:21], s[14:15]
	v_pk_mul_f32 v[126:127], v[126:127], v[146:147]
	s_nop 0
	v_pk_mul_f32 v[122:123], v[126:127], v[122:123]
	s_nop 0
	v_cvt_pk_bf16_f32 v126, v122, v123
	v_mul_f32_e32 v122, 0xbfb8aa3b, v128
	v_mul_f32_e32 v123, 0xbfb8aa3b, v129
	v_exp_f32_e32 v122, v122
	v_exp_f32_e32 v123, v123
	v_add_f32_e32 v122, 1.0, v122
	v_add_f32_e32 v123, 1.0, v123
	v_rcp_f32_e32 v122, v122
	v_rcp_f32_e32 v123, v123
	s_nop 0
	v_pk_mul_f32 v[122:123], v[128:129], v[122:123]
	s_nop 0
	v_pk_mul_f32 v[122:123], v[122:123], v[124:125]
	v_lshlrev_b64 v[124:125], 1, v[144:145]
	v_cvt_pk_bf16_f32 v127, v122, v123
	v_mov_b64_e32 v[122:123], s[84:85]
	v_mad_i64_i32 v[128:129], s[18:19], v142, s50, v[122:123]
	v_lshl_add_u64 v[128:129], v[128:129], 0, v[124:125]
	global_store_dwordx2 v[128:129], v[126:127], off
	v_mul_f32_e32 v126, 0xbfb8aa3b, v118
	v_mul_f32_e32 v127, 0xbfb8aa3b, v119
	v_exp_f32_e32 v126, v126
	v_exp_f32_e32 v127, v127
	v_add_f32_e32 v126, 1.0, v126
	v_add_f32_e32 v127, 1.0, v127
	v_rcp_f32_e32 v126, v126
	v_rcp_f32_e32 v127, v127
	s_nop 0
	v_pk_mul_f32 v[118:119], v[118:119], v[126:127]
	s_nop 0
	v_pk_mul_f32 v[114:115], v[118:119], v[114:115]
	s_nop 0
	v_cvt_pk_bf16_f32 v114, v114, v115
	v_mul_f32_e32 v115, 0xbfb8aa3b, v120
	v_exp_f32_e32 v115, v115
	s_nop 0
	v_add_f32_e32 v115, 1.0, v115
	v_rcp_f32_e32 v118, v115
	v_mul_f32_e32 v115, 0xbfb8aa3b, v121
	v_exp_f32_e32 v115, v115
	s_nop 0
	v_add_f32_e32 v115, 1.0, v115
	v_rcp_f32_e32 v119, v115
	s_nop 0
	v_pk_mul_f32 v[118:119], v[120:121], v[118:119]
	s_nop 0
	v_pk_mul_f32 v[116:117], v[118:119], v[116:117]
	s_nop 0
	v_cvt_pk_bf16_f32 v115, v116, v117
	global_store_dwordx2 v[128:129], v[114:115], off offset:32
	v_mul_f32_e32 v114, 0xbfb8aa3b, v110
	v_mul_f32_e32 v115, 0xbfb8aa3b, v111
	v_exp_f32_e32 v114, v114
	v_exp_f32_e32 v115, v115
	v_or_b32_e32 v116, 16, v142
	v_add_f32_e32 v114, 1.0, v114
	v_add_f32_e32 v115, 1.0, v115
	v_rcp_f32_e32 v114, v114
	v_rcp_f32_e32 v115, v115
	s_nop 0
	v_pk_mul_f32 v[110:111], v[110:111], v[114:115]
	s_nop 0
	v_pk_mul_f32 v[106:107], v[110:111], v[106:107]
	s_nop 0
	v_cvt_pk_bf16_f32 v106, v106, v107
	v_mul_f32_e32 v107, 0xbfb8aa3b, v112
	v_exp_f32_e32 v107, v107
	s_nop 0
	v_add_f32_e32 v107, 1.0, v107
	v_rcp_f32_e32 v110, v107
	v_mul_f32_e32 v107, 0xbfb8aa3b, v113
	v_exp_f32_e32 v107, v107
	s_nop 0
	v_add_f32_e32 v107, 1.0, v107
	v_rcp_f32_e32 v111, v107
	s_nop 0
	v_pk_mul_f32 v[110:111], v[112:113], v[110:111]
; __device__ __forceinline__ float silu_f(float x) { return x * sigm(x); }
;   __device__ __forceinline__ void operator()(const f32x4 (&acc)[2][2][4][2], const Unit& u, int wr, int wc, int fr, int fq) const {
; #pragma unroll
;     for (int ai = 0; ai < 2; ++ai)
; #pragma unroll
;       for (int m = 0; m < 4; ++m) {
;         const int r = u.pm * 256 + ai * 128 + wr * 64 + m * 16 + fr;
; #pragma unroll
;         for (int n = 0; n < 2; ++n) {
;           const f32x4 g = acc[ai][0][m][n], up = acc[ai][1][m][n];
;           const int c = u.pn * 128 + wc * 32 + n * 16 + 4 * fq;
;           uint2 w;
;           w.x = pack2(silu_f(g[0]) * up[0], silu_f(g[1]) * up[1]);
;           w.y = pack2(silu_f(g[2]) * up[2], silu_f(g[3]) * up[3]);
;           *reinterpret_cast<uint2*>(HID + (size_t)r * DFF + c) = w;
;         }
;       }
	s_nop 0
	v_pk_mul_f32 v[108:109], v[110:111], v[108:109]
	s_nop 0
	v_cvt_pk_bf16_f32 v107, v108, v109
	v_mad_i64_i32 v[108:109], s[18:19], v116, s50, v[122:123]
	v_lshl_add_u64 v[108:109], v[108:109], 0, v[124:125]
	global_store_dwordx2 v[108:109], v[106:107], off
	v_mul_f32_e32 v106, 0xbfb8aa3b, v102
	v_mul_f32_e32 v107, 0xbfb8aa3b, v103
	v_exp_f32_e32 v106, v106
	v_exp_f32_e32 v107, v107
	v_add_f32_e32 v106, 1.0, v106
	v_add_f32_e32 v107, 1.0, v107
	v_rcp_f32_e32 v106, v106
	v_rcp_f32_e32 v107, v107
	s_nop 0
	v_pk_mul_f32 v[102:103], v[102:103], v[106:107]
	s_nop 0
	v_pk_mul_f32 v[98:99], v[102:103], v[98:99]
	s_nop 0
	v_cvt_pk_bf16_f32 v98, v98, v99
	v_mul_f32_e32 v99, 0xbfb8aa3b, v104
	v_exp_f32_e32 v99, v99
	s_nop 0
	v_add_f32_e32 v99, 1.0, v99
	v_rcp_f32_e32 v102, v99
	v_mul_f32_e32 v99, 0xbfb8aa3b, v105
	v_exp_f32_e32 v99, v99
	s_nop 0
	v_add_f32_e32 v99, 1.0, v99
	v_rcp_f32_e32 v103, v99
	s_nop 0
	v_pk_mul_f32 v[102:103], v[104:105], v[102:103]
	s_nop 0
	v_pk_mul_f32 v[100:101], v[102:103], v[100:101]
	s_nop 0
	v_cvt_pk_bf16_f32 v99, v100, v101
	global_store_dwordx2 v[108:109], v[98:99], off offset:32
	v_mul_f32_e32 v98, 0xbfb8aa3b, v94
	v_mul_f32_e32 v99, 0xbfb8aa3b, v95
	v_exp_f32_e32 v98, v98
	v_exp_f32_e32 v99, v99
	v_or_b32_e32 v100, 32, v142
	v_add_f32_e32 v98, 1.0, v98
	v_add_f32_e32 v99, 1.0, v99
	v_rcp_f32_e32 v98, v98
	v_rcp_f32_e32 v99, v99
	s_nop 0
	v_pk_mul_f32 v[94:95], v[94:95], v[98:99]
	s_nop 0
	v_pk_mul_f32 v[90:91], v[94:95], v[90:91]
	s_nop 0
	v_cvt_pk_bf16_f32 v90, v90, v91
	v_mul_f32_e32 v91, 0xbfb8aa3b, v96
	v_exp_f32_e32 v91, v91
	s_nop 0
	v_add_f32_e32 v91, 1.0, v91
	v_rcp_f32_e32 v94, v91
	v_mul_f32_e32 v91, 0xbfb8aa3b, v97
	v_exp_f32_e32 v91, v91
	s_nop 0
	v_add_f32_e32 v91, 1.0, v91
	v_rcp_f32_e32 v95, v91
	s_nop 0
	v_pk_mul_f32 v[94:95], v[96:97], v[94:95]
	s_nop 0
	v_pk_mul_f32 v[92:93], v[94:95], v[92:93]
	s_nop 0
	v_cvt_pk_bf16_f32 v91, v92, v93
	v_mad_i64_i32 v[92:93], s[18:19], v100, s50, v[122:123]
	v_lshl_add_u64 v[92:93], v[92:93], 0, v[124:125]
	global_store_dwordx2 v[92:93], v[90:91], off
	v_mul_f32_e32 v90, 0xbfb8aa3b, v86
	v_mul_f32_e32 v91, 0xbfb8aa3b, v87
	v_exp_f32_e32 v90, v90
	v_exp_f32_e32 v91, v91
	v_add_f32_e32 v90, 1.0, v90
	v_add_f32_e32 v91, 1.0, v91
	v_rcp_f32_e32 v90, v90
	v_rcp_f32_e32 v91, v91
	s_nop 0
	v_pk_mul_f32 v[86:87], v[86:87], v[90:91]
	s_nop 0
	v_pk_mul_f32 v[82:83], v[86:87], v[82:83]
	s_nop 0
	v_cvt_pk_bf16_f32 v82, v82, v83
	v_mul_f32_e32 v83, 0xbfb8aa3b, v88
	v_exp_f32_e32 v83, v83
	s_nop 0
	v_add_f32_e32 v83, 1.0, v83
	v_rcp_f32_e32 v86, v83
	v_mul_f32_e32 v83, 0xbfb8aa3b, v89
	v_exp_f32_e32 v83, v83
	s_nop 0
	v_add_f32_e32 v83, 1.0, v83
	v_rcp_f32_e32 v87, v83
	s_nop 0
	v_pk_mul_f32 v[86:87], v[88:89], v[86:87]
	s_nop 0
	v_pk_mul_f32 v[84:85], v[86:87], v[84:85]
	s_nop 0
	v_cvt_pk_bf16_f32 v83, v84, v85
	global_store_dwordx2 v[92:93], v[82:83], off offset:32
	v_mul_f32_e32 v82, 0xbfb8aa3b, v78
	v_mul_f32_e32 v83, 0xbfb8aa3b, v79
	v_exp_f32_e32 v82, v82
	v_exp_f32_e32 v83, v83
	v_or_b32_e32 v84, 48, v142
	v_add_f32_e32 v82, 1.0, v82
	v_add_f32_e32 v83, 1.0, v83
	v_rcp_f32_e32 v82, v82
	v_rcp_f32_e32 v83, v83
	s_nop 0
	v_pk_mul_f32 v[78:79], v[78:79], v[82:83]
	s_nop 0
	v_pk_mul_f32 v[74:75], v[78:79], v[74:75]
	s_nop 0
	v_cvt_pk_bf16_f32 v74, v74, v75
	v_mul_f32_e32 v75, 0xbfb8aa3b, v80
	v_exp_f32_e32 v75, v75
	s_nop 0
	v_add_f32_e32 v75, 1.0, v75
	v_rcp_f32_e32 v78, v75
	v_mul_f32_e32 v75, 0xbfb8aa3b, v81
	v_exp_f32_e32 v75, v75
	s_nop 0
	v_add_f32_e32 v75, 1.0, v75
	v_rcp_f32_e32 v79, v75
	s_nop 0
	v_pk_mul_f32 v[78:79], v[80:81], v[78:79]
	s_nop 0
	v_pk_mul_f32 v[76:77], v[78:79], v[76:77]
	s_nop 0
	v_cvt_pk_bf16_f32 v75, v76, v77
	v_mad_i64_i32 v[76:77], s[18:19], v84, s50, v[122:123]
	v_lshl_add_u64 v[76:77], v[76:77], 0, v[124:125]
	global_store_dwordx2 v[76:77], v[74:75], off
	v_mul_f32_e32 v74, 0xbfb8aa3b, v70
	v_mul_f32_e32 v75, 0xbfb8aa3b, v71
	v_exp_f32_e32 v74, v74
	v_exp_f32_e32 v75, v75
	v_add_f32_e32 v74, 1.0, v74
	v_add_f32_e32 v75, 1.0, v75
	v_rcp_f32_e32 v74, v74
	v_rcp_f32_e32 v75, v75
	s_nop 0
	v_pk_mul_f32 v[70:71], v[70:71], v[74:75]
	s_nop 0
	v_pk_mul_f32 v[66:67], v[70:71], v[66:67]
	s_nop 0
	v_cvt_pk_bf16_f32 v66, v66, v67
	v_mul_f32_e32 v67, 0xbfb8aa3b, v72
	v_exp_f32_e32 v67, v67
	s_nop 0
	v_add_f32_e32 v67, 1.0, v67
	v_rcp_f32_e32 v70, v67
	v_mul_f32_e32 v67, 0xbfb8aa3b, v73
	v_exp_f32_e32 v67, v67
	s_nop 0
	v_add_f32_e32 v67, 1.0, v67
	v_rcp_f32_e32 v71, v67
	s_nop 0
	v_pk_mul_f32 v[70:71], v[72:73], v[70:71]
	s_nop 0
	v_pk_mul_f32 v[68:69], v[70:71], v[68:69]
	s_nop 0
	v_cvt_pk_bf16_f32 v67, v68, v69
	global_store_dwordx2 v[76:77], v[66:67], off offset:32
	v_mul_f32_e32 v66, 0xbfb8aa3b, v62
	v_mul_f32_e32 v67, 0xbfb8aa3b, v63
	v_exp_f32_e32 v66, v66
	v_exp_f32_e32 v67, v67
	v_add_u32_e32 v68, 0x80, v142
	v_add_f32_e32 v66, 1.0, v66
	v_add_f32_e32 v67, 1.0, v67
	v_rcp_f32_e32 v66, v66
	v_rcp_f32_e32 v67, v67
	s_nop 0
	v_pk_mul_f32 v[62:63], v[62:63], v[66:67]
	s_nop 0
	v_pk_mul_f32 v[58:59], v[62:63], v[58:59]
	s_nop 0
	v_cvt_pk_bf16_f32 v58, v58, v59
	v_mul_f32_e32 v59, 0xbfb8aa3b, v64
	v_exp_f32_e32 v59, v59
	s_nop 0
	v_add_f32_e32 v59, 1.0, v59
	v_rcp_f32_e32 v62, v59
	v_mul_f32_e32 v59, 0xbfb8aa3b, v65
	v_exp_f32_e32 v59, v59
	s_nop 0
	v_add_f32_e32 v59, 1.0, v59
	v_rcp_f32_e32 v63, v59
	s_nop 0
	v_pk_mul_f32 v[62:63], v[64:65], v[62:63]
	s_nop 0
	v_pk_mul_f32 v[60:61], v[62:63], v[60:61]
	s_nop 0
	v_cvt_pk_bf16_f32 v59, v60, v61
	v_mad_i64_i32 v[60:61], s[18:19], v68, s50, v[122:123]
	v_lshl_add_u64 v[60:61], v[60:61], 0, v[124:125]
	global_store_dwordx2 v[60:61], v[58:59], off
	v_mul_f32_e32 v58, 0xbfb8aa3b, v54
; __device__ __forceinline__ float silu_f(float x) { return x * sigm(x); }
; #define PG8_WAIT_V(n) asm volatile("s_waitcnt vmcnt(" #n ")" ::: "memory")
; #define PG8_BAR __builtin_amdgcn_s_barrier()
; template <class Epi, class Sched>
; __device__ __forceinline__ void gemm_phase(PG8_LAS unsigned char* lds, const int lda, const int ldb, const Sched& S, const Epi& E) {
;     ...
;   PG8_WAIT_V(0);
;   if (wr == 0) PG8_BAR;
;   PG8_BAR;
;   __device__ __forceinline__ void operator()(const f32x4 (&acc)[2][2][4][2], const Unit& u, int wr, int wc, int fr, int fq) const {
; #pragma unroll
;     for (int ai = 0; ai < 2; ++ai)
; #pragma unroll
;       for (int m = 0; m < 4; ++m) {
;         const int r = u.pm * 256 + ai * 128 + wr * 64 + m * 16 + fr;
; #pragma unroll
;         for (int n = 0; n < 2; ++n) {
;           const f32x4 g = acc[ai][0][m][n], up = acc[ai][1][m][n];
;           const int c = u.pn * 128 + wc * 32 + n * 16 + 4 * fq;
;           uint2 w;
;           w.x = pack2(silu_f(g[0]) * up[0], silu_f(g[1]) * up[1]);
;           w.y = pack2(silu_f(g[2]) * up[2], silu_f(g[3]) * up[3]);
;           *reinterpret_cast<uint2*>(HID + (size_t)r * DFF + c) = w;
;         }
;       }
	v_mul_f32_e32 v59, 0xbfb8aa3b, v55
	v_exp_f32_e32 v58, v58
	v_exp_f32_e32 v59, v59
	v_add_f32_e32 v58, 1.0, v58
	v_add_f32_e32 v59, 1.0, v59
	v_rcp_f32_e32 v58, v58
	v_rcp_f32_e32 v59, v59
	s_nop 0
	v_pk_mul_f32 v[54:55], v[54:55], v[58:59]
	s_nop 0
	v_pk_mul_f32 v[50:51], v[54:55], v[50:51]
	s_nop 0
	v_cvt_pk_bf16_f32 v50, v50, v51
	v_mul_f32_e32 v51, 0xbfb8aa3b, v56
	v_exp_f32_e32 v51, v51
	s_nop 0
	v_add_f32_e32 v51, 1.0, v51
	v_rcp_f32_e32 v54, v51
	v_mul_f32_e32 v51, 0xbfb8aa3b, v57
	v_exp_f32_e32 v51, v51
	s_nop 0
	v_add_f32_e32 v51, 1.0, v51
	v_rcp_f32_e32 v55, v51
	s_nop 0
	v_pk_mul_f32 v[54:55], v[56:57], v[54:55]
	s_nop 0
	v_pk_mul_f32 v[52:53], v[54:55], v[52:53]
	s_nop 0
	v_cvt_pk_bf16_f32 v51, v52, v53
	global_store_dwordx2 v[60:61], v[50:51], off offset:32
	v_mul_f32_e32 v50, 0xbfb8aa3b, v46
	v_mul_f32_e32 v51, 0xbfb8aa3b, v47
	v_exp_f32_e32 v50, v50
	v_exp_f32_e32 v51, v51
	v_add_u32_e32 v52, 0x90, v142
	v_add_f32_e32 v50, 1.0, v50
	v_add_f32_e32 v51, 1.0, v51
	v_rcp_f32_e32 v50, v50
	v_rcp_f32_e32 v51, v51
	s_nop 0
	v_pk_mul_f32 v[46:47], v[46:47], v[50:51]
	s_nop 0
	v_pk_mul_f32 v[42:43], v[46:47], v[42:43]
	s_nop 0
	v_cvt_pk_bf16_f32 v42, v42, v43
	v_mul_f32_e32 v43, 0xbfb8aa3b, v48
	v_exp_f32_e32 v43, v43
	s_nop 0
	v_add_f32_e32 v43, 1.0, v43
	v_rcp_f32_e32 v46, v43
	v_mul_f32_e32 v43, 0xbfb8aa3b, v49
	v_exp_f32_e32 v43, v43
	s_nop 0
	v_add_f32_e32 v43, 1.0, v43
	v_rcp_f32_e32 v47, v43
	s_nop 0
	v_pk_mul_f32 v[46:47], v[48:49], v[46:47]
	s_nop 0
	v_pk_mul_f32 v[44:45], v[46:47], v[44:45]
	s_nop 0
	v_cvt_pk_bf16_f32 v43, v44, v45
	v_mad_i64_i32 v[44:45], s[18:19], v52, s50, v[122:123]
	v_lshl_add_u64 v[44:45], v[44:45], 0, v[124:125]
	global_store_dwordx2 v[44:45], v[42:43], off
	v_mul_f32_e32 v42, 0xbfb8aa3b, v38
	v_mul_f32_e32 v43, 0xbfb8aa3b, v39
	v_exp_f32_e32 v42, v42
	v_exp_f32_e32 v43, v43
	v_add_f32_e32 v42, 1.0, v42
	v_add_f32_e32 v43, 1.0, v43
	v_rcp_f32_e32 v42, v42
	v_rcp_f32_e32 v43, v43
	s_nop 0
	v_pk_mul_f32 v[38:39], v[38:39], v[42:43]
	s_nop 0
	v_pk_mul_f32 v[34:35], v[38:39], v[34:35]
	s_nop 0
	v_cvt_pk_bf16_f32 v34, v34, v35
	v_mul_f32_e32 v35, 0xbfb8aa3b, v40
	v_exp_f32_e32 v35, v35
	s_nop 0
	v_add_f32_e32 v35, 1.0, v35
	v_rcp_f32_e32 v38, v35
	v_mul_f32_e32 v35, 0xbfb8aa3b, v41
	v_exp_f32_e32 v35, v35
	s_nop 0
	v_add_f32_e32 v35, 1.0, v35
	v_rcp_f32_e32 v39, v35
	s_nop 0
	v_pk_mul_f32 v[38:39], v[40:41], v[38:39]
	s_nop 0
	v_pk_mul_f32 v[36:37], v[38:39], v[36:37]
	s_nop 0
	v_cvt_pk_bf16_f32 v35, v36, v37
	global_store_dwordx2 v[44:45], v[34:35], off offset:32
	v_mul_f32_e32 v34, 0xbfb8aa3b, v30
	v_mul_f32_e32 v35, 0xbfb8aa3b, v31
	v_exp_f32_e32 v34, v34
	v_exp_f32_e32 v35, v35
	v_add_u32_e32 v36, 0xa0, v142
	v_add_f32_e32 v34, 1.0, v34
	v_add_f32_e32 v35, 1.0, v35
	v_rcp_f32_e32 v34, v34
	v_rcp_f32_e32 v35, v35
	s_nop 0
	v_pk_mul_f32 v[30:31], v[30:31], v[34:35]
	s_nop 0
	v_pk_mul_f32 v[26:27], v[30:31], v[26:27]
	s_nop 0
	v_cvt_pk_bf16_f32 v26, v26, v27
	v_mul_f32_e32 v27, 0xbfb8aa3b, v32
	v_exp_f32_e32 v27, v27
	s_nop 0
	v_add_f32_e32 v27, 1.0, v27
	v_rcp_f32_e32 v30, v27
	v_mul_f32_e32 v27, 0xbfb8aa3b, v33
	v_exp_f32_e32 v27, v27
	s_nop 0
	v_add_f32_e32 v27, 1.0, v27
	v_rcp_f32_e32 v31, v27
	s_nop 0
	v_pk_mul_f32 v[30:31], v[32:33], v[30:31]
	s_nop 0
	v_pk_mul_f32 v[28:29], v[30:31], v[28:29]
	s_nop 0
	v_cvt_pk_bf16_f32 v27, v28, v29
	v_mad_i64_i32 v[28:29], s[18:19], v36, s50, v[122:123]
	v_lshl_add_u64 v[28:29], v[28:29], 0, v[124:125]
	global_store_dwordx2 v[28:29], v[26:27], off
	v_mul_f32_e32 v26, 0xbfb8aa3b, v22
	v_mul_f32_e32 v27, 0xbfb8aa3b, v23
	v_exp_f32_e32 v26, v26
	v_exp_f32_e32 v27, v27
	v_add_f32_e32 v26, 1.0, v26
	v_add_f32_e32 v27, 1.0, v27
	v_rcp_f32_e32 v26, v26
	v_rcp_f32_e32 v27, v27
	s_nop 0
	v_pk_mul_f32 v[22:23], v[22:23], v[26:27]
	s_nop 0
	v_pk_mul_f32 v[18:19], v[22:23], v[18:19]
	s_nop 0
	v_cvt_pk_bf16_f32 v18, v18, v19
	v_mul_f32_e32 v19, 0xbfb8aa3b, v24
	v_exp_f32_e32 v19, v19
	s_nop 0
	v_add_f32_e32 v19, 1.0, v19
	v_rcp_f32_e32 v22, v19
	v_mul_f32_e32 v19, 0xbfb8aa3b, v25
	v_exp_f32_e32 v19, v19
	s_nop 0
	v_add_f32_e32 v19, 1.0, v19
	v_rcp_f32_e32 v23, v19
	s_nop 0
	v_pk_mul_f32 v[22:23], v[24:25], v[22:23]
	s_nop 0
	v_pk_mul_f32 v[20:21], v[22:23], v[20:21]
	s_nop 0
	v_cvt_pk_bf16_f32 v19, v20, v21
	global_store_dwordx2 v[28:29], v[18:19], off offset:32
	v_mul_f32_e32 v18, 0xbfb8aa3b, v14
	v_mul_f32_e32 v19, 0xbfb8aa3b, v15
	v_exp_f32_e32 v18, v18
	v_exp_f32_e32 v19, v19
	v_add_u32_e32 v20, 0xb0, v142
	v_add_f32_e32 v18, 1.0, v18
	v_add_f32_e32 v19, 1.0, v19
	v_rcp_f32_e32 v18, v18
	v_rcp_f32_e32 v19, v19
	s_nop 0
	v_pk_mul_f32 v[14:15], v[14:15], v[18:19]
	s_nop 0
	v_pk_mul_f32 v[10:11], v[14:15], v[10:11]
	s_nop 0
	v_cvt_pk_bf16_f32 v10, v10, v11
	v_mul_f32_e32 v11, 0xbfb8aa3b, v16
	v_exp_f32_e32 v11, v11
	s_nop 0
	v_add_f32_e32 v11, 1.0, v11
	v_rcp_f32_e32 v14, v11
	v_mul_f32_e32 v11, 0xbfb8aa3b, v17
	v_exp_f32_e32 v11, v11
	s_nop 0
	v_add_f32_e32 v11, 1.0, v11
	v_rcp_f32_e32 v15, v11
	s_nop 0
	v_pk_mul_f32 v[14:15], v[16:17], v[14:15]
	s_nop 0
	v_pk_mul_f32 v[12:13], v[14:15], v[12:13]
	s_nop 0
	v_cvt_pk_bf16_f32 v11, v12, v13
	v_mad_i64_i32 v[12:13], s[18:19], v20, s50, v[122:123]
	v_lshl_add_u64 v[12:13], v[12:13], 0, v[124:125]
	global_store_dwordx2 v[12:13], v[10:11], off
	v_mul_f32_e32 v10, 0xbfb8aa3b, v6
	v_mul_f32_e32 v11, 0xbfb8aa3b, v7
	v_exp_f32_e32 v10, v10
	v_exp_f32_e32 v11, v11
	s_mov_b64 s[18:19], s[12:13]
	v_add_f32_e32 v10, 1.0, v10
	v_add_f32_e32 v11, 1.0, v11
	v_rcp_f32_e32 v10, v10
	v_rcp_f32_e32 v11, v11
	s_nop 0
	v_pk_mul_f32 v[6:7], v[6:7], v[10:11]
	s_nop 0
	v_pk_mul_f32 v[2:3], v[6:7], v[2:3]
	s_nop 0
	v_cvt_pk_bf16_f32 v2, v2, v3
	v_mul_f32_e32 v3, 0xbfb8aa3b, v8
	v_exp_f32_e32 v3, v3
	s_nop 0
	v_add_f32_e32 v3, 1.0, v3
	v_rcp_f32_e32 v6, v3
	v_mul_f32_e32 v3, 0xbfb8aa3b, v9
	v_exp_f32_e32 v3, v3
	s_nop 0
	v_add_f32_e32 v3, 1.0, v3
	v_rcp_f32_e32 v7, v3
	s_nop 0
	v_pk_mul_f32 v[6:7], v[8:9], v[6:7]
	s_nop 0
	v_pk_mul_f32 v[4:5], v[6:7], v[4:5]
	s_nop 0
	v_cvt_pk_bf16_f32 v3, v4, v5
	global_store_dwordx2 v[12:13], v[2:3], off offset:32
	s_cbranch_vccz .LBB0_1601
	s_waitcnt vmcnt(0)
	v_readlane_b32 s40, v253, 12
	s_cmpk_gt_u32 s9, 0xff
	v_readlane_b32 s41, v253, 13
	v_readlane_b32 s44, v253, 16
	v_readlane_b32 s45, v253, 17
	v_readlane_b32 s52, v253, 24
	v_readlane_b32 s53, v253, 25
	v_readlane_b32 s54, v253, 26
	v_readlane_b32 s55, v253, 27
	v_readlane_b32 s38, v255, 23
	v_readlane_b32 s42, v253, 14
	v_readlane_b32 s43, v253, 15
	v_readlane_b32 s46, v253, 18
	v_readlane_b32 s47, v253, 19
	v_readlane_b32 s48, v253, 20
	v_readlane_b32 s49, v253, 21
	v_readlane_b32 s50, v253, 22
	v_readlane_b32 s51, v253, 23
	v_readlane_b32 s39, v255, 24
	s_cbranch_scc1 .LBB0_1608
	s_barrier

; #define PG8_STAGE(bufoff, gbase, voff) do { _Pragma("unroll") for (int _i = 0; _i < 2; ++_i) \
;     __builtin_amdgcn_global_load_lds((const unsigned*)((const char*)(gbase) + (voff)[_i]), (PG8_LAS unsigned*)(lds + (bufoff) + ldsw + _i * 8192), 16, 0, 0); } while (0)
; #define PG8_LDA(dst, b, h) do { _Pragma("unroll") for (int m = 0; m < 4; ++m) _Pragma("unroll") for (int k = 0; k < 2; ++k) dst[m][k] = *(const PG8_LAS bf16x8*)(lds + PG8_SA(b, h) + aoff + m * 2048 + k * 1024); } while (0)
; #define PG8_LDB(dst, b, h) do { _Pragma("unroll") for (int n = 0; n < 2; ++n) _Pragma("unroll") for (int k = 0; k < 2; ++k) dst[n][k] = *(const PG8_LAS bf16x8*)(lds + PG8_SB(b, h) + boff + n * 2048 + k * 1024); } while (0)
; #define PG8_MMA(ai, bj, At, Bt) do { __builtin_amdgcn_s_setprio(1); _Pragma("unroll") for (int m = 0; m < 4; ++m) _Pragma("unroll") for (int n = 0; n < 2; ++n) _Pragma("unroll") for (int k = 0; k < 2; ++k) \
;     acc[ai][bj][m][n] = __builtin_amdgcn_mfma_f32_16x16x32_bf16(Bt[n][k], At[m][k], acc[ai][bj][m][n], 0, 0, 0); __builtin_amdgcn_s_setprio(0); } while (0)
; #define PG8_WAIT_L(n) asm volatile("s_waitcnt lgkmcnt(" #n ")" ::: "memory")
; #define PG8_BAR __builtin_amdgcn_s_barrier()
; #define PG8_SCHED __builtin_amdgcn_sched_barrier(0)
; template <class Epi, class Sched>
; __device__ __forceinline__ void gemm_phase(PG8_LAS unsigned char* lds, const int lda, const int ldb, const Sched& S, const Epi& E) {
;     ...
;     for (int t = 0; t < nt; t += 2) {
;       const bool last = (t == nt - 2);
;       const char* a1 = cA + (size_t)(t + 1) * kstep;
;       const char* a2 = last ? nA : cA + (size_t)(t + 2) * kstep; const char* b2 = last ? nB : cB + (size_t)(t + 2) * kstep;
;       const char* a3 = a2 + kstep; const char* b3 = b2 + kstep;
;       PG8_LDB(B0, 0, 0); PG8_SCHED; PG8_LDA(At, 0, 0); PG8_STAGE(PG8_SA(1, 1), a1 + hstepA, voffA);
;       PG8_WAIT_L(8); PG8_BAR; PG8_WAIT_L(0); PG8_MMA(0, 0, At, B0); PG8_BAR; PG8_SCHED;
;       PG8_LDB(B1, 0, 1); PG8_STAGE(PG8_SB(0, 0), b2, voffB);
;       PG8_BAR; PG8_WAIT_L(0); PG8_MMA(0, 1, At, B1); PG8_BAR;
;       PG8_LDA(At, 0, 1); PG8_STAGE(PG8_SA(0, 0), a2, voffA);
;       PG8_BAR; PG8_WAIT_L(0); PG8_MMA(1, 0, At, B0); PG8_BAR; PG8_SCHED;
.LBB0_1673:
	s_add_u32 s12, s10, 0x100
	s_addc_u32 s13, s11, 0
	s_add_i32 s33, 0, 0x10000
	v_add_u32_e32 v154, s33, v131
	ds_read_b128 v[140:143], v154
	ds_read_b128 v[146:149], v154 offset:1024
	ds_read_b128 v[150:153], v154 offset:2048
	ds_read_b128 v[154:157], v154 offset:3072
	s_cmp_eq_u32 s41, 40
	s_cselect_b32 s17, s7, s13
	s_cselect_b32 s16, s6, s12
	s_cselect_b32 s15, s1, s40
	s_cselect_b32 s14, s0, s39
	v_lshl_add_u64 v[174:175], s[10:11], 0, v[136:137]
	s_add_i32 m0, s23, 0xc000
	ds_read_b128 v[158:161], v145
	ds_read_b128 v[162:165], v145 offset:1024
	ds_read_b128 v[166:169], v145 offset:2048
	ds_read_b128 v[170:173], v145 offset:3072
	ds_read_b128 v[200:203], v145 offset:4096
	ds_read_b128 v[204:207], v145 offset:5120
	ds_read_b128 v[208:211], v145 offset:6144
	ds_read_b128 v[212:215], v145 offset:7168
	global_load_lds_dwordx4 v[174:175], off
	v_lshl_add_u64 v[174:175], s[10:11], 0, v[138:139]
	s_add_i32 m0, s23, 0xe000
	s_nop 0
	global_load_lds_dwordx4 v[174:175], off
	s_waitcnt lgkmcnt(8)
	s_barrier
	s_waitcnt lgkmcnt(0)
	s_setprio 1
	v_mfma_f32_16x16x32_bf16 v[126:129], v[140:143], v[158:161], v[126:129]
	v_mfma_f32_16x16x32_bf16 v[122:125], v[150:153], v[158:161], v[122:125]
	v_mfma_f32_16x16x32_bf16 v[110:113], v[140:143], v[166:169], v[110:113]
	v_mfma_f32_16x16x32_bf16 v[106:109], v[150:153], v[166:169], v[106:109]
	v_mfma_f32_16x16x32_bf16 v[94:97], v[140:143], v[200:203], v[94:97]
	v_mfma_f32_16x16x32_bf16 v[90:93], v[150:153], v[200:203], v[90:93]
	v_mfma_f32_16x16x32_bf16 v[78:81], v[140:143], v[208:211], v[78:81]
	v_mfma_f32_16x16x32_bf16 v[74:77], v[150:153], v[208:211], v[74:77]
	v_mfma_f32_16x16x32_bf16 v[126:129], v[146:149], v[162:165], v[126:129]
	v_mfma_f32_16x16x32_bf16 v[122:125], v[154:157], v[162:165], v[122:125]
	v_mfma_f32_16x16x32_bf16 v[110:113], v[146:149], v[170:173], v[110:113]
	v_mfma_f32_16x16x32_bf16 v[106:109], v[154:157], v[170:173], v[106:109]
	v_mfma_f32_16x16x32_bf16 v[94:97], v[146:149], v[204:207], v[94:97]
	v_mfma_f32_16x16x32_bf16 v[90:93], v[154:157], v[204:207], v[90:93]
	v_mfma_f32_16x16x32_bf16 v[78:81], v[146:149], v[212:215], v[78:81]
	v_mfma_f32_16x16x32_bf16 v[74:77], v[154:157], v[212:215], v[74:77]
	s_setprio 0
	s_barrier
	s_add_i32 s42, 0, 0x14000
	v_add_u32_e32 v174, s42, v131
	s_add_i32 s10, s33, s20
	ds_read_b128 v[216:219], v174
	ds_read_b128 v[220:223], v174 offset:1024
	ds_read_b128 v[224:227], v174 offset:2048
	ds_read_b128 v[228:231], v174 offset:3072
	v_lshl_add_u64 v[174:175], s[14:15], 0, v[134:135]
	s_mov_b32 m0, s10
	v_lshl_add_u64 v[182:183], s[14:15], 0, v[132:133]
	global_load_lds_dwordx4 v[174:175], off
	s_add_i32 m0, s10, 0x2000
	s_nop 0
	global_load_lds_dwordx4 v[182:183], off
	s_waitcnt lgkmcnt(0)
	s_barrier
	s_setprio 1
	v_mfma_f32_16x16x32_bf16 v[118:121], v[216:219], v[158:161], v[118:121]
	v_mfma_f32_16x16x32_bf16 v[114:117], v[224:227], v[158:161], v[114:117]
	v_mfma_f32_16x16x32_bf16 v[102:105], v[216:219], v[166:169], v[102:105]
	v_mfma_f32_16x16x32_bf16 v[98:101], v[224:227], v[166:169], v[98:101]
	v_mfma_f32_16x16x32_bf16 v[86:89], v[216:219], v[200:203], v[86:89]
	v_mfma_f32_16x16x32_bf16 v[82:85], v[224:227], v[200:203], v[82:85]
	v_mfma_f32_16x16x32_bf16 v[70:73], v[216:219], v[208:211], v[70:73]
	v_mfma_f32_16x16x32_bf16 v[66:69], v[224:227], v[208:211], v[66:69]
	v_mfma_f32_16x16x32_bf16 v[118:121], v[220:223], v[162:165], v[118:121]
	v_mfma_f32_16x16x32_bf16 v[114:117], v[228:231], v[162:165], v[114:117]
	v_mfma_f32_16x16x32_bf16 v[102:105], v[220:223], v[170:173], v[102:105]
	v_mfma_f32_16x16x32_bf16 v[98:101], v[228:231], v[170:173], v[98:101]
	v_mfma_f32_16x16x32_bf16 v[86:89], v[220:223], v[204:207], v[86:89]
	v_mfma_f32_16x16x32_bf16 v[82:85], v[228:231], v[204:207], v[82:85]
	v_mfma_f32_16x16x32_bf16 v[70:73], v[220:223], v[212:215], v[70:73]
	v_mfma_f32_16x16x32_bf16 v[66:69], v[228:231], v[212:215], v[66:69]
	s_setprio 0
	s_mov_b32 m0, s23
	v_lshl_add_u64 v[184:185], s[16:17], 0, v[134:135]
	s_barrier
	ds_read_b128 v[158:161], v145 offset:16384
	ds_read_b128 v[162:165], v145 offset:17408
	ds_read_b128 v[166:169], v145 offset:18432
	ds_read_b128 v[170:173], v145 offset:19456
	ds_read_b128 v[200:203], v145 offset:20480
	ds_read_b128 v[204:207], v145 offset:21504
	ds_read_b128 v[208:211], v145 offset:22528
	ds_read_b128 v[212:215], v145 offset:23552
	global_load_lds_dwordx4 v[184:185], off
	v_lshl_add_u64 v[232:233], s[16:17], 0, v[132:133]
	s_mov_b32 m0, s24
	s_nop 0
	global_load_lds_dwordx4 v[232:233], off
	s_waitcnt lgkmcnt(0)
	s_barrier
	s_setprio 1
	v_mfma_f32_16x16x32_bf16 v[62:65], v[140:143], v[158:161], v[62:65]
	v_mfma_f32_16x16x32_bf16 v[58:61], v[150:153], v[158:161], v[58:61]
	v_mfma_f32_16x16x32_bf16 v[46:49], v[140:143], v[166:169], v[46:49]
	v_mfma_f32_16x16x32_bf16 v[42:45], v[150:153], v[166:169], v[42:45]
	v_mfma_f32_16x16x32_bf16 v[30:33], v[140:143], v[200:203], v[30:33]
	v_mfma_f32_16x16x32_bf16 v[26:29], v[150:153], v[200:203], v[26:29]
	v_mfma_f32_16x16x32_bf16 v[14:17], v[140:143], v[208:211], v[14:17]
	v_mfma_f32_16x16x32_bf16 v[10:13], v[150:153], v[208:211], v[10:13]
	v_mfma_f32_16x16x32_bf16 v[62:65], v[146:149], v[162:165], v[62:65]
	v_mfma_f32_16x16x32_bf16 v[58:61], v[154:157], v[162:165], v[58:61]
	v_mfma_f32_16x16x32_bf16 v[46:49], v[146:149], v[170:173], v[46:49]
	v_mfma_f32_16x16x32_bf16 v[42:45], v[154:157], v[170:173], v[42:45]
	v_mfma_f32_16x16x32_bf16 v[30:33], v[146:149], v[204:207], v[30:33]
	v_mfma_f32_16x16x32_bf16 v[26:29], v[154:157], v[204:207], v[26:29]
	v_mfma_f32_16x16x32_bf16 v[14:17], v[146:149], v[212:215], v[14:17]
	v_mfma_f32_16x16x32_bf16 v[10:13], v[154:157], v[212:215], v[10:13]
	s_setprio 0
	s_barrier
; #define PG8_STAGE(bufoff, gbase, voff) do { _Pragma("unroll") for (int _i = 0; _i < 2; ++_i) \
;     __builtin_amdgcn_global_load_lds((const unsigned*)((const char*)(gbase) + (voff)[_i]), (PG8_LAS unsigned*)(lds + (bufoff) + ldsw + _i * 8192), 16, 0, 0); } while (0)
; #define PG8_LDA(dst, b, h) do { _Pragma("unroll") for (int m = 0; m < 4; ++m) _Pragma("unroll") for (int k = 0; k < 2; ++k) dst[m][k] = *(const PG8_LAS bf16x8*)(lds + PG8_SA(b, h) + aoff + m * 2048 + k * 1024); } while (0)
; #define PG8_LDB(dst, b, h) do { _Pragma("unroll") for (int n = 0; n < 2; ++n) _Pragma("unroll") for (int k = 0; k < 2; ++k) dst[n][k] = *(const PG8_LAS bf16x8*)(lds + PG8_SB(b, h) + boff + n * 2048 + k * 1024); } while (0)
; #define PG8_MMA(ai, bj, At, Bt) do { __builtin_amdgcn_s_setprio(1); _Pragma("unroll") for (int m = 0; m < 4; ++m) _Pragma("unroll") for (int n = 0; n < 2; ++n) _Pragma("unroll") for (int k = 0; k < 2; ++k) \
;     acc[ai][bj][m][n] = __builtin_amdgcn_mfma_f32_16x16x32_bf16(Bt[n][k], At[m][k], acc[ai][bj][m][n], 0, 0, 0); __builtin_amdgcn_s_setprio(0); } while (0)
; #define PG8_WAIT_V(n) asm volatile("s_waitcnt vmcnt(" #n ")" ::: "memory")
; #define PG8_WAIT_L(n) asm volatile("s_waitcnt lgkmcnt(" #n ")" ::: "memory")
; #define PG8_BAR __builtin_amdgcn_s_barrier()
; #define PG8_SCHED __builtin_amdgcn_sched_barrier(0)
; template <class Epi, class Sched>
; __device__ __forceinline__ void gemm_phase(PG8_LAS unsigned char* lds, const int lda, const int ldb, const Sched& S, const Epi& E) {
;     ...
;       PG8_STAGE(PG8_SB(0, 1), b2 + hstepB, voffB);
;       PG8_WAIT_V(6); PG8_BAR; PG8_MMA(1, 1, At, B1); PG8_BAR;
;       PG8_LDB(B0, 1, 0); PG8_SCHED; PG8_LDA(At, 1, 0); PG8_STAGE(PG8_SA(0, 1), a2 + hstepA, voffA);
;       PG8_WAIT_L(8); PG8_BAR; PG8_WAIT_L(0); PG8_MMA(0, 0, At, B0); PG8_BAR; PG8_SCHED;
;       PG8_LDB(B1, 1, 1); PG8_STAGE(PG8_SB(1, 0), b3, voffB);
;       PG8_BAR; PG8_WAIT_L(0); PG8_MMA(0, 1, At, B1); PG8_BAR;
	s_add_u32 s10, s14, 0xb0000
	s_addc_u32 s11, s15, 0
	s_add_i32 s33, s42, s20
	v_lshl_add_u64 v[140:141], s[10:11], 0, v[134:135]
	s_mov_b32 m0, s33
	s_nop 0
	global_load_lds_dwordx4 v[140:141], off
	v_lshl_add_u64 v[140:141], s[10:11], 0, v[132:133]
	s_add_i32 m0, s33, 0x2000
	s_nop 0
	global_load_lds_dwordx4 v[140:141], off
	s_waitcnt vmcnt(6)
	s_barrier
	s_setprio 1
	v_mfma_f32_16x16x32_bf16 v[54:57], v[216:219], v[158:161], v[54:57]
	v_mfma_f32_16x16x32_bf16 v[50:53], v[224:227], v[158:161], v[50:53]
	v_mfma_f32_16x16x32_bf16 v[38:41], v[216:219], v[166:169], v[38:41]
	v_mfma_f32_16x16x32_bf16 v[34:37], v[224:227], v[166:169], v[34:37]
	v_mfma_f32_16x16x32_bf16 v[22:25], v[216:219], v[200:203], v[22:25]
	v_mfma_f32_16x16x32_bf16 v[18:21], v[224:227], v[200:203], v[18:21]
	v_mfma_f32_16x16x32_bf16 v[6:9], v[216:219], v[208:211], v[6:9]
	v_mfma_f32_16x16x32_bf16 v[2:5], v[224:227], v[208:211], v[2:5]
	v_mfma_f32_16x16x32_bf16 v[54:57], v[220:223], v[162:165], v[54:57]
	v_mfma_f32_16x16x32_bf16 v[50:53], v[228:231], v[162:165], v[50:53]
	v_mfma_f32_16x16x32_bf16 v[38:41], v[220:223], v[170:173], v[38:41]
	v_mfma_f32_16x16x32_bf16 v[34:37], v[228:231], v[170:173], v[34:37]
	v_mfma_f32_16x16x32_bf16 v[22:25], v[220:223], v[204:207], v[22:25]
	v_mfma_f32_16x16x32_bf16 v[18:21], v[228:231], v[204:207], v[18:21]
	v_mfma_f32_16x16x32_bf16 v[6:9], v[220:223], v[212:215], v[6:9]
	v_mfma_f32_16x16x32_bf16 v[2:5], v[228:231], v[212:215], v[2:5]
	s_setprio 0
	s_add_i32 s33, 0, 0x18000
	v_add_u32_e32 v154, s33, v131
	s_barrier
	ds_read_b128 v[140:143], v154
	ds_read_b128 v[146:149], v154 offset:1024
	ds_read_b128 v[150:153], v154 offset:2048
	ds_read_b128 v[154:157], v154 offset:3072
	s_add_u32 s10, s16, 0xb0000
	s_addc_u32 s11, s17, 0
	s_mov_b32 m0, s25
	v_lshl_add_u64 v[216:217], s[10:11], 0, v[134:135]
	ds_read_b128 v[158:161], v145 offset:32768
	ds_read_b128 v[162:165], v145 offset:33792
	ds_read_b128 v[166:169], v145 offset:34816
	ds_read_b128 v[170:173], v145 offset:35840
	ds_read_b128 v[200:203], v145 offset:36864
	ds_read_b128 v[204:207], v145 offset:37888
	ds_read_b128 v[208:211], v145 offset:38912
	ds_read_b128 v[212:215], v145 offset:39936
	global_load_lds_dwordx4 v[216:217], off
	v_lshl_add_u64 v[216:217], s[10:11], 0, v[132:133]
	s_mov_b32 m0, s26
	s_nop 0
	global_load_lds_dwordx4 v[216:217], off
	s_waitcnt lgkmcnt(8)
	s_barrier
	s_waitcnt lgkmcnt(0)
	s_setprio 1
	v_mfma_f32_16x16x32_bf16 v[126:129], v[140:143], v[158:161], v[126:129]
	v_mfma_f32_16x16x32_bf16 v[122:125], v[150:153], v[158:161], v[122:125]
	v_mfma_f32_16x16x32_bf16 v[110:113], v[140:143], v[166:169], v[110:113]
	v_mfma_f32_16x16x32_bf16 v[106:109], v[150:153], v[166:169], v[106:109]
	v_mfma_f32_16x16x32_bf16 v[94:97], v[140:143], v[200:203], v[94:97]
	v_mfma_f32_16x16x32_bf16 v[90:93], v[150:153], v[200:203], v[90:93]
	v_mfma_f32_16x16x32_bf16 v[78:81], v[140:143], v[208:211], v[78:81]
	v_mfma_f32_16x16x32_bf16 v[74:77], v[150:153], v[208:211], v[74:77]
	v_mfma_f32_16x16x32_bf16 v[126:129], v[146:149], v[162:165], v[126:129]
	v_mfma_f32_16x16x32_bf16 v[122:125], v[154:157], v[162:165], v[122:125]
	v_mfma_f32_16x16x32_bf16 v[110:113], v[146:149], v[170:173], v[110:113]
	v_mfma_f32_16x16x32_bf16 v[106:109], v[154:157], v[170:173], v[106:109]
	v_mfma_f32_16x16x32_bf16 v[94:97], v[146:149], v[204:207], v[94:97]
	v_mfma_f32_16x16x32_bf16 v[90:93], v[154:157], v[204:207], v[90:93]
	v_mfma_f32_16x16x32_bf16 v[78:81], v[146:149], v[212:215], v[78:81]
	v_mfma_f32_16x16x32_bf16 v[74:77], v[154:157], v[212:215], v[74:77]
	s_setprio 0
	s_barrier
	s_add_i32 s16, 0, 0x1c000
	s_add_i32 s10, s33, s20
	v_add_u32_e32 v228, s16, v131
	v_lshl_add_u64 v[174:175], v[174:175], 0, s[86:87]
	s_mov_b32 m0, s10
	ds_read_b128 v[216:219], v228
	ds_read_b128 v[220:223], v228 offset:1024
	ds_read_b128 v[224:227], v228 offset:2048
	ds_read_b128 v[228:231], v228 offset:3072
	global_load_lds_dwordx4 v[174:175], off
	v_lshl_add_u64 v[174:175], v[182:183], 0, s[86:87]
	s_add_i32 m0, s10, 0x2000
	s_nop 0
	global_load_lds_dwordx4 v[174:175], off
	s_waitcnt lgkmcnt(0)
	s_barrier
; #define PG8_STAGE(bufoff, gbase, voff) do { _Pragma("unroll") for (int _i = 0; _i < 2; ++_i) \
;     __builtin_amdgcn_global_load_lds((const unsigned*)((const char*)(gbase) + (voff)[_i]), (PG8_LAS unsigned*)(lds + (bufoff) + ldsw + _i * 8192), 16, 0, 0); } while (0)
; #define PG8_LDA(dst, b, h) do { _Pragma("unroll") for (int m = 0; m < 4; ++m) _Pragma("unroll") for (int k = 0; k < 2; ++k) dst[m][k] = *(const PG8_LAS bf16x8*)(lds + PG8_SA(b, h) + aoff + m * 2048 + k * 1024); } while (0)
; #define PG8_MMA(ai, bj, At, Bt) do { __builtin_amdgcn_s_setprio(1); _Pragma("unroll") for (int m = 0; m < 4; ++m) _Pragma("unroll") for (int n = 0; n < 2; ++n) _Pragma("unroll") for (int k = 0; k < 2; ++k) \
;     acc[ai][bj][m][n] = __builtin_amdgcn_mfma_f32_16x16x32_bf16(Bt[n][k], At[m][k], acc[ai][bj][m][n], 0, 0, 0); __builtin_amdgcn_s_setprio(0); } while (0)
; #define PG8_WAIT_V(n) asm volatile("s_waitcnt vmcnt(" #n ")" ::: "memory")
; #define PG8_WAIT_L(n) asm volatile("s_waitcnt lgkmcnt(" #n ")" ::: "memory")
; #define PG8_BAR __builtin_amdgcn_s_barrier()
; #define PG8_SCHED __builtin_amdgcn_sched_barrier(0)
; template <class Epi, class Sched>
; __device__ __forceinline__ void gemm_phase(PG8_LAS unsigned char* lds, const int lda, const int ldb, const Sched& S, const Epi& E) {
;     ...
;       PG8_BAR; PG8_WAIT_L(0); PG8_MMA(0, 1, At, B1); PG8_BAR;
;       PG8_LDA(At, 1, 1); PG8_STAGE(PG8_SA(1, 0), a3, voffA);
;       PG8_BAR; PG8_WAIT_L(0); PG8_MMA(1, 0, At, B0); PG8_BAR; PG8_SCHED;
;       PG8_STAGE(PG8_SB(1, 1), b3 + hstepB, voffB);
;       PG8_WAIT_V(6); PG8_BAR; PG8_MMA(1, 1, At, B1); PG8_BAR;
;     }
;   __device__ __forceinline__ void operator()(const f32x4 (&acc)[2][2][4][2], const Unit& u, int wr, int wc, int fr, int fq) const {
;     const int mr = (u.pm * 256 < ML) ? ((u.pm * 256) >> 11) : 32;
;     const float* gp = mod + (size_t)mr * 6144 + gate_off;
	s_setprio 1
	v_mfma_f32_16x16x32_bf16 v[118:121], v[216:219], v[158:161], v[118:121]
	v_mfma_f32_16x16x32_bf16 v[114:117], v[224:227], v[158:161], v[114:117]
	v_mfma_f32_16x16x32_bf16 v[102:105], v[216:219], v[166:169], v[102:105]
	v_mfma_f32_16x16x32_bf16 v[98:101], v[224:227], v[166:169], v[98:101]
	v_mfma_f32_16x16x32_bf16 v[86:89], v[216:219], v[200:203], v[86:89]
	v_mfma_f32_16x16x32_bf16 v[82:85], v[224:227], v[200:203], v[82:85]
	v_mfma_f32_16x16x32_bf16 v[70:73], v[216:219], v[208:211], v[70:73]
	v_mfma_f32_16x16x32_bf16 v[66:69], v[224:227], v[208:211], v[66:69]
	v_mfma_f32_16x16x32_bf16 v[118:121], v[220:223], v[162:165], v[118:121]
	v_mfma_f32_16x16x32_bf16 v[114:117], v[228:231], v[162:165], v[114:117]
	v_mfma_f32_16x16x32_bf16 v[102:105], v[220:223], v[170:173], v[102:105]
	v_mfma_f32_16x16x32_bf16 v[98:101], v[228:231], v[170:173], v[98:101]
	v_mfma_f32_16x16x32_bf16 v[86:89], v[220:223], v[204:207], v[86:89]
	v_mfma_f32_16x16x32_bf16 v[82:85], v[228:231], v[204:207], v[82:85]
	v_mfma_f32_16x16x32_bf16 v[70:73], v[220:223], v[212:215], v[70:73]
	v_mfma_f32_16x16x32_bf16 v[66:69], v[228:231], v[212:215], v[66:69]
	s_setprio 0
	s_mov_b32 m0, s28
	v_lshl_add_u64 v[174:175], v[184:185], 0, s[86:87]
	s_barrier
	ds_read_b128 v[158:161], v145 offset:49152
	ds_read_b128 v[162:165], v145 offset:50176
	ds_read_b128 v[166:169], v145 offset:51200
	ds_read_b128 v[170:173], v145 offset:52224
	ds_read_b128 v[200:203], v145 offset:53248
	ds_read_b128 v[204:207], v145 offset:54272
	ds_read_b128 v[208:211], v145 offset:55296
	ds_read_b128 v[212:215], v145 offset:56320
	global_load_lds_dwordx4 v[174:175], off
	v_lshl_add_u64 v[174:175], v[232:233], 0, s[86:87]
	s_mov_b32 m0, s29
	s_nop 0
	global_load_lds_dwordx4 v[174:175], off
	s_waitcnt lgkmcnt(0)
	s_barrier
	s_setprio 1
	v_mfma_f32_16x16x32_bf16 v[62:65], v[140:143], v[158:161], v[62:65]
	v_mfma_f32_16x16x32_bf16 v[58:61], v[150:153], v[158:161], v[58:61]
	v_mfma_f32_16x16x32_bf16 v[46:49], v[140:143], v[166:169], v[46:49]
	v_mfma_f32_16x16x32_bf16 v[42:45], v[150:153], v[166:169], v[42:45]
	v_mfma_f32_16x16x32_bf16 v[30:33], v[140:143], v[200:203], v[30:33]
	v_mfma_f32_16x16x32_bf16 v[26:29], v[150:153], v[200:203], v[26:29]
	v_mfma_f32_16x16x32_bf16 v[14:17], v[140:143], v[208:211], v[14:17]
	v_mfma_f32_16x16x32_bf16 v[10:13], v[150:153], v[208:211], v[10:13]
	v_mfma_f32_16x16x32_bf16 v[62:65], v[146:149], v[162:165], v[62:65]
	v_mfma_f32_16x16x32_bf16 v[58:61], v[154:157], v[162:165], v[58:61]
	v_mfma_f32_16x16x32_bf16 v[46:49], v[146:149], v[170:173], v[46:49]
	v_mfma_f32_16x16x32_bf16 v[42:45], v[154:157], v[170:173], v[42:45]
	v_mfma_f32_16x16x32_bf16 v[30:33], v[146:149], v[204:207], v[30:33]
	v_mfma_f32_16x16x32_bf16 v[26:29], v[154:157], v[204:207], v[26:29]
	v_mfma_f32_16x16x32_bf16 v[14:17], v[146:149], v[212:215], v[14:17]
	v_mfma_f32_16x16x32_bf16 v[10:13], v[154:157], v[212:215], v[10:13]
	s_setprio 0
	s_barrier
	s_add_u32 s10, s14, 0xb0080
	s_addc_u32 s11, s15, 0
	s_add_i32 s14, s16, s20
	v_lshl_add_u64 v[140:141], s[10:11], 0, v[134:135]
	s_mov_b32 m0, s14
	s_nop 0
	global_load_lds_dwordx4 v[140:141], off
	v_lshl_add_u64 v[140:141], s[10:11], 0, v[132:133]
	s_add_i32 m0, s14, 0x2000
	s_nop 0
	global_load_lds_dwordx4 v[140:141], off
	s_waitcnt vmcnt(6)
	s_barrier
	s_setprio 1
	v_mfma_f32_16x16x32_bf16 v[54:57], v[216:219], v[158:161], v[54:57]
	v_mfma_f32_16x16x32_bf16 v[50:53], v[224:227], v[158:161], v[50:53]
	v_mfma_f32_16x16x32_bf16 v[38:41], v[216:219], v[166:169], v[38:41]
	v_mfma_f32_16x16x32_bf16 v[34:37], v[224:227], v[166:169], v[34:37]
	v_mfma_f32_16x16x32_bf16 v[22:25], v[216:219], v[200:203], v[22:25]
	v_mfma_f32_16x16x32_bf16 v[18:21], v[224:227], v[200:203], v[18:21]
	v_mfma_f32_16x16x32_bf16 v[6:9], v[216:219], v[208:211], v[6:9]
	v_mfma_f32_16x16x32_bf16 v[2:5], v[224:227], v[208:211], v[2:5]
	v_mfma_f32_16x16x32_bf16 v[54:57], v[220:223], v[162:165], v[54:57]
	v_mfma_f32_16x16x32_bf16 v[50:53], v[228:231], v[162:165], v[50:53]
	v_mfma_f32_16x16x32_bf16 v[38:41], v[220:223], v[170:173], v[38:41]
	v_mfma_f32_16x16x32_bf16 v[34:37], v[228:231], v[170:173], v[34:37]
	v_mfma_f32_16x16x32_bf16 v[22:25], v[220:223], v[204:207], v[22:25]
	v_mfma_f32_16x16x32_bf16 v[18:21], v[228:231], v[204:207], v[18:21]
	v_mfma_f32_16x16x32_bf16 v[6:9], v[220:223], v[212:215], v[6:9]
	v_mfma_f32_16x16x32_bf16 v[2:5], v[228:231], v[212:215], v[2:5]
	s_setprio 0
	s_add_i32 s41, s41, 2
	s_add_u32 s39, s39, 0x100
	s_addc_u32 s40, s40, 0
	s_cmp_gt_u32 s41, 41
	s_mov_b64 s[10:11], s[12:13]
	s_barrier
	s_cbranch_scc0 .LBB0_1673
	s_cmpk_gt_i32 s37, 0xff
	s_mov_b64 s[10:11], 0x30000
	s_cbranch_scc1 .LBB0_1665
	s_ashr_i32 s10, s37, 3
	s_mul_hi_i32 s11, s10, 0x1800
	s_mulk_i32 s10, 0x1800
	s_branch .LBB0_1665
